# attention loops: fewer VALU per tile - merged canonicalising max pairs, K/V staging loads land directly in spare registers (no copies), per-tile 64-bit address math replaced by three running pointers
# baseline (speedup 1.0000x reference)
; __device__ __forceinline__ void finishSM(f32x16& p0, f32x16& p1, float alpha, float& l_reg, bf16x8& pa0, bf16x8& pa1, bf16x8& pa2, bf16x8& pa3) {
; #pragma unroll
;   for (int r = 0; r < 16; ++r) p1[r] = __builtin_amdgcn_exp2f(p1[r]);
;   float ps = 0;
; #pragma unroll
;   for (int r = 0; r < 16; ++r) ps += p0[r];
; #pragma unroll
;   for (int r = 0; r < 16; ++r) ps += p1[r];
;   { auto rr = __builtin_amdgcn_permlane32_swap(__float_as_uint(ps), __float_as_uint(ps), false, false);
;     ps = __uint_as_float(rr[0]) + __uint_as_float(rr[1]); }
;   l_reg = l_reg * alpha + ps;
;     ...
;   PK4(p0, 0, pa0); PK4(p0, 8, pa1); PK4(p1, 0, pa2); PK4(p1, 8, pa3);
;     ...
; }
; template <int DK, bool QL>
; __device__ __forceinline__ void qkt(f32x16& p0, f32x16& p1, const bf16* Ks, const bf16x8* qr, const char* ql, int r32, int hi) {
;   p0 = f32x16{}; p1 = f32x16{};
; #pragma unroll
;   for (int d0 = 0; d0 < DK / 16; ++d0) { int cb = (d0 * 16 + hi * 8) * 2;
;     const bf16x8 qv = QL ? *reinterpret_cast<const bf16x8*>(ql + d0 * 1024) : qr[d0];
;     bf16x8 b0 = *reinterpret_cast<const bf16x8*>((const char*)Ks + kswz<DK>(r32, cb));
;     bf16x8 b1 = *reinterpret_cast<const bf16x8*>((const char*)Ks + kswz<DK>(32 + r32, cb));
;     p0 = __builtin_amdgcn_mfma_f32_32x32x16_bf16(b0, qv, p0, 0, 0, 0);
;     p1 = __builtin_amdgcn_mfma_f32_32x32x16_bf16(b1, qv, p1, 0, 0, 0); }
; }
.LBB0_660:
	ds_read_b128 v[66:69], v153
	ds_read_b128 v[70:73], v159 offset:49152
	ds_read_b128 v[74:77], v159 offset:57344
	ds_read_b128 v[218:221], v153 offset:1024
	ds_read_b128 v[222:225], v207 offset:49152
	ds_read_b128 v[226:229], v207 offset:57344
	v_add_f32_e32 v130, 0, v145
	v_add_f32_e32 v130, v216, v130
	s_waitcnt lgkmcnt(4)
	v_mfma_f32_32x32x16_bf16 v[82:97], v[70:73], v[66:69], 0
	v_add_f32_e32 v130, v131, v130
	v_add_f32_e32 v130, v215, v130
	v_add_f32_e32 v130, v132, v130
	v_add_f32_e32 v130, v144, v130
	v_add_f32_e32 v130, v133, v130
	v_add_f32_e32 v130, v143, v130
	v_add_f32_e32 v130, v140, v130
	s_waitcnt lgkmcnt(3)
	v_mfma_f32_32x32x16_bf16 v[66:81], v[74:77], v[66:69], 0
	v_add_f32_e32 v130, v142, v130
	v_add_f32_e32 v130, v139, v130
	v_add_f32_e32 v130, v141, v130
	v_exp_f32_e32 v126, v126
	v_add_f32_e32 v130, v136, v130
	v_exp_f32_e32 v127, v127
	v_add_f32_e32 v130, v138, v130
	s_waitcnt lgkmcnt(1)
	v_mfma_f32_32x32x16_bf16 v[82:97], v[222:225], v[218:221], v[82:97]
	v_exp_f32_e32 v124, v124
	v_add_f32_e32 v130, v135, v130
	v_exp_f32_e32 v125, v125
	v_add_f32_e32 v130, v137, v130
	v_exp_f32_e32 v118, v118
	v_add_f32_e32 v130, v126, v130
	v_exp_f32_e32 v119, v119
	s_waitcnt lgkmcnt(0)
	v_mfma_f32_32x32x16_bf16 v[66:81], v[226:229], v[218:221], v[66:81]
	ds_read_b128 v[218:221], v153 offset:2048
	ds_read_b128 v[222:225], v161 offset:49152
	ds_read_b128 v[226:229], v161 offset:57344
	v_add_f32_e32 v130, v127, v130
	v_exp_f32_e32 v116, v116
	v_add_f32_e32 v130, v124, v130
	v_exp_f32_e32 v117, v117
	v_add_f32_e32 v130, v125, v130
	v_exp_f32_e32 v114, v114
	s_waitcnt lgkmcnt(1)
	v_mfma_f32_32x32x16_bf16 v[82:97], v[222:225], v[218:221], v[82:97]
	v_add_f32_e32 v130, v118, v130
	v_exp_f32_e32 v115, v115
	v_add_f32_e32 v130, v119, v130
	v_exp_f32_e32 v128, v128
	v_add_f32_e32 v130, v116, v130
	v_exp_f32_e32 v129, v129
	v_add_f32_e32 v130, v117, v130
	s_waitcnt lgkmcnt(0)
	v_mfma_f32_32x32x16_bf16 v[66:81], v[226:229], v[218:221], v[66:81]
	ds_read_b128 v[218:221], v153 offset:3072
	ds_read_b128 v[222:225], v160 offset:49152
	ds_read_b128 v[226:229], v160 offset:57344
	v_exp_f32_e32 v122, v122
	v_add_f32_e32 v130, v114, v130
	v_exp_f32_e32 v123, v123
	v_add_f32_e32 v130, v115, v130
	v_exp_f32_e32 v120, v120
	v_add_f32_e32 v130, v128, v130
	s_waitcnt lgkmcnt(1)
	v_mfma_f32_32x32x16_bf16 v[82:97], v[222:225], v[218:221], v[82:97]
	v_exp_f32_e32 v121, v121
	v_add_f32_e32 v130, v129, v130
	v_add_f32_e32 v130, v122, v130
	v_add_f32_e32 v130, v123, v130
	v_add_f32_e32 v130, v120, v130
	v_add_f32_e32 v212, v121, v130
	v_mov_b32_e32 v213, v212
	s_waitcnt lgkmcnt(0)
	v_mfma_f32_32x32x16_bf16 v[66:81], v[226:229], v[218:221], v[66:81]
	ds_read_b128 v[218:221], v153 offset:4096
	ds_read_b128 v[222:225], v158 offset:49152
	ds_read_b128 v[226:229], v158 offset:57344
	v_permlane32_swap_b32_e32 v212, v213
	s_waitcnt lgkmcnt(1)
	v_mfma_f32_32x32x16_bf16 v[82:97], v[222:225], v[218:221], v[82:97]
	s_waitcnt lgkmcnt(0)
	v_mfma_f32_32x32x16_bf16 v[66:81], v[226:229], v[218:221], v[66:81]
	ds_read_b128 v[218:221], v153 offset:5120
	ds_read_b128 v[222:225], v156 offset:49152
	ds_read_b128 v[226:229], v156 offset:57344
	s_waitcnt lgkmcnt(1)
	v_mfma_f32_32x32x16_bf16 v[82:97], v[222:225], v[218:221], v[82:97]
	s_waitcnt lgkmcnt(0)
	v_mfma_f32_32x32x16_bf16 v[66:81], v[226:229], v[218:221], v[66:81]
	ds_read_b128 v[218:221], v153 offset:6144
	ds_read_b128 v[222:225], v157 offset:49152
	ds_read_b128 v[226:229], v157 offset:57344
	s_waitcnt lgkmcnt(1)
	v_mfma_f32_32x32x16_bf16 v[82:97], v[222:225], v[218:221], v[82:97]
	s_waitcnt lgkmcnt(0)
	v_mfma_f32_32x32x16_bf16 v[66:81], v[226:229], v[218:221], v[66:81]
	ds_read_b128 v[218:221], v153 offset:7168
	ds_read_b128 v[222:225], v176 offset:49152
	ds_read_b128 v[226:229], v176 offset:57344
	v_cvt_pk_bf16_f32 v130, v145, v216
	v_cvt_pk_bf16_f32 v131, v131, v215
	v_cvt_pk_bf16_f32 v132, v132, v144
	v_cvt_pk_bf16_f32 v133, v133, v143
	v_cvt_pk_bf16_f32 v140, v140, v142
	v_cvt_pk_bf16_f32 v141, v139, v141
	s_waitcnt lgkmcnt(1)
	v_mfma_f32_32x32x16_bf16 v[82:97], v[222:225], v[218:221], v[82:97]
	v_cvt_pk_bf16_f32 v142, v136, v138
	v_cvt_pk_bf16_f32 v143, v135, v137
	v_cvt_pk_bf16_f32 v136, v126, v127
	v_cvt_pk_bf16_f32 v137, v124, v125
	v_cvt_pk_bf16_f32 v138, v118, v119
	v_cvt_pk_bf16_f32 v139, v116, v117
	v_cvt_pk_bf16_f32 v214, v114, v115
	s_waitcnt lgkmcnt(0)
	v_mfma_f32_32x32x16_bf16 v[66:81], v[226:229], v[218:221], v[66:81]
	v_cvt_pk_bf16_f32 v215, v128, v129
	v_cvt_pk_bf16_f32 v216, v122, v123
	v_permlane32_swap_b32_e32 v130, v132
	v_cvt_pk_bf16_f32 v217, v120, v121
	v_permlane32_swap_b32_e32 v214, v216
	v_permlane32_swap_b32_e32 v131, v133
	v_permlane32_swap_b32_e32 v140, v142
	v_permlane32_swap_b32_e32 v141, v143
	v_permlane32_swap_b32_e32 v136, v138
	v_permlane32_swap_b32_e32 v137, v139
	v_permlane32_swap_b32_e32 v215, v217
	s_mov_b32 s2, 0xfff10000
	v_add_co_u32_e32 v118, vcc, s2, v146
	s_mov_b32 s2, 0xfff60000
	s_nop 0
	v_addc_co_u32_e32 v119, vcc, -1, v147, vcc
	v_add_co_u32_e32 v122, vcc, s2, v146
	s_nop 1
	v_addc_co_u32_e32 v123, vcc, -1, v147, vcc
	global_load_dwordx4 v[244:247], v[118:119], off
	s_nop 0
	global_load_dwordx4 v[118:121], v[118:119], off offset:-512
	s_nop 0
	global_load_dwordx4 v[194:197], v[122:123], off
	s_nop 0
	global_load_dwordx4 v[122:125], v[122:123], off offset:-512
	ds_read_b64_tr_b16 v[218:219], v152 offset:0
	ds_read_b64_tr_b16 v[220:221], v152 offset:0x800
	ds_read_b64_tr_b16 v[222:223], v152 offset:0x1000
	ds_read_b64_tr_b16 v[224:225], v152 offset:0x1800
	ds_read_b64_tr_b16 v[226:227], v152 offset:0x2000
	ds_read_b64_tr_b16 v[228:229], v152 offset:0x2800
	ds_read_b64_tr_b16 v[230:231], v152 offset:0x3000
	ds_read_b64_tr_b16 v[232:233], v152 offset:0x3800
	s_waitcnt lgkmcnt(6)
; #define SBAR() __builtin_amdgcn_sched_barrier(0)
; __device__ __forceinline__ void partialSM(f32x16& p0, f32x16& p1, float& m_reg, float& mn, float& alpha, float C, float thrRaw) {
;   float pmax = p0[0];
; #pragma unroll
;   for (int r = 1; r < 16; ++r) pmax = fmaxf(pmax, p0[r]);
; #pragma unroll
;   for (int r = 0; r < 16; ++r) pmax = fmaxf(pmax, p1[r]);
;   { auto rr = __builtin_amdgcn_permlane32_swap(__float_as_uint(pmax), __float_as_uint(pmax), false, false);
;     pmax = fmaxf(__uint_as_float(rr[0]), __uint_as_float(rr[1])); }
;   if (__builtin_expect(__all(pmax - m_reg <= thrRaw), 1)) { mn = m_reg; alpha = 1.f; }
;   else { mn = fmaxf(m_reg, pmax); alpha = __builtin_amdgcn_exp2f((m_reg - mn) * C); m_reg = mn; }
;   float mnC = -mn * C;
; #pragma unroll
;   for (int r = 0; r < 16; ++r) p0[r] = fmaf(p0[r], C, mnC);
; #pragma unroll
;   for (int r = 0; r < 16; ++r) p1[r] = fmaf(p1[r], C, mnC);
; #pragma unroll
;   for (int r = 0; r < 16; ++r) p0[r] = __builtin_amdgcn_exp2f(p0[r]);
; }
; template <int D0> __device__ __forceinline__ void pv_one(f32x16& od, int vb, bf16x8 pa0, bf16x8 pa1, bf16x8 pa2, bf16x8 pa3) {
;   const s16x4 l0 = tr_read<v_rd_off(D0, 0, 0)>(vb), h0 = tr_read<v_rd_off(D0, 0, 1)>(vb), l1 = tr_read<v_rd_off(D0, 1, 0)>(vb), h1 = tr_read<v_rd_off(D0, 1, 1)>(vb);
;   const s16x4 l2 = tr_read<v_rd_off(D0, 2, 0)>(vb), h2 = tr_read<v_rd_off(D0, 2, 1)>(vb), l3 = tr_read<v_rd_off(D0, 3, 0)>(vb), h3 = tr_read<v_rd_off(D0, 3, 1)>(vb);
;   asm volatile("s_waitcnt lgkmcnt(0)" ::: "memory"); SBAR();
;     ...
;   od = __builtin_amdgcn_mfma_f32_32x32x16_bf16(pa0, PK(l0, h0), od, 0, 0, 0);
;   od = __builtin_amdgcn_mfma_f32_32x32x16_bf16(pa1, PK(l1, h1), od, 0, 0, 0);
;   od = __builtin_amdgcn_mfma_f32_32x32x16_bf16(pa2, PK(l2, h2), od, 0, 0, 0);
;   od = __builtin_amdgcn_mfma_f32_32x32x16_bf16(pa3, PK(l3, h3), od, 0, 0, 0);
;     ...
; }
; __device__ __forceinline__ void pv_d0(f32x16* o, int vb, bf16x8 pa0, bf16x8 pa1, bf16x8 pa2, bf16x8 pa3) {
;   pv_one<0>(o[0], vb, pa0, pa1, pa2, pa3); pv_one<1>(o[1], vb, pa0, pa1, pa2, pa3); pv_one<2>(o[2], vb, pa0, pa1, pa2, pa3); pv_one<3>(o[3], vb, pa0, pa1, pa2, pa3);
	s_nop 0
	v_mfma_f32_32x32x16_bf16 v[18:33], v[130:133], v[218:221], v[18:33]
	ds_read_b64_tr_b16 v[218:219], v152 offset:0x200
	ds_read_b64_tr_b16 v[220:221], v152 offset:0xa00
	s_waitcnt lgkmcnt(6)
	v_mfma_f32_32x32x16_bf16 v[18:33], v[140:143], v[222:225], v[18:33]
	ds_read_b64_tr_b16 v[222:223], v152 offset:0x1200
	ds_read_b64_tr_b16 v[224:225], v152 offset:0x1a00
	s_waitcnt lgkmcnt(6)
	v_mfma_f32_32x32x16_bf16 v[18:33], v[136:139], v[226:229], v[18:33]
	ds_read_b64_tr_b16 v[226:227], v152 offset:0x2200
	ds_read_b64_tr_b16 v[228:229], v152 offset:0x2a00
	s_waitcnt lgkmcnt(6)
	v_mfma_f32_32x32x16_bf16 v[18:33], v[214:217], v[230:233], v[18:33]
	ds_read_b64_tr_b16 v[230:231], v152 offset:0x3200
	ds_read_b64_tr_b16 v[232:233], v152 offset:0x3a00
	s_waitcnt lgkmcnt(6)
	v_mfma_f32_32x32x16_bf16 v[50:65], v[130:133], v[218:221], v[50:65]
	ds_read_b64_tr_b16 v[218:219], v152 offset:0x400
	ds_read_b64_tr_b16 v[220:221], v152 offset:0xc00
	s_waitcnt lgkmcnt(6)
	v_mfma_f32_32x32x16_bf16 v[50:65], v[140:143], v[222:225], v[50:65]
	ds_read_b64_tr_b16 v[222:223], v152 offset:0x1400
	ds_read_b64_tr_b16 v[224:225], v152 offset:0x1c00
	s_waitcnt lgkmcnt(6)
	v_mfma_f32_32x32x16_bf16 v[50:65], v[136:139], v[226:229], v[50:65]
	ds_read_b64_tr_b16 v[226:227], v152 offset:0x2400
	ds_read_b64_tr_b16 v[228:229], v152 offset:0x2c00
	s_waitcnt lgkmcnt(6)
	v_mfma_f32_32x32x16_bf16 v[50:65], v[214:217], v[230:233], v[50:65]
	ds_read_b64_tr_b16 v[230:231], v152 offset:0x3400
	ds_read_b64_tr_b16 v[232:233], v152 offset:0x3c00
	s_waitcnt lgkmcnt(6)
	v_mfma_f32_32x32x16_bf16 v[2:17], v[130:133], v[218:221], v[2:17]
	ds_read_b64_tr_b16 v[218:219], v152 offset:0x600
	ds_read_b64_tr_b16 v[220:221], v152 offset:0xe00
	s_waitcnt lgkmcnt(6)
	v_mfma_f32_32x32x16_bf16 v[2:17], v[140:143], v[222:225], v[2:17]
	ds_read_b64_tr_b16 v[222:223], v152 offset:0x1600
	ds_read_b64_tr_b16 v[224:225], v152 offset:0x1e00
	s_waitcnt lgkmcnt(6)
	v_mfma_f32_32x32x16_bf16 v[2:17], v[136:139], v[226:229], v[2:17]
	ds_read_b64_tr_b16 v[226:227], v152 offset:0x2600
	ds_read_b64_tr_b16 v[228:229], v152 offset:0x2e00
	s_waitcnt lgkmcnt(6)
	v_mfma_f32_32x32x16_bf16 v[2:17], v[214:217], v[230:233], v[2:17]
	ds_read_b64_tr_b16 v[230:231], v152 offset:0x3600
	ds_read_b64_tr_b16 v[232:233], v152 offset:0x3e00
	s_waitcnt lgkmcnt(6)
	v_mfma_f32_32x32x16_bf16 v[34:49], v[130:133], v[218:221], v[34:49]
	v_max_f32_e32 v130, v83, v82
	v_max3_f32 v130, v130, v84, v85
	v_max3_f32 v130, v130, v86, v87
	v_max3_f32 v130, v130, v88, v89
	v_max3_f32 v130, v130, v90, v91
	v_max3_f32 v130, v130, v92, v93
	v_max3_f32 v130, v130, v94, v95
	s_waitcnt lgkmcnt(4)
	v_mfma_f32_32x32x16_bf16 v[34:49], v[140:143], v[222:225], v[34:49]
	v_max3_f32 v130, v130, v96, v97
	v_max3_f32 v130, v130, v66, v67
	v_max3_f32 v130, v130, v68, v69
	v_max3_f32 v130, v130, v70, v71
	v_max3_f32 v130, v130, v72, v73
	v_max3_f32 v130, v130, v74, v75
	v_max3_f32 v130, v130, v76, v77
	v_max3_f32 v130, v130, v78, v79
	s_waitcnt lgkmcnt(2)
	v_mfma_f32_32x32x16_bf16 v[34:49], v[136:139], v[226:229], v[34:49]
	v_max3_f32 v130, v130, v80, v81
	v_mov_b32_e32 v131, v130
	s_nop 1
	v_permlane32_swap_b32_e32 v130, v131
	v_max_f32_e32 v130, v131, v130
	v_sub_f32_e32 v131, v130, v134
	s_mov_b32 s2, 0x42b504f3
	v_cmp_ge_f32_e32 vcc, s2, v131
	v_max_f32_e32 v130, v134, v130
	s_waitcnt lgkmcnt(0)
	v_mfma_f32_32x32x16_bf16 v[34:49], v[214:217], v[230:233], v[34:49]
	v_sub_f32_e32 v131, v134, v130
	v_mul_f32_e32 v131, 0x3e0293ee, v131
	v_exp_f32_e32 v131, v131
	s_cmp_eq_u64 vcc, exec
	s_cselect_b64 s[2:3], -1, 0
	s_waitcnt vmcnt(4)
	v_cndmask_b32_e64 v214, v131, 1.0, s[2:3]
	v_cmp_gt_f32_e32 vcc, 1.0, v214
	s_waitcnt vmcnt(4)
	ds_write_b128 v177, v[98:101] offset:32768
	ds_write_b128 v208, v[102:105] offset:32768
	s_cbranch_vccz .LBB0_664
	s_and_saveexec_b64 s[4:5], s[0:1]
	ds_write_b32 v149, v214 offset:128
	s_or_b64 exec, exec, s[4:5]
	s_waitcnt lgkmcnt(0)
	v_add_u32_e32 v131, v148, v0
	ds_read_b128 v[136:139], v131 offset:128
	ds_read_b128 v[140:143], v131 offset:160
	ds_read_b128 v[216:219], v131 offset:192
	ds_read_b128 v[220:223], v131 offset:224
	s_waitcnt lgkmcnt(3)
	v_pk_mul_f32 v[50:51], v[136:137], v[50:51]
	v_pk_mul_f32 v[52:53], v[52:53], v[138:139]
	s_waitcnt lgkmcnt(2)
	v_pk_mul_f32 v[54:55], v[54:55], v[140:141]
	v_pk_mul_f32 v[56:57], v[56:57], v[142:143]
	s_waitcnt lgkmcnt(1)
	v_pk_mul_f32 v[58:59], v[58:59], v[216:217]
	v_pk_mul_f32 v[60:61], v[60:61], v[218:219]
	s_waitcnt lgkmcnt(0)
	v_pk_mul_f32 v[62:63], v[62:63], v[220:221]
	v_pk_mul_f32 v[30:31], v[30:31], v[220:221]
	v_pk_mul_f32 v[26:27], v[26:27], v[216:217]
	v_pk_mul_f32 v[22:23], v[22:23], v[140:141]
	v_pk_mul_f32 v[32:33], v[32:33], v[222:223]
	v_pk_mul_f32 v[28:29], v[28:29], v[218:219]
	v_pk_mul_f32 v[24:25], v[24:25], v[142:143]
	v_pk_mul_f32 v[20:21], v[20:21], v[138:139]
	v_pk_mul_f32 v[18:19], v[18:19], v[136:137]
	v_pk_mul_f32 v[64:65], v[64:65], v[222:223]
	v_pk_mul_f32 v[34:35], v[136:137], v[34:35]
	v_pk_mul_f32 v[36:37], v[36:37], v[138:139]
	v_pk_mul_f32 v[38:39], v[38:39], v[140:141]
	v_pk_mul_f32 v[40:41], v[40:41], v[142:143]
	v_pk_mul_f32 v[42:43], v[42:43], v[216:217]
	v_pk_mul_f32 v[44:45], v[44:45], v[218:219]
	v_pk_mul_f32 v[46:47], v[46:47], v[220:221]
	v_pk_mul_f32 v[14:15], v[14:15], v[220:221]
	v_pk_mul_f32 v[10:11], v[10:11], v[216:217]
	v_pk_mul_f32 v[6:7], v[6:7], v[140:141]
	v_pk_mul_f32 v[16:17], v[16:17], v[222:223]
	v_pk_mul_f32 v[12:13], v[12:13], v[218:219]
	v_pk_mul_f32 v[8:9], v[8:9], v[142:143]
	v_pk_mul_f32 v[4:5], v[4:5], v[138:139]
	v_pk_mul_f32 v[2:3], v[2:3], v[136:137]
	v_pk_mul_f32 v[48:49], v[48:49], v[222:223]

; #define SBAR() __builtin_amdgcn_sched_barrier(0)
; __device__ __forceinline__ void partialSM(f32x16& p0, f32x16& p1, float& m_reg, float& mn, float& alpha, float C, float thrRaw) {
;   float pmax = p0[0];
; #pragma unroll
;   for (int r = 1; r < 16; ++r) pmax = fmaxf(pmax, p0[r]);
; #pragma unroll
;   for (int r = 0; r < 16; ++r) pmax = fmaxf(pmax, p1[r]);
;   { auto rr = __builtin_amdgcn_permlane32_swap(__float_as_uint(pmax), __float_as_uint(pmax), false, false);
;     pmax = fmaxf(__uint_as_float(rr[0]), __uint_as_float(rr[1])); }
;   if (__builtin_expect(__all(pmax - m_reg <= thrRaw), 1)) { mn = m_reg; alpha = 1.f; }
;   else { mn = fmaxf(m_reg, pmax); alpha = __builtin_amdgcn_exp2f((m_reg - mn) * C); m_reg = mn; }
;   float mnC = -mn * C;
; #pragma unroll
;   for (int r = 0; r < 16; ++r) p0[r] = fmaf(p0[r], C, mnC);
; #pragma unroll
;   for (int r = 0; r < 16; ++r) p1[r] = fmaf(p1[r], C, mnC);
; #pragma unroll
;   for (int r = 0; r < 16; ++r) p0[r] = __builtin_amdgcn_exp2f(p0[r]);
; }
; template <int D0> __device__ __forceinline__ void pv_one(f32x16& od, int vb, bf16x8 pa0, bf16x8 pa1, bf16x8 pa2, bf16x8 pa3) {
;   const s16x4 l0 = tr_read<v_rd_off(D0, 0, 0)>(vb), h0 = tr_read<v_rd_off(D0, 0, 1)>(vb), l1 = tr_read<v_rd_off(D0, 1, 0)>(vb), h1 = tr_read<v_rd_off(D0, 1, 1)>(vb);
;   const s16x4 l2 = tr_read<v_rd_off(D0, 2, 0)>(vb), h2 = tr_read<v_rd_off(D0, 2, 1)>(vb), l3 = tr_read<v_rd_off(D0, 3, 0)>(vb), h3 = tr_read<v_rd_off(D0, 3, 1)>(vb);
;   asm volatile("s_waitcnt lgkmcnt(0)" ::: "memory"); SBAR();
;     ...
;   od = __builtin_amdgcn_mfma_f32_32x32x16_bf16(pa0, PK(l0, h0), od, 0, 0, 0);
;   od = __builtin_amdgcn_mfma_f32_32x32x16_bf16(pa1, PK(l1, h1), od, 0, 0, 0);
;   od = __builtin_amdgcn_mfma_f32_32x32x16_bf16(pa2, PK(l2, h2), od, 0, 0, 0);
;   od = __builtin_amdgcn_mfma_f32_32x32x16_bf16(pa3, PK(l3, h3), od, 0, 0, 0);
;     ...
; }
; __device__ __forceinline__ void pv_d0(f32x16* o, int vb, bf16x8 pa0, bf16x8 pa1, bf16x8 pa2, bf16x8 pa3) {
;   pv_one<0>(o[0], vb, pa0, pa1, pa2, pa3); pv_one<1>(o[1], vb, pa0, pa1, pa2, pa3); pv_one<2>(o[2], vb, pa0, pa1, pa2, pa3); pv_one<3>(o[3], vb, pa0, pa1, pa2, pa3);
.LBB0_666:
	ds_read_b64_tr_b16 v[220:221], v151 offset:0
	ds_read_b64_tr_b16 v[222:223], v151 offset:0x800
	ds_read_b64_tr_b16 v[224:225], v151 offset:0x1000
	ds_read_b64_tr_b16 v[226:227], v151 offset:0x1800
	ds_read_b64_tr_b16 v[228:229], v151 offset:0x2000
	ds_read_b64_tr_b16 v[230:231], v151 offset:0x2800
	ds_read_b64_tr_b16 v[232:233], v151 offset:0x3000
	ds_read_b64_tr_b16 v[234:235], v151 offset:0x3800
	s_waitcnt lgkmcnt(6)
	s_nop 0
	v_mfma_f32_32x32x16_bf16 v[18:33], v[130:133], v[220:223], v[18:33]
	ds_read_b64_tr_b16 v[220:221], v151 offset:0x200
	ds_read_b64_tr_b16 v[222:223], v151 offset:0xa00
	s_waitcnt lgkmcnt(6)
	v_mfma_f32_32x32x16_bf16 v[18:33], v[134:137], v[224:227], v[18:33]
	ds_read_b64_tr_b16 v[224:225], v151 offset:0x1200
	ds_read_b64_tr_b16 v[226:227], v151 offset:0x1a00
	s_waitcnt lgkmcnt(6)
	v_mfma_f32_32x32x16_bf16 v[18:33], v[138:141], v[228:231], v[18:33]
	ds_read_b64_tr_b16 v[228:229], v151 offset:0x2200
	ds_read_b64_tr_b16 v[230:231], v151 offset:0x2a00
	s_waitcnt lgkmcnt(6)
	v_mfma_f32_32x32x16_bf16 v[18:33], v[142:145], v[232:235], v[18:33]
	ds_read_b64_tr_b16 v[232:233], v151 offset:0x3200
	ds_read_b64_tr_b16 v[234:235], v151 offset:0x3a00
	s_waitcnt lgkmcnt(6)
	v_mfma_f32_32x32x16_bf16 v[50:65], v[130:133], v[220:223], v[50:65]
	ds_read_b64_tr_b16 v[220:221], v151 offset:0x400
	ds_read_b64_tr_b16 v[222:223], v151 offset:0xc00
	s_waitcnt lgkmcnt(6)
	v_mfma_f32_32x32x16_bf16 v[50:65], v[134:137], v[224:227], v[50:65]
	ds_read_b64_tr_b16 v[224:225], v151 offset:0x1400
	ds_read_b64_tr_b16 v[226:227], v151 offset:0x1c00
	s_waitcnt lgkmcnt(6)
	v_mfma_f32_32x32x16_bf16 v[50:65], v[138:141], v[228:231], v[50:65]
	ds_read_b64_tr_b16 v[228:229], v151 offset:0x2400
	ds_read_b64_tr_b16 v[230:231], v151 offset:0x2c00
	s_waitcnt lgkmcnt(6)
	v_mfma_f32_32x32x16_bf16 v[50:65], v[142:145], v[232:235], v[50:65]
	ds_read_b64_tr_b16 v[232:233], v151 offset:0x3400
	ds_read_b64_tr_b16 v[234:235], v151 offset:0x3c00
	s_waitcnt lgkmcnt(6)
	v_mfma_f32_32x32x16_bf16 v[2:17], v[130:133], v[220:223], v[2:17]
	ds_read_b64_tr_b16 v[220:221], v151 offset:0x600
	ds_read_b64_tr_b16 v[222:223], v151 offset:0xe00
	s_waitcnt lgkmcnt(6)
	v_mfma_f32_32x32x16_bf16 v[2:17], v[134:137], v[224:227], v[2:17]
	ds_read_b64_tr_b16 v[224:225], v151 offset:0x1600
	ds_read_b64_tr_b16 v[226:227], v151 offset:0x1e00
	s_waitcnt lgkmcnt(6)
	v_mfma_f32_32x32x16_bf16 v[2:17], v[138:141], v[228:231], v[2:17]
	ds_read_b64_tr_b16 v[228:229], v151 offset:0x2600
	ds_read_b64_tr_b16 v[230:231], v151 offset:0x2e00
	s_waitcnt lgkmcnt(6)
	v_mfma_f32_32x32x16_bf16 v[2:17], v[142:145], v[232:235], v[2:17]
	ds_read_b64_tr_b16 v[232:233], v151 offset:0x3600
	ds_read_b64_tr_b16 v[234:235], v151 offset:0x3e00
	s_waitcnt lgkmcnt(6)
	v_mfma_f32_32x32x16_bf16 v[34:49], v[130:133], v[220:223], v[34:49]
	v_max_f32_e32 v130, v83, v82
	v_max3_f32 v130, v130, v84, v85
	v_max3_f32 v130, v130, v86, v87
	v_max3_f32 v130, v130, v88, v89
	v_max3_f32 v130, v130, v90, v91
	v_max3_f32 v130, v130, v92, v93
	v_max3_f32 v130, v130, v94, v95
	s_waitcnt lgkmcnt(4)
	v_mfma_f32_32x32x16_bf16 v[34:49], v[134:137], v[224:227], v[34:49]
	v_max3_f32 v130, v130, v96, v97
	v_max3_f32 v130, v130, v66, v67
	v_max3_f32 v130, v130, v68, v69
	v_max3_f32 v130, v130, v70, v71
	v_max3_f32 v130, v130, v72, v73
	v_max3_f32 v130, v130, v74, v75
	v_max3_f32 v130, v130, v76, v77
	v_max3_f32 v130, v130, v78, v79
	s_waitcnt lgkmcnt(2)
	v_mfma_f32_32x32x16_bf16 v[34:49], v[138:141], v[228:231], v[34:49]
	v_max3_f32 v130, v130, v80, v81
	v_mov_b32_e32 v131, v130
	s_nop 1
	v_permlane32_swap_b32_e32 v130, v131
	v_max_f32_e32 v130, v131, v130
	v_sub_f32_e32 v131, v130, v215
	s_mov_b32 s2, 0x42b504f3
	v_cmp_ge_f32_e32 vcc, s2, v131
	v_max_f32_e32 v131, v215, v130
	s_waitcnt lgkmcnt(0)
	v_mfma_f32_32x32x16_bf16 v[34:49], v[142:145], v[232:235], v[34:49]
	v_sub_f32_e32 v130, v215, v131
	v_mul_f32_e32 v130, 0x3e0293ee, v130
	v_exp_f32_e32 v130, v130
	s_cmp_eq_u64 vcc, exec
	s_cselect_b64 s[2:3], -1, 0
	s_waitcnt vmcnt(4)
	v_cndmask_b32_e64 v130, v130, 1.0, s[2:3]
	v_cmp_gt_f32_e32 vcc, 1.0, v130
	ds_write_b128 v177, v[118:121] offset:49152
	ds_write_b128 v208, v[122:125] offset:49152
	s_cbranch_vccz .LBB0_670
	s_and_saveexec_b64 s[6:7], s[0:1]
	ds_write_b32 v149, v130 offset:128
	s_or_b64 exec, exec, s[6:7]
	s_waitcnt lgkmcnt(0)
	v_add_u32_e32 v126, v148, v0
	ds_read_b128 v[114:117], v126 offset:128
	ds_read_b128 v[118:121], v126 offset:160
	ds_read_b128 v[122:125], v126 offset:192
	ds_read_b128 v[126:129], v126 offset:224
	s_waitcnt lgkmcnt(3)
	v_pk_mul_f32 v[50:51], v[114:115], v[50:51]
	v_pk_mul_f32 v[52:53], v[52:53], v[116:117]
	s_waitcnt lgkmcnt(2)
	v_pk_mul_f32 v[54:55], v[54:55], v[118:119]
	v_pk_mul_f32 v[56:57], v[56:57], v[120:121]
	s_waitcnt lgkmcnt(1)
	v_pk_mul_f32 v[58:59], v[58:59], v[122:123]
	v_pk_mul_f32 v[60:61], v[60:61], v[124:125]
	s_waitcnt lgkmcnt(0)
	v_pk_mul_f32 v[62:63], v[62:63], v[126:127]
	v_pk_mul_f32 v[30:31], v[30:31], v[126:127]
	v_pk_mul_f32 v[26:27], v[26:27], v[122:123]
	v_pk_mul_f32 v[22:23], v[22:23], v[118:119]
	v_pk_mul_f32 v[32:33], v[32:33], v[128:129]
	v_pk_mul_f32 v[28:29], v[28:29], v[124:125]
	v_pk_mul_f32 v[24:25], v[24:25], v[120:121]
	v_pk_mul_f32 v[20:21], v[20:21], v[116:117]
	v_pk_mul_f32 v[18:19], v[18:19], v[114:115]
	v_pk_mul_f32 v[64:65], v[64:65], v[128:129]
	v_pk_mul_f32 v[34:35], v[114:115], v[34:35]
	v_pk_mul_f32 v[36:37], v[36:37], v[116:117]
	v_pk_mul_f32 v[38:39], v[38:39], v[118:119]
	v_pk_mul_f32 v[40:41], v[40:41], v[120:121]
	v_pk_mul_f32 v[42:43], v[42:43], v[122:123]
	v_pk_mul_f32 v[44:45], v[44:45], v[124:125]
	v_pk_mul_f32 v[46:47], v[46:47], v[126:127]
	v_pk_mul_f32 v[14:15], v[14:15], v[126:127]
	v_pk_mul_f32 v[10:11], v[10:11], v[122:123]
	v_pk_mul_f32 v[6:7], v[6:7], v[118:119]
	v_pk_mul_f32 v[16:17], v[16:17], v[128:129]
	v_pk_mul_f32 v[12:13], v[12:13], v[124:125]
	v_pk_mul_f32 v[8:9], v[8:9], v[120:121]
	v_pk_mul_f32 v[4:5], v[4:5], v[116:117]
	v_pk_mul_f32 v[2:3], v[2:3], v[114:115]
	v_pk_mul_f32 v[48:49], v[48:49], v[128:129]

; __device__ __forceinline__ int opaque_tid() { int t = threadIdx.x; asm volatile("" : "+v"(t)); return t; }
; __device__ __forceinline__ int v_st(int k, int c) { const int kk = (k & ~0xC) | ((k & 4) << 1) | ((k & 8) >> 1); return ((kk >> 3) * 4 + (c >> 5)) * 512 + ((kk & 7) * 32 + (c & 31)) * 2; }
; __device__ __forceinline__ int v_rd_base(int lane) { return ((lane & 3) << 3) | (((lane >> 2) & 3) << 6) | (((lane >> 4) & 1) << 5) | (((lane >> 5) & 1) << 8); }
; #define HOOK(P0, P1, j) do { if (NA) na_hook(P0, P1, krow0 + (j), q_row, q_col, win_r, win_c, rpb, inv_scale, hi); } while (0)
; template <int DK, bool NA, bool QL, int SD> ...
;   const int tid = opaque_tid(), wid = tid >> 6, lane = tid & 63, r32 = lane & 31, hi = lane >> 5;
;   bf16* V_lds = (bf16*)lds; bf16* K_lds = (bf16*)(lds + 2 * SHM_V);
;   float* ws = (float*)(lds + 2 * SHM_V + 2 * SHM_K) + wid * 64; float* li_l = ws; float* al_l = ws + 32;
;   const float* rpb = (const float*)(lds + RPB_OFF);
;   int win_r = q_row - 4; win_r = win_r < 0 ? 0 : (win_r > 56 ? 56 : win_r);
;   int win_c = q_col - 8; win_c = win_c < 0 ? 0 : (win_c > 48 ? 48 : win_c);
;   float m_reg = -1e30f, l_reg = 0; bf16x8 qr[QL ? 1 : DK / 16];
;   char* ql = lds + Q_OFF + (wid * (DK / 16) * 64 + lane) * 16;
; #pragma unroll
;   for (int d = 0; d < 4; ++d) o[d] = f32x16{};
;   const bf16* Qw = Qb + (long)(wid * 32 + r32) * LDP + hi * 8;
; #pragma unroll
;   for (int d0 = 0; d0 < DK / 16; ++d0) { const bf16x8 qv = *reinterpret_cast<const bf16x8*>(Qw + d0 * 16); if (QL) *reinterpret_cast<bf16x8*>(ql + d0 * 1024) = qv; else qr[d0] = qv; }
;   const int sr = tid >> 4, sc = (tid & 15) * 8, vst0 = v_st(sr, sc), vst1 = v_st(32 + sr, sc);
;   const int ksr = DK == 128 ? sr : (tid >> 3), ksc = DK == 128 ? sc : (tid & 7) * 8;
;   const int vb0 = (int)(uintptr_t)V_lds + v_rd_base(lane);
;   struct { bf16x8 vs0, vs1, ks0, ks1; } sr_[SD];
;     ...
;   f32x16 pA0, pA1, pB0, pB1; float mnA, mnB, alA, alB; bf16x8 pa0, pa1, pa2, pa3;
;   constexpr int SE = 0, SO = SD - 1;
;   SLOAD(SE, 0); asm volatile("s_waitcnt vmcnt(0)" ::: "memory"); SWRITE(0, SE); __syncthreads();
;   qkt<DK, QL>(pA0, pA1, K_lds, qr, ql, r32, hi); HOOK(pA0, pA1, 0); partialSM(pA0, pA1, m_reg, mnA, alA, C, thrRaw);
;   SLOAD(SO, KVBLK); if (SD == 2) { if (2 < NT) SLOAD(SE, 2 * KVBLK); }
;   SWAIT(); SWRITE(1, SO); __syncthreads();
.LBB0_680:
	s_andn2_b64 vcc, exec, s[0:1]
	s_cbranch_vccnz .LBB0_369
	v_mov_b32_e32 v73, v188
	v_readlane_b32 s0, v253, 17
	v_readlane_b32 s1, v253, 18
	v_ashrrev_i32_e32 v74, 4, v73
	v_lshlrev_b32_e32 v16, 3, v73
	v_add_u32_e32 v18, 32, v74
	v_ashrrev_i32_e32 v75, 3, v73
	v_mov_b64_e32 v[50:51], s[0:1]
	s_movk_i32 s3, 0x2800
	v_and_b32_e32 v0, 0x78, v16
	v_mad_i64_i32 v[2:3], s[0:1], v74, s3, v[50:51]
	v_mad_i64_i32 v[4:5], s[0:1], v18, s3, v[50:51]
	v_mad_i64_i32 v[10:11], s[0:1], v75, s3, v[50:51]
	v_lshlrev_b32_e32 v52, 1, v0
	v_mov_b32_e32 v53, v1
	v_ashrrev_i32_e32 v0, 1, v73
	s_movk_i32 s0, 0xffe0
	v_lshlrev_b32_e32 v17, 4, v73
	v_lshl_add_u64 v[2:3], v[2:3], 0, v[52:53]
	v_lshl_add_u64 v[6:7], v[4:5], 0, v[52:53]
	v_bfi_b32 v0, s0, v0, v73
	v_readlane_b32 s0, v253, 9
	global_load_dwordx4 v[2:5], v[2:3], off offset:2048
	s_nop 0
	global_load_dwordx4 v[6:9], v[6:7], off offset:2048
	v_and_b32_e32 v54, 0x70, v17
	v_mov_b32_e32 v55, v1
	v_readlane_b32 s1, v253, 10
	v_lshl_add_u64 v[10:11], v[10:11], 0, v[54:55]
	global_load_dwordx4 v[10:13], v[10:11], off offset:1024
	v_mov_b64_e32 v[14:15], s[0:1]
	v_mad_i64_i32 v[14:15], s[0:1], v0, s3, v[14:15]
	v_lshrrev_b32_e32 v0, 1, v73
	v_and_b32_e32 v0, 16, v0
	v_lshl_add_u64 v[14:15], v[14:15], 0, v[0:1]
	global_load_dwordx4 v[110:113], v[14:15], off
	global_load_dwordx4 v[106:109], v[14:15], off offset:32
	global_load_dwordx4 v[98:101], v[14:15], off offset:64
	global_load_dwordx4 v[102:105], v[14:15], off offset:96
	v_add_u32_e32 v84, 64, v74
	v_add_u32_e32 v88, 0x60, v74
	v_add_u32_e32 v92, 64, v75
	v_mad_i64_i32 v[84:85], s[0:1], v84, s3, v[50:51]
	v_mad_i64_i32 v[88:89], s[0:1], v88, s3, v[50:51]
	v_mad_i64_i32 v[92:93], s[0:1], v92, s3, v[50:51]
	v_lshl_add_u64 v[84:85], v[84:85], 0, v[52:53]
	v_lshl_add_u64 v[88:89], v[88:89], 0, v[52:53]
	v_lshl_add_u64 v[92:93], v[92:93], 0, v[54:55]
	global_load_dwordx4 v[84:87], v[84:85], off offset:2048
	global_load_dwordx4 v[88:91], v[88:89], off offset:2048
	global_load_dwordx4 v[92:95], v[92:93], off offset:1024
	v_and_b32_e32 v20, 0xfffff0, v74
	v_lshlrev_b32_e32 v21, 1, v74
	v_lshrrev_b32_e32 v22, 1, v74
	v_and_b32_e32 v24, 3, v74
	v_and_or_b32 v20, v21, 8, v20
	v_and_or_b32 v21, v22, 4, v24
	v_and_b32_e32 v22, 0xfffff0, v18
	v_lshlrev_b32_e32 v18, 1, v18
	v_bfe_u32 v23, v16, 5, 2
	v_lshrrev_b32_e32 v14, 1, v20
	v_and_or_b32 v18, v18, 8, v22
	v_and_b32_e32 v76, 31, v73
	v_or_b32_e32 v14, v14, v23
	v_lshrrev_b32_e32 v18, 1, v18
	v_and_b32_e32 v25, 48, v17
	v_lshlrev_b32_e32 v60, 7, v76
	v_and_b32_e32 v16, 0x70, v16
	v_lshlrev_b32_e32 v15, 6, v21
	v_lshlrev_b32_e32 v14, 9, v14
	v_or_b32_e32 v18, v18, v23
	v_and_b32_e32 v19, 0x70, v73
	v_lshlrev_b32_e32 v26, 7, v75
	v_bitop3_b32 v24, v0, v60, v16 bitop3:0xde
	v_or3_b32 v14, v14, v15, v25
	v_lshlrev_b32_e32 v18, 9, v18
	v_bitop3_b32 v19, v54, v26, v19 bitop3:0xde
	v_add_u32_e32 v212, 0, v24
	v_or3_b32 v15, v18, v15, v25
	v_add_u32_e32 v214, 0, v14
	v_add_u32_e32 v213, 0, v19
	s_waitcnt vmcnt(0)
	v_add_u32_e32 v215, 0, v15
	s_add_i32 s8, 0, 0x10000
	v_and_b32_e32 v77, 63, v73
	v_add_u32_e32 v68, 64, v75
	v_mad_i64_i32 v[58:59], s[0:1], v74, s3, 0
	v_mad_i64_i32 v[56:57], s[0:1], v75, s3, 0
	v_mad_i64_i32 v[68:69], s[0:1], v68, s3, v[50:51]
	s_cmp_lg_u32 0, -1
	s_cselect_b32 s2, 0, 0
	v_lshl_add_u64 v[68:69], v[68:69], 0, v[54:55]
	s_waitcnt vmcnt(6)
	ds_write_b128 v214, v[2:5]
	s_waitcnt vmcnt(5)
	ds_write_b128 v215, v[6:9]
	s_waitcnt vmcnt(4)
	ds_write_b128 v213, v[10:13] offset:32768
	s_waitcnt lgkmcnt(0)
	s_barrier
	ds_read_b128 v[2:5], v212 offset:32768
	ds_read_b128 v[6:9], v212 offset:36864
	s_waitcnt vmcnt(3) lgkmcnt(1)
	v_mfma_f32_32x32x16_bf16 v[18:33], v[2:5], v[110:113], 0
	v_or_b32_e32 v2, 32, v0
	v_bitop3_b32 v2, v2, v60, v16 bitop3:0xde
	v_add_u32_e32 v216, 0, v2
	ds_read_b128 v[2:5], v216 offset:32768
	v_lshlrev_b32_e32 v10, 1, v73
	v_lshlrev_b32_e32 v11, 3, v77
	v_and_b32_e32 v12, 0xc0, v17
	s_waitcnt lgkmcnt(1)
	v_mfma_f32_32x32x16_bf16 v[34:49], v[6:9], v[110:113], 0
	v_and_b32_e32 v6, 0x3fffffc0, v73
	v_lshl_add_u32 v207, v6, 2, s8
	ds_read_b128 v[6:9], v216 offset:36864
	v_and_b32_e32 v10, 32, v10
	v_readlane_b32 s16, v254, 62
	v_readlane_b32 s17, v254, 63
	v_readlane_b32 s18, v255, 0
	s_waitcnt vmcnt(2) lgkmcnt(1)
	v_mfma_f32_32x32x16_bf16 v[18:33], v[2:5], v[106:109], v[18:33]
	v_or_b32_e32 v2, 64, v0
	v_bitop3_b32 v2, v2, v60, v16 bitop3:0xde
	v_add_u32_e32 v217, 0, v2
	ds_read_b128 v[2:5], v217 offset:32768
	v_readlane_b32 s19, v255, 1
	v_readlane_b32 s20, v255, 2
	v_readlane_b32 s21, v255, 3
	s_waitcnt lgkmcnt(1)
	v_mfma_f32_32x32x16_bf16 v[34:49], v[6:9], v[106:109], v[34:49]
	v_and_or_b32 v6, v11, 24, v12
	v_and_b32_e32 v7, 0x100, v11
	v_or3_b32 v78, v6, v10, v7
	ds_read_b128 v[6:9], v217 offset:36864
	v_readlane_b32 s22, v255, 4
	v_readlane_b32 s23, v255, 5
	v_readlane_b32 s24, v255, 6
	s_waitcnt vmcnt(1) lgkmcnt(1)
	v_mfma_f32_32x32x16_bf16 v[18:33], v[2:5], v[98:101], v[18:33]
	v_or_b32_e32 v2, 0x60, v0
	v_bitop3_b32 v2, v2, v60, v16 bitop3:0xde
	v_add_u32_e32 v218, 0, v2
	ds_read_b128 v[2:5], v218 offset:32768
	ds_read_b128 v[60:63], v218 offset:36864
	v_readlane_b32 s25, v255, 7
	v_readlane_b32 s26, v255, 8
	s_waitcnt lgkmcnt(2)
	v_mfma_f32_32x32x16_bf16 v[34:49], v[6:9], v[98:101], v[34:49]
	v_readlane_b32 s27, v255, 9
	v_readlane_b32 s28, v255, 10
	v_readlane_b32 s29, v255, 11
	v_readlane_b32 s30, v255, 12
	v_readlane_b32 s31, v255, 13
	s_mov_b32 s16, s17
	v_add_u32_e32 v211, s2, v78
	s_waitcnt vmcnt(0) lgkmcnt(1)
	v_mfma_f32_32x32x16_bf16 v[18:33], v[2:5], v[102:105], v[18:33]
	s_mov_b32 s18, s17
	s_mov_b32 s19, s17
	s_mov_b32 s20, s17
	s_mov_b32 s21, s17
	s_mov_b32 s22, s17
	s_mov_b32 s23, s17
	s_mov_b32 s24, s17
	s_waitcnt lgkmcnt(0)
; #define SLOAD(i, k0) do { sr_[i].vs0 = *reinterpret_cast<const bf16x8*>(&Vh[(long)((k0) + sr) * LDP + sc]); sr_[i].vs1 = *reinterpret_cast<const bf16x8*>(&Vh[(long)((k0) + 32 + sr) * LDP + sc]); \
;     sr_[i].ks0 = *reinterpret_cast<const bf16x8*>(&Kh[(long)((k0) + ksr) * LDP + ksc]); if (DK == 128) sr_[i].ks1 = *reinterpret_cast<const bf16x8*>(&Kh[(long)((k0) + 32 + ksr) * LDP + ksc]); } while (0)
; #define SWAIT() do { if (SD == 1) asm volatile("s_waitcnt vmcnt(0)" ::: "memory"); else if (DK == 128) asm volatile("s_waitcnt vmcnt(4)" ::: "memory"); else asm volatile("s_waitcnt vmcnt(3)" ::: "memory"); } while (0)
; #define HOOK(P0, P1, j) do { if (NA) na_hook(P0, P1, krow0 + (j), q_row, q_col, win_r, win_c, rpb, inv_scale, hi); } while (0)
; __device__ __forceinline__ void partialSM(f32x16& p0, f32x16& p1, float& m_reg, float& mn, float& alpha, float C, float thrRaw) {
;   float pmax = p0[0];
; #pragma unroll
;   for (int r = 1; r < 16; ++r) pmax = fmaxf(pmax, p0[r]);
; #pragma unroll
;   for (int r = 0; r < 16; ++r) pmax = fmaxf(pmax, p1[r]);
;   { auto rr = __builtin_amdgcn_permlane32_swap(__float_as_uint(pmax), __float_as_uint(pmax), false, false);
;     pmax = fmaxf(__uint_as_float(rr[0]), __uint_as_float(rr[1])); }
;   if (__builtin_expect(__all(pmax - m_reg <= thrRaw), 1)) { mn = m_reg; alpha = 1.f; }
;   else { mn = fmaxf(m_reg, pmax); alpha = __builtin_amdgcn_exp2f((m_reg - mn) * C); m_reg = mn; }
;   float mnC = -mn * C;
; #pragma unroll
;   for (int r = 0; r < 16; ++r) p0[r] = fmaf(p0[r], C, mnC);
; #pragma unroll
;   for (int r = 0; r < 16; ++r) p1[r] = fmaf(p1[r], C, mnC);
; #pragma unroll
;   for (int r = 0; r < 16; ++r) p0[r] = __builtin_amdgcn_exp2f(p0[r]);
; }
; template <int DK, bool NA, bool QL, int SD> ...
;     ...
;   SLOAD(SE, 0); asm volatile("s_waitcnt vmcnt(0)" ::: "memory"); SWRITE(0, SE); __syncthreads();
;   qkt<DK, QL>(pA0, pA1, K_lds, qr, ql, r32, hi); HOOK(pA0, pA1, 0); partialSM(pA0, pA1, m_reg, mnA, alA, C, thrRaw);
;   SLOAD(SO, KVBLK); if (SD == 2) { if (2 < NT) SLOAD(SE, 2 * KVBLK); }
;   SWAIT(); SWRITE(1, SO); __syncthreads();
	v_mfma_f32_32x32x16_bf16 v[34:49], v[60:63], v[102:105], v[34:49]
	s_nop 2
	v_max_f32_e32 v60, v19, v19
	v_max_f32_e32 v61, v18, v18
	v_max_f32_e32 v60, v61, v60
	v_max3_f32 v60, v60, v20, v21
	v_max3_f32 v60, v60, v22, v23
	v_max3_f32 v60, v60, v24, v25
	v_max3_f32 v60, v60, v26, v27
	v_max3_f32 v60, v60, v28, v29
	v_max3_f32 v60, v60, v30, v31
	v_max3_f32 v60, v60, v32, v33
	v_max3_f32 v60, v60, v34, v35
	v_max3_f32 v60, v60, v36, v37
	v_max3_f32 v60, v60, v38, v39
	v_max3_f32 v60, v60, v40, v41
	v_max3_f32 v72, v60, v42, v43
	v_max3_f32 v72, v72, v44, v45
	v_max3_f32 v72, v72, v46, v47
	v_max3_f32 v72, v72, v48, v49
	v_mov_b32_e32 v79, v72
	s_nop 1
	v_permlane32_swap_b32_e32 v72, v79
	v_add_u32_e32 v60, 64, v74
	v_add_u32_e32 v62, 0x60, v74
	v_max_f32_e32 v79, v79, v79
	v_max_f32_e32 v72, v72, v72
	v_mad_i64_i32 v[60:61], s[0:1], v60, s3, v[50:51]
	v_mad_i64_i32 v[62:63], s[0:1], v62, s3, v[50:51]
	v_max_f32_e32 v72, v72, v79
	v_add_f32_e32 v79, 0x7149f2ca, v72
	s_mov_b32 s0, 0x42800000
	v_max_f32_e32 v72, 0xf149f2ca, v72
	v_cmp_ge_f32_e32 vcc, s0, v79
	v_sub_f32_e32 v79, 0xf149f2ca, v72
	v_mul_f32_e32 v79, 0x3e38aa3b, v79
	v_exp_f32_e32 v79, v79
	s_cmp_eq_u64 vcc, exec
	s_cselect_b64 vcc, -1, 0
	v_cndmask_b32_e32 v142, v72, v199, vcc
	v_mul_f32_e32 v72, 0xbe38aa3b, v142
	v_cndmask_b32_e64 v219, v79, 1.0, vcc
	v_fmamk_f32 v79, v18, 0x3e38aa3b, v72
	v_add_u32_e32 v18, 0x80, v75
	v_fmamk_f32 v80, v19, 0x3e38aa3b, v72
	v_mad_i64_i32 v[18:19], s[0:1], v18, s3, v[50:51]
	v_lshl_add_u64 v[60:61], v[60:61], 0, v[52:53]
	v_lshl_add_u64 v[64:65], v[62:63], 0, v[52:53]
	v_lshl_add_u64 v[18:19], v[18:19], 0, v[54:55]
	s_nop 0
	v_fmamk_f32 v81, v20, 0x3e38aa3b, v72
	v_add_u32_e32 v20, 0x80, v74
	global_load_dwordx4 v[122:125], v[18:19], off offset:1024
	v_add_u32_e32 v18, 0xa0, v74
	v_mad_i64_i32 v[18:19], s[0:1], v18, s3, v[50:51]
	v_fmamk_f32 v82, v21, 0x3e38aa3b, v72
	v_lshl_add_u64 v[18:19], v[18:19], 0, v[52:53]
	v_mad_i64_i32 v[20:21], s[0:1], v20, s3, v[50:51]
	v_lshl_add_u64 v[20:21], v[20:21], 0, v[52:53]
	global_load_dwordx4 v[118:121], v[18:19], off offset:2048
	global_load_dwordx4 v[114:117], v[20:21], off offset:2048
	v_mov_b32_e32 v20, v72
	v_fmamk_f32 v22, v22, 0x3e38aa3b, v72
	v_fmamk_f32 v23, v23, 0x3e38aa3b, v72
	v_fmamk_f32 v24, v24, 0x3e38aa3b, v72
	v_fmamk_f32 v25, v25, 0x3e38aa3b, v72
	v_fmamk_f32 v26, v26, 0x3e38aa3b, v72
	v_fmamk_f32 v27, v27, 0x3e38aa3b, v72
	v_fmamk_f32 v28, v28, 0x3e38aa3b, v72
	v_fmamk_f32 v29, v29, 0x3e38aa3b, v72
	v_fmamk_f32 v30, v30, 0x3e38aa3b, v72
	v_fmamk_f32 v18, v31, 0x3e38aa3b, v72
	v_fmamk_f32 v19, v32, 0x3e38aa3b, v72
	v_fmac_f32_e32 v20, 0x3e38aa3b, v33
	s_mov_b32 s25, s17
	s_mov_b32 s26, s17
	s_mov_b32 s27, s17
	s_mov_b32 s28, s17
	s_mov_b32 s29, s17
	s_mov_b32 s30, s17
	s_mov_b32 s31, s17
	v_mov_b64_e32 v[2:3], s[16:17]
	v_exp_f32_e32 v177, v79
	v_exp_f32_e32 v226, v80
	v_exp_f32_e32 v161, v81
	v_exp_f32_e32 v223, v82
	v_exp_f32_e32 v153, v22
	v_exp_f32_e32 v176, v23
	v_exp_f32_e32 v152, v24
	v_exp_f32_e32 v160, v25
	v_exp_f32_e32 v149, v26
	v_exp_f32_e32 v151, v27
	v_exp_f32_e32 v147, v28
	v_exp_f32_e32 v150, v29
	v_exp_f32_e32 v145, v30
	v_exp_f32_e32 v148, v18
	v_exp_f32_e32 v144, v19
	v_exp_f32_e32 v146, v20
	s_addk_i32 s2, 0x4000
	v_and_b32_e32 v18, 15, v73
	v_mov_b64_e32 v[16:17], s[30:31]
	s_waitcnt vmcnt(3)
	v_add_u32_e32 v210, s2, v78
	v_lshl_or_b32 v58, v18, 4, v58
	v_readlane_b32 s2, v254, 34
	v_and_b32_e32 v18, 7, v73
	v_mov_b64_e32 v[4:5], s[18:19]
	v_mov_b64_e32 v[6:7], s[20:21]
	v_mov_b64_e32 v[8:9], s[22:23]
	v_mov_b64_e32 v[10:11], s[24:25]
	v_mov_b64_e32 v[12:13], s[26:27]
	v_mov_b64_e32 v[14:15], s[28:29]
	s_mov_b32 s0, 0x3e38aa3b
	v_readlane_b32 s3, v254, 35
	v_lshl_or_b32 v56, v18, 4, v56
	v_mov_b32_e32 v209, 0
	v_mov_b64_e32 v[32:33], v[16:17]
	s_mov_b32 s9, 1
	s_mov_b32 s13, s17
	v_pk_fma_f32 v[132:133], v[48:49], s[0:1], v[72:73] op_sel_hi:[1,0,0]
	v_pk_fma_f32 v[134:135], v[46:47], s[0:1], v[72:73] op_sel_hi:[1,0,0]
	v_pk_fma_f32 v[140:141], v[44:45], s[0:1], v[72:73] op_sel_hi:[1,0,0]
	v_pk_fma_f32 v[126:127], v[42:43], s[0:1], v[72:73] op_sel_hi:[1,0,0]
	v_pk_fma_f32 v[128:129], v[40:41], s[0:1], v[72:73] op_sel_hi:[1,0,0]
	v_pk_fma_f32 v[130:131], v[38:39], s[0:1], v[72:73] op_sel_hi:[1,0,0]
	v_pk_fma_f32 v[136:137], v[36:37], s[0:1], v[72:73] op_sel_hi:[1,0,0]
	v_pk_fma_f32 v[138:139], v[34:35], s[0:1], v[72:73] op_sel_hi:[1,0,0]
	s_waitcnt vmcnt(5)
	ds_write_b128 v214, v[84:87] offset:16384
	s_waitcnt vmcnt(4)
	ds_write_b128 v215, v[88:91] offset:16384
	s_waitcnt vmcnt(3)
	ds_write_b128 v213, v[92:95] offset:49152
	v_cmp_gt_u32_e64 s[0:1], 32, v77
	v_lshl_add_u32 v208, v76, 2, v207
	v_lshl_add_u64 v[156:157], s[2:3], 0, v[58:59]
	v_lshl_add_u64 v[158:159], s[2:3], 0, v[56:57]
	v_mov_b64_e32 v[30:31], v[14:15]
	v_mov_b64_e32 v[28:29], v[12:13]
	v_mov_b64_e32 v[26:27], v[10:11]
	v_mov_b64_e32 v[24:25], v[8:9]
	v_mov_b64_e32 v[22:23], v[6:7]
	v_mov_b64_e32 v[20:21], v[4:5]
	v_mov_b64_e32 v[18:19], v[2:3]
	v_mov_b32_e32 v34, 0
	v_mov_b32_e32 v35, v209
	v_mov_b32_e32 v36, v209
	v_mov_b32_e32 v37, v209
	v_mov_b32_e32 v38, v209
	v_mov_b32_e32 v39, v209
	v_mov_b32_e32 v40, v209
	v_mov_b32_e32 v41, v209
	v_mov_b32_e32 v42, v209
	v_mov_b32_e32 v43, v209
	v_mov_b32_e32 v44, v209
	v_mov_b32_e32 v45, v209
	v_mov_b32_e32 v46, v209
	v_mov_b32_e32 v47, v209
	v_mov_b32_e32 v48, v209
	v_mov_b32_e32 v49, v209
	v_mov_b32_e32 v50, 0
	v_mov_b32_e32 v51, v209
	v_mov_b32_e32 v52, v209
	v_mov_b32_e32 v53, v209
	v_mov_b32_e32 v54, v209
	v_mov_b32_e32 v55, v209
	v_mov_b32_e32 v56, v209
	v_mov_b32_e32 v57, v209
	v_mov_b32_e32 v58, v209
	v_mov_b32_e32 v59, v209
	v_mov_b32_e32 v60, v209
	v_mov_b32_e32 v61, v209
	v_mov_b32_e32 v62, v209
	v_mov_b32_e32 v63, v209
	v_mov_b32_e32 v64, v209
	v_mov_b32_e32 v65, v209
	v_readlane_b32 s6, v254, 32
	v_readlane_b32 s7, v254, 33
	s_nop 3
	v_lshl_add_u64 v[178:179], v[156:157], 0, s[6:7]
	v_lshl_add_u64 v[204:205], v[158:159], 0, s[6:7]
	s_mov_b32 s6, 0xe130000
	s_mov_b32 s7, 0
	s_nop 0
	v_lshl_add_u64 v[180:181], v[178:179], 0, s[6:7]
	s_mov_b32 s6, 0xe0e0000
	s_nop 0
	v_lshl_add_u64 v[178:179], v[178:179], 0, s[6:7]
	v_lshl_add_u64 v[204:205], v[204:205], 0, s[6:7]
	s_waitcnt lgkmcnt(0)
	s_barrier
; #define SBAR() __builtin_amdgcn_sched_barrier(0)
; #define SLOAD(i, k0) do { sr_[i].vs0 = *reinterpret_cast<const bf16x8*>(&Vh[(long)((k0) + sr) * LDP + sc]); sr_[i].vs1 = *reinterpret_cast<const bf16x8*>(&Vh[(long)((k0) + 32 + sr) * LDP + sc]); \
;     sr_[i].ks0 = *reinterpret_cast<const bf16x8*>(&Kh[(long)((k0) + ksr) * LDP + ksc]); if (DK == 128) sr_[i].ks1 = *reinterpret_cast<const bf16x8*>(&Kh[(long)((k0) + 32 + ksr) * LDP + ksc]); } while (0)
; #define HOOK(P0, P1, j) do { if (NA) na_hook(P0, P1, krow0 + (j), q_row, q_col, win_r, win_c, rpb, inv_scale, hi); } while (0)
; __device__ __forceinline__ void finishSM(f32x16& p0, f32x16& p1, float alpha, float& l_reg, bf16x8& pa0, bf16x8& pa1, bf16x8& pa2, bf16x8& pa3) {
; #pragma unroll
;   for (int r = 0; r < 16; ++r) p1[r] = __builtin_amdgcn_exp2f(p1[r]);
;   float ps = 0;
; #pragma unroll
;   for (int r = 0; r < 16; ++r) ps += p0[r];
; #pragma unroll
;   for (int r = 0; r < 16; ++r) ps += p1[r];
;   { auto rr = __builtin_amdgcn_permlane32_swap(__float_as_uint(ps), __float_as_uint(ps), false, false);
;     ps = __uint_as_float(rr[0]) + __uint_as_float(rr[1]); }
;   l_reg = l_reg * alpha + ps;
;     ...
;   PK4(p0, 0, pa0); PK4(p0, 8, pa1); PK4(p1, 0, pa2); PK4(p1, 8, pa3);
;     ...
; }
; template <int DK, bool QL>
; __device__ __forceinline__ void qkt(f32x16& p0, f32x16& p1, const bf16* Ks, const bf16x8* qr, const char* ql, int r32, int hi) {
;   p0 = f32x16{}; p1 = f32x16{};
; #pragma unroll
;   for (int d0 = 0; d0 < DK / 16; ++d0) { int cb = (d0 * 16 + hi * 8) * 2;
;     const bf16x8 qv = QL ? *reinterpret_cast<const bf16x8*>(ql + d0 * 1024) : qr[d0];
;     bf16x8 b0 = *reinterpret_cast<const bf16x8*>((const char*)Ks + kswz<DK>(r32, cb));
;     bf16x8 b1 = *reinterpret_cast<const bf16x8*>((const char*)Ks + kswz<DK>(32 + r32, cb));
;     p0 = __builtin_amdgcn_mfma_f32_32x32x16_bf16(b0, qv, p0, 0, 0, 0);
;     p1 = __builtin_amdgcn_mfma_f32_32x32x16_bf16(b1, qv, p1, 0, 0, 0); }
; }
; template <int DK, bool NA, bool QL, int SD> ...
;     ...
;     SBAR(); qkt<DK, QL>(pB0, pB1, (bf16*)((char*)K_lds + SHM_K), qr, ql, r32, hi); HOOK(pB0, pB1, j);
;     finishSM(pA0, pA1, alA, l_reg, pa0, pa1, pa2, pa3); SBAR();
;     SLOAD(SO, (j + SD) * KVBLK); SBAR();
;     pv_d0(o, vb0, pa0, pa1, pa2, pa3); partialSM(pB0, pB1, m_reg, mnB, alB, C, thrRaw);
.LBB0_682:
	ds_read_b128 v[66:69], v212 offset:49152
	ds_read_b128 v[70:73], v212 offset:53248
	v_exp_f32_e32 v143, v138
	v_add_f32_e32 v138, 0, v177
	v_add_f32_e32 v138, v226, v138
	s_waitcnt lgkmcnt(1)
	v_mfma_f32_32x32x16_bf16 v[82:97], v[66:69], v[110:113], 0
	v_add_f32_e32 v138, v161, v138
	v_add_f32_e32 v138, v223, v138
	v_add_f32_e32 v138, v153, v138
	ds_read_b128 v[228:231], v216 offset:49152
	ds_read_b128 v[232:235], v216 offset:53248
	v_add_f32_e32 v138, v176, v138
	v_add_f32_e32 v138, v152, v138
	v_add_f32_e32 v138, v160, v138
	s_waitcnt lgkmcnt(2)
	v_mfma_f32_32x32x16_bf16 v[66:81], v[70:73], v[110:113], 0
	v_add_f32_e32 v138, v149, v138
	v_add_f32_e32 v138, v151, v138
	v_add_f32_e32 v138, v147, v138
	v_add_f32_e32 v138, v150, v138
	v_add_f32_e32 v138, v145, v138
	v_exp_f32_e32 v164, v139
	v_add_f32_e32 v138, v148, v138
	s_waitcnt lgkmcnt(1)
	v_mfma_f32_32x32x16_bf16 v[82:97], v[228:231], v[106:109], v[82:97]
	v_exp_f32_e32 v136, v136
	v_add_f32_e32 v138, v144, v138
	v_exp_f32_e32 v137, v137
	v_add_f32_e32 v138, v146, v138
	v_exp_f32_e32 v130, v130
	v_add_f32_e32 v138, v143, v138
	v_exp_f32_e32 v131, v131
	s_waitcnt lgkmcnt(0)
	v_mfma_f32_32x32x16_bf16 v[66:81], v[232:235], v[106:109], v[66:81]
	ds_read_b128 v[228:231], v217 offset:49152
	ds_read_b128 v[232:235], v217 offset:53248
	v_add_f32_e32 v138, v164, v138
	v_exp_f32_e32 v128, v128
	v_add_f32_e32 v138, v136, v138
	v_exp_f32_e32 v129, v129
	v_add_f32_e32 v138, v137, v138
	v_exp_f32_e32 v126, v126
	s_waitcnt lgkmcnt(1)
	v_mfma_f32_32x32x16_bf16 v[82:97], v[228:231], v[98:101], v[82:97]
	v_add_f32_e32 v138, v130, v138
	v_exp_f32_e32 v127, v127
	v_add_f32_e32 v138, v131, v138
	v_exp_f32_e32 v165, v140
	v_add_f32_e32 v138, v128, v138
	v_exp_f32_e32 v166, v141
	v_add_f32_e32 v138, v129, v138
	s_waitcnt lgkmcnt(0)
	v_mfma_f32_32x32x16_bf16 v[66:81], v[232:235], v[98:101], v[66:81]
	ds_read_b128 v[228:231], v218 offset:49152
	ds_read_b128 v[232:235], v218 offset:53248
	v_exp_f32_e32 v134, v134
	v_add_f32_e32 v138, v126, v138
	v_exp_f32_e32 v135, v135
	v_add_f32_e32 v138, v127, v138
	v_exp_f32_e32 v132, v132
	v_add_f32_e32 v138, v165, v138
	s_waitcnt lgkmcnt(1)
	v_mfma_f32_32x32x16_bf16 v[82:97], v[228:231], v[102:105], v[82:97]
	v_exp_f32_e32 v133, v133
	v_add_f32_e32 v138, v166, v138
	v_add_f32_e32 v138, v134, v138
	v_add_f32_e32 v138, v135, v138
	v_add_f32_e32 v138, v132, v138
	v_add_f32_e32 v220, v133, v138
	v_mov_b32_e32 v221, v220
	s_waitcnt lgkmcnt(0)
	v_mfma_f32_32x32x16_bf16 v[66:81], v[232:235], v[102:105], v[66:81]
	v_cvt_pk_bf16_f32 v138, v177, v226
	v_cvt_pk_bf16_f32 v139, v161, v223
	v_cvt_pk_bf16_f32 v140, v153, v176
	v_cvt_pk_bf16_f32 v141, v152, v160
	v_cvt_pk_bf16_f32 v222, v149, v151
	v_cvt_pk_bf16_f32 v223, v147, v150
	v_cvt_pk_bf16_f32 v224, v145, v148
	v_permlane32_swap_b32_e32 v220, v221
	v_permlane32_swap_b32_e32 v138, v140
	v_cvt_pk_bf16_f32 v225, v144, v146
	v_permlane32_swap_b32_e32 v222, v224
	v_cvt_pk_bf16_f32 v144, v143, v164
	v_cvt_pk_bf16_f32 v145, v136, v137
	v_cvt_pk_bf16_f32 v146, v130, v131
	v_cvt_pk_bf16_f32 v147, v128, v129
	v_cvt_pk_bf16_f32 v148, v126, v127
	v_cvt_pk_bf16_f32 v149, v165, v166
	v_cvt_pk_bf16_f32 v150, v134, v135
	v_cvt_pk_bf16_f32 v151, v132, v133
	v_permlane32_swap_b32_e32 v139, v141
	v_permlane32_swap_b32_e32 v223, v225
	v_permlane32_swap_b32_e32 v144, v146
	v_permlane32_swap_b32_e32 v145, v147
	v_permlane32_swap_b32_e32 v148, v150
	v_permlane32_swap_b32_e32 v149, v151
	global_load_dwordx4 v[182:185], v[178:179], off offset:2048
	global_load_dwordx4 v[194:197], v[180:181], off offset:2048
	global_load_dwordx4 v[134:137], v[204:205], off offset:1024
	s_mov_b32 s4, 0xa0000
	s_mov_b32 s5, 0
	s_nop 0
	v_lshl_add_u64 v[178:179], v[178:179], 0, s[4:5]
	v_lshl_add_u64 v[180:181], v[180:181], 0, s[4:5]
	v_lshl_add_u64 v[204:205], v[204:205], 0, s[4:5]
	ds_read_b64_tr_b16 v[226:227], v211 offset:0
	ds_read_b64_tr_b16 v[228:229], v211 offset:0x800
	ds_read_b64_tr_b16 v[230:231], v211 offset:0x1000
	ds_read_b64_tr_b16 v[232:233], v211 offset:0x1800
	ds_read_b64_tr_b16 v[234:235], v211 offset:0x2000
	ds_read_b64_tr_b16 v[236:237], v211 offset:0x2800
	ds_read_b64_tr_b16 v[238:239], v211 offset:0x3000
	ds_read_b64_tr_b16 v[240:241], v211 offset:0x3800
	s_waitcnt lgkmcnt(6)
	s_nop 0
	v_mfma_f32_32x32x16_bf16 v[18:33], v[138:141], v[226:229], v[18:33]
	ds_read_b64_tr_b16 v[226:227], v211 offset:0x200
	ds_read_b64_tr_b16 v[228:229], v211 offset:0xa00
	s_waitcnt lgkmcnt(6)
	v_mfma_f32_32x32x16_bf16 v[18:33], v[222:225], v[230:233], v[18:33]
	ds_read_b64_tr_b16 v[230:231], v211 offset:0x1200
	ds_read_b64_tr_b16 v[232:233], v211 offset:0x1a00
	s_waitcnt lgkmcnt(6)
	v_mfma_f32_32x32x16_bf16 v[18:33], v[144:147], v[234:237], v[18:33]
	ds_read_b64_tr_b16 v[234:235], v211 offset:0x2200
	ds_read_b64_tr_b16 v[236:237], v211 offset:0x2a00
	s_waitcnt lgkmcnt(6)
	v_mfma_f32_32x32x16_bf16 v[18:33], v[148:151], v[238:241], v[18:33]
	ds_read_b64_tr_b16 v[238:239], v211 offset:0x3200
	ds_read_b64_tr_b16 v[240:241], v211 offset:0x3a00
	s_waitcnt lgkmcnt(6)
	v_mfma_f32_32x32x16_bf16 v[2:17], v[138:141], v[226:229], v[2:17]
	ds_read_b64_tr_b16 v[226:227], v211 offset:0x400
	ds_read_b64_tr_b16 v[228:229], v211 offset:0xc00
	s_waitcnt lgkmcnt(6)
	v_mfma_f32_32x32x16_bf16 v[2:17], v[222:225], v[230:233], v[2:17]
	ds_read_b64_tr_b16 v[230:231], v211 offset:0x1400
	ds_read_b64_tr_b16 v[232:233], v211 offset:0x1c00
	s_waitcnt lgkmcnt(6)
	v_mfma_f32_32x32x16_bf16 v[2:17], v[144:147], v[234:237], v[2:17]
	ds_read_b64_tr_b16 v[234:235], v211 offset:0x2400
	ds_read_b64_tr_b16 v[236:237], v211 offset:0x2c00
	s_waitcnt lgkmcnt(6)
; #define SBAR() __builtin_amdgcn_sched_barrier(0)
; __device__ __forceinline__ void partialSM(f32x16& p0, f32x16& p1, float& m_reg, float& mn, float& alpha, float C, float thrRaw) {
;   float pmax = p0[0];
; #pragma unroll
;   for (int r = 1; r < 16; ++r) pmax = fmaxf(pmax, p0[r]);
; #pragma unroll
;   for (int r = 0; r < 16; ++r) pmax = fmaxf(pmax, p1[r]);
;   { auto rr = __builtin_amdgcn_permlane32_swap(__float_as_uint(pmax), __float_as_uint(pmax), false, false);
;     pmax = fmaxf(__uint_as_float(rr[0]), __uint_as_float(rr[1])); }
;   if (__builtin_expect(__all(pmax - m_reg <= thrRaw), 1)) { mn = m_reg; alpha = 1.f; }
;   else { mn = fmaxf(m_reg, pmax); alpha = __builtin_amdgcn_exp2f((m_reg - mn) * C); m_reg = mn; }
;   float mnC = -mn * C;
; #pragma unroll
;   for (int r = 0; r < 16; ++r) p0[r] = fmaf(p0[r], C, mnC);
; #pragma unroll
;   for (int r = 0; r < 16; ++r) p1[r] = fmaf(p1[r], C, mnC);
; #pragma unroll
;   for (int r = 0; r < 16; ++r) p0[r] = __builtin_amdgcn_exp2f(p0[r]);
; }
; template <int D0> __device__ __forceinline__ void pv_one(f32x16& od, int vb, bf16x8 pa0, bf16x8 pa1, bf16x8 pa2, bf16x8 pa3) {
;   const s16x4 l0 = tr_read<v_rd_off(D0, 0, 0)>(vb), h0 = tr_read<v_rd_off(D0, 0, 1)>(vb), l1 = tr_read<v_rd_off(D0, 1, 0)>(vb), h1 = tr_read<v_rd_off(D0, 1, 1)>(vb);
;   const s16x4 l2 = tr_read<v_rd_off(D0, 2, 0)>(vb), h2 = tr_read<v_rd_off(D0, 2, 1)>(vb), l3 = tr_read<v_rd_off(D0, 3, 0)>(vb), h3 = tr_read<v_rd_off(D0, 3, 1)>(vb);
;   asm volatile("s_waitcnt lgkmcnt(0)" ::: "memory"); SBAR();
;     ...
;   od = __builtin_amdgcn_mfma_f32_32x32x16_bf16(pa0, PK(l0, h0), od, 0, 0, 0);
;   od = __builtin_amdgcn_mfma_f32_32x32x16_bf16(pa1, PK(l1, h1), od, 0, 0, 0);
;   od = __builtin_amdgcn_mfma_f32_32x32x16_bf16(pa2, PK(l2, h2), od, 0, 0, 0);
;   od = __builtin_amdgcn_mfma_f32_32x32x16_bf16(pa3, PK(l3, h3), od, 0, 0, 0);
;     ...
; }
; __device__ __forceinline__ void pv_d0(f32x16* o, int vb, bf16x8 pa0, bf16x8 pa1, bf16x8 pa2, bf16x8 pa3) {
;   pv_one<0>(o[0], vb, pa0, pa1, pa2, pa3); pv_one<1>(o[1], vb, pa0, pa1, pa2, pa3); pv_one<2>(o[2], vb, pa0, pa1, pa2, pa3); pv_one<3>(o[3], vb, pa0, pa1, pa2, pa3);
	v_mfma_f32_32x32x16_bf16 v[2:17], v[148:151], v[238:241], v[2:17]
	ds_read_b64_tr_b16 v[238:239], v211 offset:0x3400
	ds_read_b64_tr_b16 v[240:241], v211 offset:0x3c00
	s_waitcnt lgkmcnt(6)
	v_mfma_f32_32x32x16_bf16 v[50:65], v[138:141], v[226:229], v[50:65]
	ds_read_b64_tr_b16 v[226:227], v211 offset:0x600
	ds_read_b64_tr_b16 v[228:229], v211 offset:0xe00
	s_waitcnt lgkmcnt(6)
	v_mfma_f32_32x32x16_bf16 v[50:65], v[222:225], v[230:233], v[50:65]
	ds_read_b64_tr_b16 v[230:231], v211 offset:0x1600
	ds_read_b64_tr_b16 v[232:233], v211 offset:0x1e00
	s_waitcnt lgkmcnt(6)
	v_mfma_f32_32x32x16_bf16 v[50:65], v[144:147], v[234:237], v[50:65]
	ds_read_b64_tr_b16 v[234:235], v211 offset:0x2600
	ds_read_b64_tr_b16 v[236:237], v211 offset:0x2e00
	s_waitcnt lgkmcnt(6)
	v_mfma_f32_32x32x16_bf16 v[50:65], v[148:151], v[238:241], v[50:65]
	ds_read_b64_tr_b16 v[238:239], v211 offset:0x3600
	ds_read_b64_tr_b16 v[240:241], v211 offset:0x3e00
	s_waitcnt lgkmcnt(6)
	v_mfma_f32_32x32x16_bf16 v[34:49], v[138:141], v[226:229], v[34:49]
	v_max_f32_e32 v138, v83, v82
	v_max3_f32 v138, v138, v84, v85
	v_max3_f32 v138, v138, v86, v87
	v_max3_f32 v138, v138, v88, v89
	v_max3_f32 v138, v138, v90, v91
	v_max3_f32 v138, v138, v92, v93
	v_max3_f32 v138, v138, v94, v95
	s_waitcnt lgkmcnt(4)
	v_mfma_f32_32x32x16_bf16 v[34:49], v[222:225], v[230:233], v[34:49]
	v_max3_f32 v138, v138, v96, v97
	v_max3_f32 v138, v138, v66, v67
	v_max3_f32 v138, v138, v68, v69
	v_max3_f32 v138, v138, v70, v71
	v_max3_f32 v138, v138, v72, v73
	v_max3_f32 v138, v138, v74, v75
	v_max3_f32 v138, v138, v76, v77
	v_max3_f32 v138, v138, v78, v79
	s_waitcnt lgkmcnt(2)
	v_mfma_f32_32x32x16_bf16 v[34:49], v[144:147], v[234:237], v[34:49]
	v_max3_f32 v138, v138, v80, v81
	v_mov_b32_e32 v139, v138
	s_nop 1
	v_permlane32_swap_b32_e32 v138, v139
	v_max_f32_e32 v138, v139, v138
	v_sub_f32_e32 v139, v138, v142
	s_mov_b32 s2, 0x42800000
	v_cmp_ge_f32_e32 vcc, s2, v139
	v_max_f32_e32 v138, v142, v138
	s_waitcnt lgkmcnt(0)
	v_mfma_f32_32x32x16_bf16 v[34:49], v[148:151], v[238:241], v[34:49]
	v_sub_f32_e32 v139, v142, v138
	v_mul_f32_e32 v139, 0x3e38aa3b, v139
	v_exp_f32_e32 v139, v139
	s_cmp_eq_u64 vcc, exec
	s_cselect_b64 s[2:3], -1, 0
	s_waitcnt vmcnt(3)
	v_cndmask_b32_e64 v222, v139, 1.0, s[2:3]
	v_cmp_gt_f32_e32 vcc, 1.0, v222
	s_waitcnt vmcnt(3)
	ds_write_b128 v213, v[122:125] offset:32768
	s_cbranch_vccz .LBB0_686
	s_and_saveexec_b64 s[4:5], s[0:1]
	ds_write_b32 v208, v222 offset:128
	s_or_b64 exec, exec, s[4:5]
	s_waitcnt lgkmcnt(0)
	v_add_u32_e32 v139, v207, v0
	ds_read_b128 v[144:147], v139 offset:128
	ds_read_b128 v[148:151], v139 offset:160
	ds_read_b128 v[224:227], v139 offset:192
	ds_read_b128 v[228:231], v139 offset:224
	s_waitcnt lgkmcnt(3)
	v_pk_mul_f32 v[2:3], v[144:145], v[2:3]
	v_pk_mul_f32 v[4:5], v[4:5], v[146:147]
	s_waitcnt lgkmcnt(2)
	v_pk_mul_f32 v[6:7], v[6:7], v[148:149]
	v_pk_mul_f32 v[8:9], v[8:9], v[150:151]
	s_waitcnt lgkmcnt(1)
	v_pk_mul_f32 v[10:11], v[10:11], v[224:225]
	v_pk_mul_f32 v[12:13], v[12:13], v[226:227]
	s_waitcnt lgkmcnt(0)
	v_pk_mul_f32 v[14:15], v[14:15], v[228:229]
	v_pk_mul_f32 v[30:31], v[30:31], v[228:229]
	v_pk_mul_f32 v[26:27], v[26:27], v[224:225]
	v_pk_mul_f32 v[22:23], v[22:23], v[148:149]
	v_pk_mul_f32 v[32:33], v[32:33], v[230:231]
	v_pk_mul_f32 v[28:29], v[28:29], v[226:227]
	v_pk_mul_f32 v[24:25], v[24:25], v[150:151]
	v_pk_mul_f32 v[20:21], v[20:21], v[146:147]
	v_pk_mul_f32 v[18:19], v[18:19], v[144:145]
	v_pk_mul_f32 v[16:17], v[16:17], v[230:231]
	v_pk_mul_f32 v[34:35], v[144:145], v[34:35]
	v_pk_mul_f32 v[36:37], v[36:37], v[146:147]
	v_pk_mul_f32 v[38:39], v[38:39], v[148:149]
	v_pk_mul_f32 v[40:41], v[40:41], v[150:151]
	v_pk_mul_f32 v[42:43], v[42:43], v[224:225]
	v_pk_mul_f32 v[44:45], v[44:45], v[226:227]
	v_pk_mul_f32 v[46:47], v[46:47], v[228:229]
	v_pk_mul_f32 v[62:63], v[62:63], v[228:229]
	v_pk_mul_f32 v[58:59], v[58:59], v[224:225]
	v_pk_mul_f32 v[54:55], v[54:55], v[148:149]
	v_pk_mul_f32 v[64:65], v[64:65], v[230:231]
	v_pk_mul_f32 v[60:61], v[60:61], v[226:227]
	v_pk_mul_f32 v[56:57], v[56:57], v[150:151]
	v_pk_mul_f32 v[52:53], v[52:53], v[146:147]
	v_pk_mul_f32 v[50:51], v[50:51], v[144:145]
	v_pk_mul_f32 v[48:49], v[48:49], v[230:231]
.LBB0_686:
	v_cndmask_b32_e64 v223, v138, v142, s[2:3]
	v_mul_f32_e32 v224, 0xbe38aa3b, v223
	v_fmamk_f32 v82, v82, 0x3e38aa3b, v224
	v_fmamk_f32 v83, v83, 0x3e38aa3b, v224
	v_fmamk_f32 v84, v84, 0x3e38aa3b, v224
	v_fmamk_f32 v85, v85, 0x3e38aa3b, v224
	v_fmamk_f32 v86, v86, 0x3e38aa3b, v224
	v_fmamk_f32 v87, v87, 0x3e38aa3b, v224
	v_fmamk_f32 v88, v88, 0x3e38aa3b, v224
	v_fmamk_f32 v89, v89, 0x3e38aa3b, v224
	v_fmamk_f32 v90, v90, 0x3e38aa3b, v224
	v_fmamk_f32 v91, v91, 0x3e38aa3b, v224
	v_fmamk_f32 v92, v92, 0x3e38aa3b, v224
	v_fmamk_f32 v93, v93, 0x3e38aa3b, v224
	v_fmamk_f32 v94, v94, 0x3e38aa3b, v224
	v_fmamk_f32 v95, v95, 0x3e38aa3b, v224
	v_fmamk_f32 v96, v96, 0x3e38aa3b, v224
	v_fmamk_f32 v97, v97, 0x3e38aa3b, v224
	v_exp_f32_e32 v138, v82
	v_exp_f32_e32 v153, v83
	v_exp_f32_e32 v139, v84
	v_exp_f32_e32 v152, v85
	v_exp_f32_e32 v140, v86
	v_exp_f32_e32 v151, v87
	v_exp_f32_e32 v141, v88
	v_exp_f32_e32 v150, v89
	v_exp_f32_e32 v142, v90
	v_exp_f32_e32 v149, v91
	v_exp_f32_e32 v143, v92
	v_exp_f32_e32 v148, v93
	v_exp_f32_e32 v144, v94
	v_exp_f32_e32 v147, v95
	v_exp_f32_e32 v145, v96
	v_exp_f32_e32 v146, v97
	v_fmamk_f32 v233, v66, 0x3e38aa3b, v224
	v_fmamk_f32 v234, v67, 0x3e38aa3b, v224
	v_fmamk_f32 v235, v68, 0x3e38aa3b, v224
	v_fmamk_f32 v236, v69, 0x3e38aa3b, v224
	v_fmamk_f32 v237, v70, 0x3e38aa3b, v224
	v_fmamk_f32 v226, v71, 0x3e38aa3b, v224
	v_fmamk_f32 v227, v72, 0x3e38aa3b, v224
	v_fmamk_f32 v228, v73, 0x3e38aa3b, v224
	v_fmamk_f32 v229, v74, 0x3e38aa3b, v224
	v_fmamk_f32 v230, v75, 0x3e38aa3b, v224
	v_fmamk_f32 v231, v76, 0x3e38aa3b, v224
	v_fmamk_f32 v232, v77, 0x3e38aa3b, v224
	v_fmamk_f32 v225, v78, 0x3e38aa3b, v224
	v_fmamk_f32 v238, v79, 0x3e38aa3b, v224
	v_fmamk_f32 v239, v80, 0x3e38aa3b, v224
	v_fmac_f32_e32 v224, 0x3e38aa3b, v81
	s_waitcnt lgkmcnt(0)
	s_barrier
; #define SBAR() __builtin_amdgcn_sched_barrier(0)
; #define SLOAD(i, k0) do { sr_[i].vs0 = *reinterpret_cast<const bf16x8*>(&Vh[(long)((k0) + sr) * LDP + sc]); sr_[i].vs1 = *reinterpret_cast<const bf16x8*>(&Vh[(long)((k0) + 32 + sr) * LDP + sc]); \
;     sr_[i].ks0 = *reinterpret_cast<const bf16x8*>(&Kh[(long)((k0) + ksr) * LDP + ksc]); if (DK == 128) sr_[i].ks1 = *reinterpret_cast<const bf16x8*>(&Kh[(long)((k0) + 32 + ksr) * LDP + ksc]); } while (0)
; #define HOOK(P0, P1, j) do { if (NA) na_hook(P0, P1, krow0 + (j), q_row, q_col, win_r, win_c, rpb, inv_scale, hi); } while (0)
; __device__ __forceinline__ void finishSM(f32x16& p0, f32x16& p1, float alpha, float& l_reg, bf16x8& pa0, bf16x8& pa1, bf16x8& pa2, bf16x8& pa3) {
; #pragma unroll
;   for (int r = 0; r < 16; ++r) p1[r] = __builtin_amdgcn_exp2f(p1[r]);
;   float ps = 0;
; #pragma unroll
;   for (int r = 0; r < 16; ++r) ps += p0[r];
; #pragma unroll
;   for (int r = 0; r < 16; ++r) ps += p1[r];
;   { auto rr = __builtin_amdgcn_permlane32_swap(__float_as_uint(ps), __float_as_uint(ps), false, false);
;     ps = __uint_as_float(rr[0]) + __uint_as_float(rr[1]); }
;   l_reg = l_reg * alpha + ps;
;     ...
;   PK4(p0, 0, pa0); PK4(p0, 8, pa1); PK4(p1, 0, pa2); PK4(p1, 8, pa3);
;     ...
; }
; template <int DK, bool QL>
; __device__ __forceinline__ void qkt(f32x16& p0, f32x16& p1, const bf16* Ks, const bf16x8* qr, const char* ql, int r32, int hi) {
;   p0 = f32x16{}; p1 = f32x16{};
; #pragma unroll
;   for (int d0 = 0; d0 < DK / 16; ++d0) { int cb = (d0 * 16 + hi * 8) * 2;
;     const bf16x8 qv = QL ? *reinterpret_cast<const bf16x8*>(ql + d0 * 1024) : qr[d0];
;     bf16x8 b0 = *reinterpret_cast<const bf16x8*>((const char*)Ks + kswz<DK>(r32, cb));
;     bf16x8 b1 = *reinterpret_cast<const bf16x8*>((const char*)Ks + kswz<DK>(32 + r32, cb));
;     p0 = __builtin_amdgcn_mfma_f32_32x32x16_bf16(b0, qv, p0, 0, 0, 0);
;     p1 = __builtin_amdgcn_mfma_f32_32x32x16_bf16(b1, qv, p1, 0, 0, 0); }
; }
; template <int DK, bool NA, bool QL, int SD> ...
;     ...
;     SBAR(); qkt<DK, QL>(pA0, pA1, K_lds, qr, ql, r32, hi); HOOK(pA0, pA1, j + 1);
;     finishSM(pB0, pB1, alB, l_reg, pa0, pa1, pa2, pa3); SBAR();
;     if (SD == 1 || j + 3 < NT) SLOAD(SE, (j + 1 + SD) * KVBLK); SBAR();
;     pv_d0(o, vb0 + (int)SHM_V, pa0, pa1, pa2, pa3); partialSM(pA0, pA1, m_reg, mnA, alA, C, thrRaw);
	ds_write_b128 v214, v[114:117]
	ds_write_b128 v215, v[118:121]
	ds_read_b128 v[66:69], v212 offset:32768
	ds_read_b128 v[70:73], v212 offset:36864
	v_exp_f32_e32 v164, v233
	v_exp_f32_e32 v233, v224
	v_add_f32_e32 v224, 0, v138
	v_add_f32_e32 v224, v153, v224
	s_waitcnt lgkmcnt(1)
	v_mfma_f32_32x32x16_bf16 v[82:97], v[66:69], v[110:113], 0
	v_add_f32_e32 v224, v139, v224
	v_add_f32_e32 v224, v152, v224
	v_add_f32_e32 v224, v140, v224
	ds_read_b128 v[240:243], v216 offset:32768
	ds_read_b128 v[244:247], v216 offset:36864
	v_add_f32_e32 v224, v151, v224
	v_add_f32_e32 v224, v141, v224
	v_add_f32_e32 v224, v150, v224
	s_waitcnt lgkmcnt(2)
	v_mfma_f32_32x32x16_bf16 v[66:81], v[70:73], v[110:113], 0
	v_add_f32_e32 v224, v142, v224
	v_add_f32_e32 v224, v149, v224
	v_add_f32_e32 v224, v143, v224
	v_add_f32_e32 v224, v148, v224
	v_add_f32_e32 v224, v144, v224
	v_exp_f32_e32 v165, v234
	v_add_f32_e32 v224, v147, v224
	s_waitcnt lgkmcnt(1)
	v_mfma_f32_32x32x16_bf16 v[82:97], v[240:243], v[106:109], v[82:97]
	v_exp_f32_e32 v166, v235
	v_add_f32_e32 v224, v145, v224
	v_exp_f32_e32 v167, v236
	v_add_f32_e32 v224, v146, v224
	v_exp_f32_e32 v172, v237
	v_add_f32_e32 v224, v164, v224
	v_exp_f32_e32 v173, v226
	s_waitcnt lgkmcnt(0)
	v_mfma_f32_32x32x16_bf16 v[66:81], v[244:247], v[106:109], v[66:81]
	ds_read_b128 v[240:243], v217 offset:32768
	ds_read_b128 v[244:247], v217 offset:36864
	v_add_f32_e32 v224, v165, v224
	v_exp_f32_e32 v174, v227
	v_add_f32_e32 v224, v166, v224
	v_exp_f32_e32 v175, v228
	v_add_f32_e32 v224, v167, v224
	v_exp_f32_e32 v226, v229
	s_waitcnt lgkmcnt(1)
	v_mfma_f32_32x32x16_bf16 v[82:97], v[240:243], v[98:101], v[82:97]
	v_add_f32_e32 v224, v172, v224
	v_exp_f32_e32 v227, v230
	v_add_f32_e32 v224, v173, v224
	v_exp_f32_e32 v228, v231
	v_add_f32_e32 v224, v174, v224
	v_exp_f32_e32 v229, v232
	v_add_f32_e32 v224, v175, v224
	s_waitcnt lgkmcnt(0)
	v_mfma_f32_32x32x16_bf16 v[66:81], v[244:247], v[98:101], v[66:81]
	ds_read_b128 v[240:243], v218 offset:32768
	ds_read_b128 v[244:247], v218 offset:36864
	v_exp_f32_e32 v230, v225
	v_add_f32_e32 v224, v226, v224
	v_exp_f32_e32 v231, v238
	v_add_f32_e32 v224, v227, v224
	v_exp_f32_e32 v232, v239
	v_add_f32_e32 v224, v228, v224
	s_waitcnt lgkmcnt(1)
	v_mfma_f32_32x32x16_bf16 v[82:97], v[240:243], v[102:105], v[82:97]
	v_add_f32_e32 v224, v229, v224
	v_add_f32_e32 v224, v230, v224
	v_add_f32_e32 v224, v231, v224
	v_add_f32_e32 v224, v232, v224
	v_add_f32_e32 v224, v233, v224
	v_mov_b32_e32 v225, v224
	v_cvt_pk_bf16_f32 v138, v138, v153
	s_waitcnt lgkmcnt(0)
	v_mfma_f32_32x32x16_bf16 v[66:81], v[244:247], v[102:105], v[66:81]
	v_cvt_pk_bf16_f32 v139, v139, v152
	v_cvt_pk_bf16_f32 v140, v140, v151
	v_cvt_pk_bf16_f32 v141, v141, v150
	v_cvt_pk_bf16_f32 v142, v142, v149
	v_cvt_pk_bf16_f32 v143, v143, v148
	v_cvt_pk_bf16_f32 v144, v144, v147
	v_cvt_pk_bf16_f32 v145, v145, v146
	v_cvt_pk_bf16_f32 v146, v164, v165
	v_cvt_pk_bf16_f32 v147, v166, v167
	v_cvt_pk_bf16_f32 v148, v172, v173
	v_cvt_pk_bf16_f32 v149, v174, v175
	v_cvt_pk_bf16_f32 v150, v226, v227
	v_cvt_pk_bf16_f32 v151, v228, v229
	v_cvt_pk_bf16_f32 v152, v230, v231
	v_cvt_pk_bf16_f32 v153, v232, v233
	v_permlane32_swap_b32_e32 v224, v225
	v_permlane32_swap_b32_e32 v138, v140
	v_permlane32_swap_b32_e32 v139, v141
	v_permlane32_swap_b32_e32 v142, v144
	v_permlane32_swap_b32_e32 v143, v145
	v_permlane32_swap_b32_e32 v146, v148
	v_permlane32_swap_b32_e32 v147, v149
	v_permlane32_swap_b32_e32 v150, v152
	v_permlane32_swap_b32_e32 v151, v153
	s_cmp_gt_u32 s9, 60
	s_cselect_b64 s[4:5], -1, 0
	s_and_b64 vcc, exec, s[4:5]
	s_cbranch_vccnz .Lod_d1
	global_load_dwordx4 v[114:117], v[178:179], off offset:2048
	global_load_dwordx4 v[118:121], v[180:181], off offset:2048
	global_load_dwordx4 v[122:125], v[204:205], off offset:1024
	s_mov_b32 s6, 0xa0000
	s_mov_b32 s7, 0
	s_nop 0
	v_lshl_add_u64 v[178:179], v[178:179], 0, s[6:7]
	v_lshl_add_u64 v[180:181], v[180:181], 0, s[6:7]
	v_lshl_add_u64 v[204:205], v[204:205], 0, s[6:7]
.LBB0_688:
	ds_read_b64_tr_b16 v[226:227], v210 offset:0
	ds_read_b64_tr_b16 v[228:229], v210 offset:0x800
	ds_read_b64_tr_b16 v[230:231], v210 offset:0x1000
	ds_read_b64_tr_b16 v[232:233], v210 offset:0x1800
	ds_read_b64_tr_b16 v[234:235], v210 offset:0x2000
	ds_read_b64_tr_b16 v[236:237], v210 offset:0x2800
	ds_read_b64_tr_b16 v[238:239], v210 offset:0x3000
	ds_read_b64_tr_b16 v[240:241], v210 offset:0x3800
	s_waitcnt lgkmcnt(6)
	s_nop 0
	v_mfma_f32_32x32x16_bf16 v[18:33], v[138:141], v[226:229], v[18:33]
	ds_read_b64_tr_b16 v[226:227], v210 offset:0x200
	ds_read_b64_tr_b16 v[228:229], v210 offset:0xa00
	s_waitcnt lgkmcnt(6)
	v_mfma_f32_32x32x16_bf16 v[18:33], v[142:145], v[230:233], v[18:33]
	ds_read_b64_tr_b16 v[230:231], v210 offset:0x1200
	ds_read_b64_tr_b16 v[232:233], v210 offset:0x1a00
	s_waitcnt lgkmcnt(6)
	v_mfma_f32_32x32x16_bf16 v[18:33], v[146:149], v[234:237], v[18:33]
	ds_read_b64_tr_b16 v[234:235], v210 offset:0x2200
	ds_read_b64_tr_b16 v[236:237], v210 offset:0x2a00
	s_waitcnt lgkmcnt(6)
	v_mfma_f32_32x32x16_bf16 v[18:33], v[150:153], v[238:241], v[18:33]
	ds_read_b64_tr_b16 v[238:239], v210 offset:0x3200
	ds_read_b64_tr_b16 v[240:241], v210 offset:0x3a00
	s_waitcnt lgkmcnt(6)
	v_mfma_f32_32x32x16_bf16 v[2:17], v[138:141], v[226:229], v[2:17]
	ds_read_b64_tr_b16 v[226:227], v210 offset:0x400
	ds_read_b64_tr_b16 v[228:229], v210 offset:0xc00
	s_waitcnt lgkmcnt(6)
	v_mfma_f32_32x32x16_bf16 v[2:17], v[142:145], v[230:233], v[2:17]
	ds_read_b64_tr_b16 v[230:231], v210 offset:0x1400
	ds_read_b64_tr_b16 v[232:233], v210 offset:0x1c00
	s_waitcnt lgkmcnt(6)
; #define SBAR() __builtin_amdgcn_sched_barrier(0)
; #define SLOAD(i, k0) do { sr_[i].vs0 = *reinterpret_cast<const bf16x8*>(&Vh[(long)((k0) + sr) * LDP + sc]); sr_[i].vs1 = *reinterpret_cast<const bf16x8*>(&Vh[(long)((k0) + 32 + sr) * LDP + sc]); \
;     sr_[i].ks0 = *reinterpret_cast<const bf16x8*>(&Kh[(long)((k0) + ksr) * LDP + ksc]); if (DK == 128) sr_[i].ks1 = *reinterpret_cast<const bf16x8*>(&Kh[(long)((k0) + 32 + ksr) * LDP + ksc]); } while (0)
; #define SWAIT() do { if (SD == 1) asm volatile("s_waitcnt vmcnt(0)" ::: "memory"); else if (DK == 128) asm volatile("s_waitcnt vmcnt(4)" ::: "memory"); else asm volatile("s_waitcnt vmcnt(3)" ::: "memory"); } while (0)
; #define HOOK(P0, P1, j) do { if (NA) na_hook(P0, P1, krow0 + (j), q_row, q_col, win_r, win_c, rpb, inv_scale, hi); } while (0)
; __device__ __forceinline__ void partialSM(f32x16& p0, f32x16& p1, float& m_reg, float& mn, float& alpha, float C, float thrRaw) {
;   float pmax = p0[0];
; #pragma unroll
;   for (int r = 1; r < 16; ++r) pmax = fmaxf(pmax, p0[r]);
; #pragma unroll
;   for (int r = 0; r < 16; ++r) pmax = fmaxf(pmax, p1[r]);
;   { auto rr = __builtin_amdgcn_permlane32_swap(__float_as_uint(pmax), __float_as_uint(pmax), false, false);
;     pmax = fmaxf(__uint_as_float(rr[0]), __uint_as_float(rr[1])); }
;   if (__builtin_expect(__all(pmax - m_reg <= thrRaw), 1)) { mn = m_reg; alpha = 1.f; }
;   else { mn = fmaxf(m_reg, pmax); alpha = __builtin_amdgcn_exp2f((m_reg - mn) * C); m_reg = mn; }
;   float mnC = -mn * C;
; #pragma unroll
;   for (int r = 0; r < 16; ++r) p0[r] = fmaf(p0[r], C, mnC);
; #pragma unroll
;   for (int r = 0; r < 16; ++r) p1[r] = fmaf(p1[r], C, mnC);
; #pragma unroll
;   for (int r = 0; r < 16; ++r) p0[r] = __builtin_amdgcn_exp2f(p0[r]);
; }
; template <int DK, bool NA, bool QL, int SD> ...
;     ...
;     __syncthreads(); SWAIT(); SWRITE(0, SE);
;     RESC(alB); __syncthreads();
;     SBAR(); qkt<DK, QL>(pA0, pA1, K_lds, qr, ql, r32, hi); HOOK(pA0, pA1, j + 1);
;     finishSM(pB0, pB1, alB, l_reg, pa0, pa1, pa2, pa3); SBAR();
;     if (SD == 1 || j + 3 < NT) SLOAD(SE, (j + 1 + SD) * KVBLK); SBAR();
;     pv_d0(o, vb0 + (int)SHM_V, pa0, pa1, pa2, pa3); partialSM(pA0, pA1, m_reg, mnA, alA, C, thrRaw);
;     __syncthreads(); SWAIT(); SWRITE(1, SO);
;     RESC(alA); __syncthreads();
;   }
	v_mfma_f32_32x32x16_bf16 v[2:17], v[146:149], v[234:237], v[2:17]
	ds_read_b64_tr_b16 v[234:235], v210 offset:0x2400
	ds_read_b64_tr_b16 v[236:237], v210 offset:0x2c00
	s_waitcnt lgkmcnt(6)
	v_mfma_f32_32x32x16_bf16 v[2:17], v[150:153], v[238:241], v[2:17]
	ds_read_b64_tr_b16 v[238:239], v210 offset:0x3400
	ds_read_b64_tr_b16 v[240:241], v210 offset:0x3c00
	s_waitcnt lgkmcnt(6)
	v_mfma_f32_32x32x16_bf16 v[50:65], v[138:141], v[226:229], v[50:65]
	ds_read_b64_tr_b16 v[226:227], v210 offset:0x600
	ds_read_b64_tr_b16 v[228:229], v210 offset:0xe00
	s_waitcnt lgkmcnt(6)
	v_mfma_f32_32x32x16_bf16 v[50:65], v[142:145], v[230:233], v[50:65]
	ds_read_b64_tr_b16 v[230:231], v210 offset:0x1600
	ds_read_b64_tr_b16 v[232:233], v210 offset:0x1e00
	s_waitcnt lgkmcnt(6)
	v_mfma_f32_32x32x16_bf16 v[50:65], v[146:149], v[234:237], v[50:65]
	ds_read_b64_tr_b16 v[234:235], v210 offset:0x2600
	ds_read_b64_tr_b16 v[236:237], v210 offset:0x2e00
	s_waitcnt lgkmcnt(6)
	v_mfma_f32_32x32x16_bf16 v[50:65], v[150:153], v[238:241], v[50:65]
	ds_read_b64_tr_b16 v[238:239], v210 offset:0x3600
	ds_read_b64_tr_b16 v[240:241], v210 offset:0x3e00
	s_waitcnt lgkmcnt(6)
	v_mfma_f32_32x32x16_bf16 v[34:49], v[138:141], v[226:229], v[34:49]
	v_max_f32_e32 v138, v83, v82
	v_max3_f32 v138, v138, v84, v85
	v_max3_f32 v138, v138, v86, v87
	v_max3_f32 v138, v138, v88, v89
	v_max3_f32 v138, v138, v90, v91
	v_max3_f32 v138, v138, v92, v93
	v_max3_f32 v138, v138, v94, v95
	s_waitcnt lgkmcnt(4)
	v_mfma_f32_32x32x16_bf16 v[34:49], v[142:145], v[230:233], v[34:49]
	v_max3_f32 v138, v138, v96, v97
	v_max3_f32 v138, v138, v66, v67
	v_max3_f32 v138, v138, v68, v69
	v_max3_f32 v138, v138, v70, v71
	v_max3_f32 v138, v138, v72, v73
	v_max3_f32 v138, v138, v74, v75
	v_max3_f32 v138, v138, v76, v77
	v_max3_f32 v138, v138, v78, v79
	s_waitcnt lgkmcnt(2)
	v_mfma_f32_32x32x16_bf16 v[34:49], v[146:149], v[234:237], v[34:49]
	v_max3_f32 v138, v138, v80, v81
	v_mov_b32_e32 v139, v138
	s_nop 1
	v_permlane32_swap_b32_e32 v138, v139
	v_max_f32_e32 v138, v139, v138
	v_sub_f32_e32 v139, v138, v223
	s_mov_b32 s2, 0x42800000
	v_cmp_ge_f32_e32 vcc, s2, v139
	v_max_f32_e32 v138, v223, v138
	s_waitcnt lgkmcnt(0)
	v_mfma_f32_32x32x16_bf16 v[34:49], v[150:153], v[238:241], v[34:49]
	v_sub_f32_e32 v139, v223, v138
	v_mul_f32_e32 v139, 0x3e38aa3b, v139
	v_exp_f32_e32 v139, v139
	s_cmp_eq_u64 vcc, exec
	s_cselect_b64 s[2:3], -1, 0
	s_waitcnt vmcnt(3)
	v_cndmask_b32_e64 v143, v139, 1.0, s[2:3]
	v_cmp_gt_f32_e32 vcc, 1.0, v143
	ds_write_b128 v213, v[134:137] offset:49152
	s_cbranch_vccz .LBB0_692
	s_and_saveexec_b64 s[6:7], s[0:1]
	ds_write_b32 v208, v143 offset:128
	s_or_b64 exec, exec, s[6:7]
	s_waitcnt lgkmcnt(0)
	v_add_u32_e32 v139, v207, v0
	ds_read_b128 v[126:129], v139 offset:128
	ds_read_b128 v[130:133], v139 offset:160
	ds_read_b128 v[134:137], v139 offset:224
	ds_read_b128 v[144:147], v139 offset:192
	s_waitcnt lgkmcnt(3)
	v_pk_mul_f32 v[50:51], v[126:127], v[50:51]
	v_pk_mul_f32 v[52:53], v[128:129], v[52:53]
	s_waitcnt lgkmcnt(2)
	v_pk_mul_f32 v[54:55], v[130:131], v[54:55]
	s_waitcnt lgkmcnt(1)
	v_pk_mul_f32 v[30:31], v[30:31], v[134:135]
	s_waitcnt lgkmcnt(0)
	v_pk_mul_f32 v[26:27], v[26:27], v[144:145]
	v_pk_mul_f32 v[22:23], v[22:23], v[130:131]
	v_pk_mul_f32 v[32:33], v[32:33], v[136:137]
	v_pk_mul_f32 v[28:29], v[28:29], v[146:147]
	v_pk_mul_f32 v[24:25], v[24:25], v[132:133]
	v_pk_mul_f32 v[20:21], v[20:21], v[128:129]
	v_pk_mul_f32 v[18:19], v[18:19], v[126:127]
	v_pk_mul_f32 v[14:15], v[134:135], v[14:15]
	v_pk_mul_f32 v[10:11], v[144:145], v[10:11]
	v_pk_mul_f32 v[6:7], v[130:131], v[6:7]
	v_pk_mul_f32 v[16:17], v[136:137], v[16:17]
	v_pk_mul_f32 v[12:13], v[146:147], v[12:13]
	v_pk_mul_f32 v[8:9], v[132:133], v[8:9]
	v_pk_mul_f32 v[4:5], v[128:129], v[4:5]
	v_pk_mul_f32 v[2:3], v[126:127], v[2:3]
	v_pk_mul_f32 v[56:57], v[132:133], v[56:57]
	v_pk_mul_f32 v[34:35], v[126:127], v[34:35]
	v_pk_mul_f32 v[36:37], v[36:37], v[128:129]
	v_pk_mul_f32 v[38:39], v[38:39], v[130:131]
	v_pk_mul_f32 v[40:41], v[40:41], v[132:133]
	v_pk_mul_f32 v[58:59], v[58:59], v[144:145]
	v_pk_mul_f32 v[42:43], v[42:43], v[144:145]
	v_pk_mul_f32 v[60:61], v[60:61], v[146:147]
	v_pk_mul_f32 v[44:45], v[44:45], v[146:147]
	v_pk_mul_f32 v[62:63], v[62:63], v[134:135]
	v_pk_mul_f32 v[46:47], v[46:47], v[134:135]
	v_pk_mul_f32 v[64:65], v[64:65], v[136:137]
	v_pk_mul_f32 v[48:49], v[48:49], v[136:137]
.LBB0_692:
	v_cndmask_b32_e64 v142, v138, v223, s[2:3]
	v_mul_f32_e32 v132, 0xbe38aa3b, v142
	v_mov_b32_e32 v133, v132
	v_fmamk_f32 v82, v82, 0x3e38aa3b, v132
	v_fmamk_f32 v83, v83, 0x3e38aa3b, v132
	v_fmamk_f32 v84, v84, 0x3e38aa3b, v132
	v_fmamk_f32 v85, v85, 0x3e38aa3b, v132
	v_fmamk_f32 v86, v86, 0x3e38aa3b, v132
	v_fmamk_f32 v87, v87, 0x3e38aa3b, v132
	v_fmamk_f32 v88, v88, 0x3e38aa3b, v132
	v_fmamk_f32 v89, v89, 0x3e38aa3b, v132
	v_fmamk_f32 v90, v90, 0x3e38aa3b, v132
	v_fmamk_f32 v91, v91, 0x3e38aa3b, v132
	v_fmamk_f32 v92, v92, 0x3e38aa3b, v132
	v_fmamk_f32 v93, v93, 0x3e38aa3b, v132
	v_fmamk_f32 v94, v94, 0x3e38aa3b, v132
	v_fmamk_f32 v95, v95, 0x3e38aa3b, v132
	v_fmamk_f32 v96, v96, 0x3e38aa3b, v132
	v_fmac_f32_e32 v133, 0x3e38aa3b, v97
	s_mov_b32 s2, 0x3e38aa3b
	v_exp_f32_e32 v177, v82
	v_exp_f32_e32 v226, v83
	v_exp_f32_e32 v161, v84
	v_exp_f32_e32 v223, v85
	v_exp_f32_e32 v153, v86
	v_exp_f32_e32 v176, v87
	v_exp_f32_e32 v152, v88
	v_exp_f32_e32 v160, v89
	v_exp_f32_e32 v149, v90
	v_exp_f32_e32 v151, v91
	v_exp_f32_e32 v147, v92
	v_exp_f32_e32 v150, v93
	v_exp_f32_e32 v145, v94
	v_exp_f32_e32 v148, v95
	v_exp_f32_e32 v144, v96
	v_exp_f32_e32 v146, v133
	v_pk_fma_f32 v[138:139], v[66:67], s[2:3], v[132:133] op_sel_hi:[1,0,0]
	v_add_f32_e32 v66, v220, v221
	v_pk_fma_f32 v[136:137], v[68:69], s[2:3], v[132:133] op_sel_hi:[1,0,0]
	v_pk_fma_f32 v[130:131], v[70:71], s[2:3], v[132:133] op_sel_hi:[1,0,0]
	v_pk_fma_f32 v[128:129], v[72:73], s[2:3], v[132:133] op_sel_hi:[1,0,0]
	v_pk_fma_f32 v[126:127], v[74:75], s[2:3], v[132:133] op_sel_hi:[1,0,0]
	v_pk_fma_f32 v[140:141], v[76:77], s[2:3], v[132:133] op_sel_hi:[1,0,0]
	v_pk_fma_f32 v[134:135], v[78:79], s[2:3], v[132:133] op_sel_hi:[1,0,0]
	v_pk_fma_f32 v[132:133], v[80:81], s[2:3], v[132:133] op_sel_hi:[1,0,0]
	v_fmac_f32_e32 v66, v219, v209
	v_add_f32_e32 v209, v224, v225
	v_fmac_f32_e32 v209, v66, v222
	s_add_i32 s9, s9, 2
	s_and_b64 vcc, exec, s[4:5]
	s_waitcnt lgkmcnt(0)
	s_barrier
	s_cbranch_vccnz .LBB0_694
	v_mov_b32_e32 v219, v143
	ds_write_b128 v214, v[182:185] offset:16384
	ds_write_b128 v215, v[194:197] offset:16384
	s_branch .LBB0_682

; #define SBAR() __builtin_amdgcn_sched_barrier(0)
; #define RESC(a) do { if (__any((a) < 1.f)) { if (hi == 0) al_l[r32] = (a); asm volatile("s_waitcnt lgkmcnt(0)" ::: "memory"); \
;     _Pragma("unroll") for (int d = 0; d < 4; ++d) _Pragma("unroll") for (int r = 0; r < 16; ++r) o[d][r] *= al_l[crow(r, hi)]; } } while (0)
; #define HOOK(P0, P1, j) do { if (NA) na_hook(P0, P1, krow0 + (j), q_row, q_col, win_r, win_c, rpb, inv_scale, hi); } while (0)
; __device__ __forceinline__ void finishSM(f32x16& p0, f32x16& p1, float alpha, float& l_reg, bf16x8& pa0, bf16x8& pa1, bf16x8& pa2, bf16x8& pa3) {
; #pragma unroll
;   for (int r = 0; r < 16; ++r) p1[r] = __builtin_amdgcn_exp2f(p1[r]);
;   float ps = 0;
; #pragma unroll
;   for (int r = 0; r < 16; ++r) ps += p0[r];
; #pragma unroll
;   for (int r = 0; r < 16; ++r) ps += p1[r];
;   { auto rr = __builtin_amdgcn_permlane32_swap(__float_as_uint(ps), __float_as_uint(ps), false, false);
;     ps = __uint_as_float(rr[0]) + __uint_as_float(rr[1]); }
;   l_reg = l_reg * alpha + ps;
;     ...
;   PK4(p0, 0, pa0); PK4(p0, 8, pa1); PK4(p1, 0, pa2); PK4(p1, 8, pa3);
;     ...
; }
; template <int DK, bool NA, bool QL, int SD> ...
;     ...
;   SBAR(); qkt<DK, QL>(pB0, pB1, (bf16*)((char*)K_lds + SHM_K), qr, ql, r32, hi); HOOK(pB0, pB1, NT - 1);
;   finishSM(pA0, pA1, alA, l_reg, pa0, pa1, pa2, pa3); SBAR();
;   pv_d0(o, vb0, pa0, pa1, pa2, pa3); partialSM(pB0, pB1, m_reg, mnB, alB, C, thrRaw);
;   __syncthreads(); RESC(alB);
;   finishSM(pB0, pB1, alB, l_reg, pa0, pa1, pa2, pa3); SBAR();
;   pv_d0(o, vb0 + (int)SHM_V, pa0, pa1, pa2, pa3);
.LBB0_698:
	v_cndmask_b32_e64 v101, v101, v142, s[2:3]
	v_mul_f32_e32 v101, 0xbe38aa3b, v101
	v_fmamk_f32 v82, v82, 0x3e38aa3b, v101
	v_fmamk_f32 v83, v83, 0x3e38aa3b, v101
	v_fmamk_f32 v102, v84, 0x3e38aa3b, v101
	v_exp_f32_e32 v84, v82
	v_fmamk_f32 v103, v86, 0x3e38aa3b, v101
	v_exp_f32_e32 v86, v83
	v_fmamk_f32 v85, v85, 0x3e38aa3b, v101
	v_exp_f32_e32 v82, v102
	v_fmamk_f32 v66, v66, 0x3e38aa3b, v101
	v_exp_f32_e32 v85, v85
	v_fmamk_f32 v104, v87, 0x3e38aa3b, v101
	v_fmamk_f32 v113, v96, 0x3e38aa3b, v101
	v_fmamk_f32 v96, v77, 0x3e38aa3b, v101
	v_exp_f32_e32 v77, v103
	v_exp_f32_e32 v102, v66
	v_add_f32_e32 v66, 0, v84
	v_fmamk_f32 v105, v88, 0x3e38aa3b, v101
	v_exp_f32_e32 v83, v104
	v_add_f32_e32 v66, v86, v66
	v_fmamk_f32 v106, v89, 0x3e38aa3b, v101
	v_fmamk_f32 v112, v95, 0x3e38aa3b, v101
	v_fmamk_f32 v95, v76, 0x3e38aa3b, v101
	v_exp_f32_e32 v76, v105
	v_add_f32_e32 v66, v82, v66
	v_fmamk_f32 v107, v90, 0x3e38aa3b, v101
	v_fmamk_f32 v114, v97, 0x3e38aa3b, v101
	v_fmamk_f32 v97, v78, 0x3e38aa3b, v101
	v_exp_f32_e32 v78, v106
	v_add_f32_e32 v66, v85, v66
	v_fmamk_f32 v108, v91, 0x3e38aa3b, v101
	v_fmamk_f32 v109, v92, 0x3e38aa3b, v101
	v_fmamk_f32 v92, v73, 0x3e38aa3b, v101
	v_exp_f32_e32 v73, v107
	v_add_f32_e32 v66, v77, v66
	v_fmamk_f32 v111, v94, 0x3e38aa3b, v101
	v_fmamk_f32 v94, v75, 0x3e38aa3b, v101
	v_exp_f32_e32 v75, v108
	v_add_f32_e32 v66, v83, v66
	v_fmamk_f32 v110, v93, 0x3e38aa3b, v101
	v_fmamk_f32 v90, v71, 0x3e38aa3b, v101
	v_exp_f32_e32 v71, v109
	v_add_f32_e32 v66, v76, v66
	v_fmamk_f32 v93, v74, 0x3e38aa3b, v101
	v_exp_f32_e32 v74, v110
	v_add_f32_e32 v66, v78, v66
	v_fmamk_f32 v88, v69, 0x3e38aa3b, v101
	v_exp_f32_e32 v69, v111
	v_add_f32_e32 v66, v73, v66
	v_fmamk_f32 v91, v72, 0x3e38aa3b, v101
	v_exp_f32_e32 v72, v112
	v_add_f32_e32 v66, v75, v66
	v_fmamk_f32 v87, v68, 0x3e38aa3b, v101
	v_exp_f32_e32 v68, v113
	v_add_f32_e32 v66, v71, v66
	v_fmamk_f32 v89, v70, 0x3e38aa3b, v101
	v_exp_f32_e32 v70, v114
	v_add_f32_e32 v66, v74, v66
	v_fmamk_f32 v67, v67, 0x3e38aa3b, v101
	v_add_f32_e32 v66, v69, v66
	v_exp_f32_e32 v103, v67
	v_add_f32_e32 v66, v72, v66
	v_exp_f32_e32 v87, v87
	v_add_f32_e32 v66, v68, v66
	v_exp_f32_e32 v88, v88
	v_add_f32_e32 v66, v70, v66
	v_exp_f32_e32 v89, v89
	v_add_f32_e32 v66, v102, v66
	v_exp_f32_e32 v90, v90
	v_add_f32_e32 v66, v103, v66
	v_exp_f32_e32 v91, v91
	v_add_f32_e32 v66, v87, v66
	v_exp_f32_e32 v92, v92
	v_add_f32_e32 v66, v88, v66
	v_exp_f32_e32 v93, v93
	v_add_f32_e32 v66, v89, v66
	v_exp_f32_e32 v94, v94
	v_add_f32_e32 v66, v90, v66
	v_exp_f32_e32 v95, v95
	v_add_f32_e32 v66, v91, v66
	v_exp_f32_e32 v96, v96
	v_add_f32_e32 v66, v92, v66
	v_fmamk_f32 v79, v79, 0x3e38aa3b, v101
	v_exp_f32_e32 v97, v97
	v_add_f32_e32 v66, v93, v66
	v_fmamk_f32 v80, v80, 0x3e38aa3b, v101
	v_exp_f32_e32 v104, v79
	v_add_f32_e32 v66, v94, v66
	v_fmac_f32_e32 v101, 0x3e38aa3b, v81
	v_exp_f32_e32 v105, v80
	v_add_f32_e32 v66, v95, v66
	v_exp_f32_e32 v101, v101
	v_add_f32_e32 v66, v96, v66
	v_add_f32_e32 v66, v97, v66
	v_add_f32_e32 v66, v104, v66
	v_add_f32_e32 v66, v105, v66
	v_add_f32_e32 v66, v101, v66
	v_mov_b32_e32 v67, v66
	s_nop 1
	v_permlane32_swap_b32_e32 v66, v67
	v_cvt_pk_bf16_f32 v80, v84, v86
	v_cvt_pk_bf16_f32 v81, v82, v85
	v_cvt_pk_bf16_f32 v82, v77, v83
	v_cvt_pk_bf16_f32 v83, v76, v78
	v_cvt_pk_bf16_f32 v76, v73, v75
	v_cvt_pk_bf16_f32 v77, v71, v74
	v_cvt_pk_bf16_f32 v78, v69, v72
	v_cvt_pk_bf16_f32 v79, v68, v70
	v_cvt_pk_bf16_f32 v68, v102, v103
	v_cvt_pk_bf16_f32 v69, v87, v88
	v_cvt_pk_bf16_f32 v70, v89, v90
	v_cvt_pk_bf16_f32 v71, v91, v92
	v_cvt_pk_bf16_f32 v72, v93, v94
	v_cvt_pk_bf16_f32 v73, v95, v96
	v_cvt_pk_bf16_f32 v74, v97, v104
	v_cvt_pk_bf16_f32 v75, v105, v101
	s_nop 0
	v_permlane32_swap_b32_e32 v80, v82
	v_permlane32_swap_b32_e32 v81, v83
	v_permlane32_swap_b32_e32 v76, v78
	v_permlane32_swap_b32_e32 v77, v79
	v_permlane32_swap_b32_e32 v68, v70
	v_permlane32_swap_b32_e32 v69, v71
	v_permlane32_swap_b32_e32 v72, v74
	v_permlane32_swap_b32_e32 v73, v75
	ds_read_b64_tr_b16 v[84:85], v210 offset:0
	ds_read_b64_tr_b16 v[86:87], v210 offset:0x800
	ds_read_b64_tr_b16 v[88:89], v210 offset:0x1000
	ds_read_b64_tr_b16 v[90:91], v210 offset:0x1800
	ds_read_b64_tr_b16 v[92:93], v210 offset:0x2000
	ds_read_b64_tr_b16 v[94:95], v210 offset:0x2800
	ds_read_b64_tr_b16 v[102:103], v210 offset:0x3000
	ds_read_b64_tr_b16 v[104:105], v210 offset:0x3800
	s_waitcnt lgkmcnt(0)
	s_nop 0
	v_mfma_f32_32x32x16_bf16 v[18:33], v[80:83], v[84:87], v[18:33]
	ds_read_b64_tr_b16 v[84:85], v210 offset:0x200
	ds_read_b64_tr_b16 v[86:87], v210 offset:0xa00
	v_mfma_f32_32x32x16_bf16 v[18:33], v[76:79], v[88:91], v[18:33]
	ds_read_b64_tr_b16 v[88:89], v210 offset:0x1200
	ds_read_b64_tr_b16 v[90:91], v210 offset:0x1a00
	v_mfma_f32_32x32x16_bf16 v[18:33], v[68:71], v[92:95], v[18:33]
	ds_read_b64_tr_b16 v[92:93], v210 offset:0x2200
	ds_read_b64_tr_b16 v[94:95], v210 offset:0x2a00
	v_mfma_f32_32x32x16_bf16 v[18:33], v[72:75], v[102:105], v[18:33]
	ds_read_b64_tr_b16 v[102:103], v210 offset:0x3200
	ds_read_b64_tr_b16 v[104:105], v210 offset:0x3a00
	s_waitcnt lgkmcnt(0)
	v_mfma_f32_32x32x16_bf16 v[2:17], v[80:83], v[84:87], v[2:17]
	ds_read_b64_tr_b16 v[84:85], v210 offset:0x400
	ds_read_b64_tr_b16 v[86:87], v210 offset:0xc00
	v_mfma_f32_32x32x16_bf16 v[2:17], v[76:79], v[88:91], v[2:17]
	ds_read_b64_tr_b16 v[88:89], v210 offset:0x1400
	ds_read_b64_tr_b16 v[90:91], v210 offset:0x1c00
	v_mfma_f32_32x32x16_bf16 v[2:17], v[68:71], v[92:95], v[2:17]
	ds_read_b64_tr_b16 v[92:93], v210 offset:0x2400
	ds_read_b64_tr_b16 v[94:95], v210 offset:0x2c00
	v_mfma_f32_32x32x16_bf16 v[2:17], v[72:75], v[102:105], v[2:17]
	ds_read_b64_tr_b16 v[102:103], v210 offset:0x3400
	ds_read_b64_tr_b16 v[104:105], v210 offset:0x3c00
	s_waitcnt lgkmcnt(0)
; __device__ __forceinline__ int opaque_tid() { int t = threadIdx.x; asm volatile("" : "+v"(t)); return t; }
; #define SBAR() __builtin_amdgcn_sched_barrier(0)
; __device__ __forceinline__ int crow(int r, int hi) { return (r & 3) + 8 * (r >> 2) + 4 * hi; }
; __device__ __forceinline__ unsigned cvtpk(float lo, float hi) { unsigned r; asm volatile("v_cvt_pk_bf16_f32 %0, %1, %2" : "=v"(r) : "v"(lo), "v"(hi)); return r; }
; #define RESC(a) do { if (__any((a) < 1.f)) { if (hi == 0) al_l[r32] = (a); asm volatile("s_waitcnt lgkmcnt(0)" ::: "memory"); \
;     _Pragma("unroll") for (int d = 0; d < 4; ++d) _Pragma("unroll") for (int r = 0; r < 16; ++r) o[d][r] *= al_l[crow(r, hi)]; } } while (0)
; template <int DK, bool NA, bool QL, int SD> ...
;     ...
;   pv_d0(o, vb0, pa0, pa1, pa2, pa3); partialSM(pB0, pB1, m_reg, mnB, alB, C, thrRaw);
;   __syncthreads(); RESC(alB);
;   finishSM(pB0, pB1, alB, l_reg, pa0, pa1, pa2, pa3); SBAR();
;   pv_d0(o, vb0 + (int)SHM_V, pa0, pa1, pa2, pa3);
;   if (hi == 0) li_l[r32] = l_reg; asm volatile("s_waitcnt vmcnt(0) lgkmcnt(0)" ::: "memory");
; #pragma unroll
;   for (int r = 0; r < 16; ++r) { const float rl = __builtin_amdgcn_rcpf(li_l[crow(r, hi)]);
; #pragma unroll
;     for (int d = 0; d < 4; ++d) o[d][r] *= rl; }
; __global__ void __launch_bounds__(NTHR) mega_fwd(Params p) {
;     ...
;                     { const int t2 = opaque_tid(); v4u* STv = (v4u*)((char*)lds + 69632) + t2;
; #pragma unroll
;                       for (int k = 0; k < 8; ++k) { const int d = k >> 1, r0 = 8 * (k & 1); v4u w;
;                           w.x = att::cvtpk(o[d][r0], o[d][r0 + 1]); w.y = att::cvtpk(o[d][r0 + 2], o[d][r0 + 3]); w.z = att::cvtpk(o[d][r0 + 4], o[d][r0 + 5]); w.w = att::cvtpk(o[d][r0 + 6], o[d][r0 + 7]);
;                           STv[k * 512] = w; } }
	v_mfma_f32_32x32x16_bf16 v[50:65], v[80:83], v[84:87], v[50:65]
	ds_read_b64_tr_b16 v[84:85], v210 offset:0x600
	ds_read_b64_tr_b16 v[86:87], v210 offset:0xe00
	v_mfma_f32_32x32x16_bf16 v[50:65], v[76:79], v[88:91], v[50:65]
	ds_read_b64_tr_b16 v[88:89], v210 offset:0x1600
	ds_read_b64_tr_b16 v[90:91], v210 offset:0x1e00
	v_mfma_f32_32x32x16_bf16 v[50:65], v[68:71], v[92:95], v[50:65]
	ds_read_b64_tr_b16 v[92:93], v210 offset:0x2600
	ds_read_b64_tr_b16 v[94:95], v210 offset:0x2e00
	v_mfma_f32_32x32x16_bf16 v[50:65], v[72:75], v[102:105], v[50:65]
	ds_read_b64_tr_b16 v[102:103], v210 offset:0x3600
	ds_read_b64_tr_b16 v[104:105], v210 offset:0x3e00
	s_waitcnt lgkmcnt(0)
	v_mfma_f32_32x32x16_bf16 v[34:49], v[80:83], v[84:87], v[34:49]
	v_mfma_f32_32x32x16_bf16 v[34:49], v[76:79], v[88:91], v[34:49]
	v_mfma_f32_32x32x16_bf16 v[34:49], v[68:71], v[92:95], v[34:49]
	v_mfma_f32_32x32x16_bf16 v[34:49], v[72:75], v[102:105], v[34:49]
	s_and_saveexec_b64 s[2:3], s[0:1]
	v_add_f32_e32 v68, v98, v99
	v_fmac_f32_e32 v68, v209, v143
	v_add_f32_e32 v66, v66, v67
	v_fmac_f32_e32 v66, v68, v100
	ds_write_b32 v208, v66
	s_or_b64 exec, exec, s[2:3]
	s_waitcnt vmcnt(0) lgkmcnt(0)
	v_add_u32_e32 v0, v207, v0
	ds_read_b128 v[66:69], v0
	ds_read_b128 v[70:73], v0 offset:32
	v_readlane_b32 s0, v253, 17
	v_readlane_b32 s1, v253, 18
	s_movk_i32 s3, 0x2800
	s_waitcnt lgkmcnt(1)
	v_rcp_f32_e32 v66, v66
	v_rcp_f32_e32 v67, v67
	s_cmp_lg_u32 0, -1
	s_cselect_b32 s2, 0, 0
	v_mul_f32_e32 v75, v66, v2
	v_rcp_f32_e32 v2, v68
	v_mul_f32_e32 v68, v67, v3
	v_rcp_f32_e32 v3, v69
	v_mul_f32_e32 v74, v66, v18
	v_mul_f32_e32 v50, v66, v50
	v_mul_f32_e32 v34, v66, v34
	v_mul_f32_e32 v66, v67, v19
	v_mul_f32_e32 v51, v67, v51
	v_mul_f32_e32 v35, v67, v35
	v_mul_f32_e32 v67, v2, v20
	v_mul_f32_e32 v69, v2, v4
	v_mul_f32_e32 v52, v2, v52
	v_mul_f32_e32 v36, v2, v36
	v_mul_f32_e32 v76, v3, v21
	s_waitcnt lgkmcnt(0)
	v_rcp_f32_e32 v2, v70
	v_mul_f32_e32 v70, v3, v5
	v_mul_f32_e32 v53, v3, v53
	v_mul_f32_e32 v37, v3, v37
	v_rcp_f32_e32 v3, v71
	v_mul_f32_e32 v22, v2, v22
	v_mul_f32_e32 v6, v2, v6
	v_mul_f32_e32 v54, v2, v54
	v_mul_f32_e32 v38, v2, v38
	v_mul_f32_e32 v23, v3, v23
	v_mul_f32_e32 v7, v3, v7
	v_mul_f32_e32 v55, v3, v55
	v_mul_f32_e32 v39, v3, v39
	ds_read_b128 v[2:5], v0 offset:64
	v_rcp_f32_e32 v18, v72
	v_rcp_f32_e32 v71, v73
	s_mov_b32 s12, s13
	s_mov_b32 s14, s13
	v_mul_f32_e32 v24, v18, v24
	v_mul_f32_e32 v8, v18, v8
	v_mul_f32_e32 v56, v18, v56
	v_mul_f32_e32 v40, v18, v40
	ds_read_b128 v[18:21], v0 offset:96
	s_waitcnt lgkmcnt(1)
	v_rcp_f32_e32 v0, v2
	v_rcp_f32_e32 v2, v3
	v_rcp_f32_e32 v3, v4
	v_mul_f32_e32 v25, v71, v25
	v_mul_f32_e32 v26, v0, v26
	v_mul_f32_e32 v10, v0, v10
	v_mul_f32_e32 v58, v0, v58
	v_mul_f32_e32 v0, v0, v42
	v_mul_f32_e32 v27, v2, v27
	v_mul_f32_e32 v11, v2, v11
	v_mul_f32_e32 v42, v2, v59
	v_mul_f32_e32 v43, v2, v43
	v_rcp_f32_e32 v2, v5
	v_mul_f32_e32 v28, v3, v28
	v_mul_f32_e32 v12, v3, v12
	v_mul_f32_e32 v59, v3, v60
	v_mul_f32_e32 v44, v3, v44
	v_mul_f32_e32 v29, v2, v29
	s_waitcnt lgkmcnt(0)
	v_rcp_f32_e32 v3, v18
	v_mul_f32_e32 v13, v2, v13
	v_mul_f32_e32 v18, v2, v61
	v_mul_f32_e32 v45, v2, v45
	v_rcp_f32_e32 v2, v19
	v_mul_f32_e32 v30, v3, v30
	v_mul_f32_e32 v14, v3, v14
	v_mul_f32_e32 v19, v3, v62
	v_mul_f32_e32 v46, v3, v46
	v_mul_f32_e32 v31, v2, v31
	v_rcp_f32_e32 v3, v20
	v_mul_f32_e32 v15, v2, v15
	v_mul_f32_e32 v20, v2, v63
	v_mul_f32_e32 v47, v2, v47
	v_rcp_f32_e32 v2, v21
	v_mul_f32_e32 v32, v3, v32
	v_mul_f32_e32 v16, v3, v16
	v_mul_f32_e32 v21, v3, v64
	v_mul_f32_e32 v33, v2, v33
	v_mul_f32_e32 v17, v2, v17
	v_mul_f32_e32 v60, v2, v65
	v_mul_f32_e32 v49, v2, v49
	v_mov_b32_e32 v2, v188
	v_mul_f32_e32 v48, v3, v48
	v_lshl_add_u32 v2, v2, 4, 0
	v_add_u32_e32 v61, 0x11000, v2
	v_cvt_pk_bf16_f32 v2, v74, v66
	v_cvt_pk_bf16_f32 v3, v67, v76
	v_cvt_pk_bf16_f32 v4, v22, v23
	v_cvt_pk_bf16_f32 v5, v24, v25
	ds_write_b128 v61, v[2:5]
	v_cvt_pk_bf16_f32 v2, v26, v27
	v_cvt_pk_bf16_f32 v3, v28, v29
	v_cvt_pk_bf16_f32 v4, v30, v31
	v_cvt_pk_bf16_f32 v5, v32, v33
	v_mul_f32_e32 v9, v71, v9
	ds_write_b128 v61, v[2:5] offset:8192
	v_cvt_pk_bf16_f32 v2, v75, v68
	v_cvt_pk_bf16_f32 v3, v69, v70
	v_cvt_pk_bf16_f32 v4, v6, v7
	v_cvt_pk_bf16_f32 v5, v8, v9
	ds_write_b128 v61, v[2:5] offset:16384
	v_cvt_pk_bf16_f32 v2, v10, v11
	v_cvt_pk_bf16_f32 v3, v12, v13
	v_cvt_pk_bf16_f32 v4, v14, v15
	v_cvt_pk_bf16_f32 v5, v16, v17
	v_mul_f32_e32 v57, v71, v57
	ds_write_b128 v61, v[2:5] offset:24576
	v_cvt_pk_bf16_f32 v2, v50, v51
	v_cvt_pk_bf16_f32 v3, v52, v53
	v_cvt_pk_bf16_f32 v4, v54, v55
	v_cvt_pk_bf16_f32 v5, v56, v57
	ds_write_b128 v61, v[2:5] offset:32768
	v_cvt_pk_bf16_f32 v2, v58, v42
	v_cvt_pk_bf16_f32 v3, v59, v18
	v_cvt_pk_bf16_f32 v4, v19, v20
	v_cvt_pk_bf16_f32 v5, v21, v60
	v_mul_f32_e32 v41, v71, v41
	ds_write_b128 v61, v[2:5] offset:40960
	v_cvt_pk_bf16_f32 v2, v34, v35
	v_cvt_pk_bf16_f32 v3, v36, v37
	v_cvt_pk_bf16_f32 v4, v38, v39
	v_cvt_pk_bf16_f32 v5, v40, v41
	v_mov_b32_e32 v74, v188
	ds_write_b128 v61, v[2:5] offset:49152
	v_cvt_pk_bf16_f32 v2, v0, v43
	v_cvt_pk_bf16_f32 v3, v44, v45
	v_cvt_pk_bf16_f32 v4, v46, v47
	v_cvt_pk_bf16_f32 v5, v48, v49
	ds_write_b128 v61, v[2:5] offset:57344
	v_mov_b64_e32 v[50:51], s[0:1]
	v_ashrrev_i32_e32 v75, 4, v74
	v_lshlrev_b32_e32 v16, 3, v74
	v_and_b32_e32 v0, 0x78, v16
	v_add_u32_e32 v17, 32, v75
	v_mad_i64_i32 v[2:3], s[0:1], v75, s3, v[50:51]
	v_lshlrev_b32_e32 v52, 1, v0
	v_mov_b32_e32 v53, v1
	v_mad_i64_i32 v[4:5], s[0:1], v17, s3, v[50:51]
	v_ashrrev_i32_e32 v72, 3, v74
	v_lshl_add_u64 v[2:3], v[2:3], 0, v[52:53]
	v_lshl_add_u64 v[6:7], v[4:5], 0, v[52:53]
	v_lshlrev_b32_e32 v22, 4, v74
; __device__ __forceinline__ int opaque_tid() { int t = threadIdx.x; asm volatile("" : "+v"(t)); return t; }
; __device__ __forceinline__ int v_st(int k, int c) { const int kk = (k & ~0xC) | ((k & 4) << 1) | ((k & 8) >> 1); return ((kk >> 3) * 4 + (c >> 5)) * 512 + ((kk & 7) * 32 + (c & 31)) * 2; }
; __device__ __forceinline__ int v_rd_base(int lane) { return ((lane & 3) << 3) | (((lane >> 2) & 3) << 6) | (((lane >> 4) & 1) << 5) | (((lane >> 5) & 1) << 8); }
; #define HOOK(P0, P1, j) do { if (NA) na_hook(P0, P1, krow0 + (j), q_row, q_col, win_r, win_c, rpb, inv_scale, hi); } while (0)
; template <int DK, bool NA, bool QL, int SD> ...
;   const int tid = opaque_tid(), wid = tid >> 6, lane = tid & 63, r32 = lane & 31, hi = lane >> 5;
;   bf16* V_lds = (bf16*)lds; bf16* K_lds = (bf16*)(lds + 2 * SHM_V);
;   float* ws = (float*)(lds + 2 * SHM_V + 2 * SHM_K) + wid * 64; float* li_l = ws; float* al_l = ws + 32;
;   const float* rpb = (const float*)(lds + RPB_OFF);
;   int win_r = q_row - 4; win_r = win_r < 0 ? 0 : (win_r > 56 ? 56 : win_r);
;   int win_c = q_col - 8; win_c = win_c < 0 ? 0 : (win_c > 48 ? 48 : win_c);
;   float m_reg = -1e30f, l_reg = 0; bf16x8 qr[QL ? 1 : DK / 16];
;   char* ql = lds + Q_OFF + (wid * (DK / 16) * 64 + lane) * 16;
; #pragma unroll
;   for (int d = 0; d < 4; ++d) o[d] = f32x16{};
;   const bf16* Qw = Qb + (long)(wid * 32 + r32) * LDP + hi * 8;
; #pragma unroll
;   for (int d0 = 0; d0 < DK / 16; ++d0) { const bf16x8 qv = *reinterpret_cast<const bf16x8*>(Qw + d0 * 16); if (QL) *reinterpret_cast<bf16x8*>(ql + d0 * 1024) = qv; else qr[d0] = qv; }
;   const int sr = tid >> 4, sc = (tid & 15) * 8, vst0 = v_st(sr, sc), vst1 = v_st(32 + sr, sc);
;   const int ksr = DK == 128 ? sr : (tid >> 3), ksc = DK == 128 ? sc : (tid & 7) * 8;
;   const int vb0 = (int)(uintptr_t)V_lds + v_rd_base(lane);
;   struct { bf16x8 vs0, vs1, ks0, ks1; } sr_[SD];
;     ...
;   f32x16 pA0, pA1, pB0, pB1; float mnA, mnB, alA, alB; bf16x8 pa0, pa1, pa2, pa3;
;   constexpr int SE = 0, SO = SD - 1;
;   SLOAD(SE, 0); asm volatile("s_waitcnt vmcnt(0)" ::: "memory"); SWRITE(0, SE); __syncthreads();
;   qkt<DK, QL>(pA0, pA1, K_lds, qr, ql, r32, hi); HOOK(pA0, pA1, 0); partialSM(pA0, pA1, m_reg, mnA, alA, C, thrRaw);
;   SLOAD(SO, KVBLK); if (SD == 2) { if (2 < NT) SLOAD(SE, 2 * KVBLK); }
;   SWAIT(); SWRITE(1, SO); __syncthreads();
	global_load_dwordx4 v[2:5], v[2:3], off offset:2048
	s_nop 0
	global_load_dwordx4 v[6:9], v[6:7], off offset:2048
	v_mad_i64_i32 v[10:11], s[0:1], v72, s3, v[50:51]
	v_and_b32_e32 v56, 0x70, v22
	v_mov_b32_e32 v57, v1
	v_ashrrev_i32_e32 v0, 1, v74
	s_movk_i32 s0, 0xffe0
	v_lshl_add_u64 v[10:11], v[10:11], 0, v[56:57]
	v_bfi_b32 v0, s0, v0, v74
	v_readlane_b32 s0, v253, 9
	global_load_dwordx4 v[10:13], v[10:11], off offset:1152
	v_readlane_b32 s1, v253, 10
	v_bfe_u32 v18, v16, 5, 2
	v_and_b32_e32 v19, 3, v75
	v_mov_b64_e32 v[14:15], s[0:1]
	v_mad_i64_i32 v[14:15], s[0:1], v0, s3, v[14:15]
	v_lshrrev_b32_e32 v0, 1, v74
	v_and_b32_e32 v0, 16, v0
	v_lshl_add_u64 v[14:15], v[14:15], 0, v[0:1]
	global_load_dwordx4 v[110:113], v[14:15], off offset:128
	global_load_dwordx4 v[106:109], v[14:15], off offset:160
	global_load_dwordx4 v[102:105], v[14:15], off offset:192
	global_load_dwordx4 v[98:101], v[14:15], off offset:224
	v_add_u32_e32 v84, 64, v75
	v_add_u32_e32 v88, 0x60, v75
	v_add_u32_e32 v92, 64, v72
	v_mad_i64_i32 v[84:85], s[0:1], v84, s3, v[50:51]
	v_mad_i64_i32 v[88:89], s[0:1], v88, s3, v[50:51]
	v_mad_i64_i32 v[92:93], s[0:1], v92, s3, v[50:51]
	v_lshl_add_u64 v[84:85], v[84:85], 0, v[52:53]
	v_lshl_add_u64 v[88:89], v[88:89], 0, v[52:53]
	v_lshl_add_u64 v[92:93], v[92:93], 0, v[56:57]
	global_load_dwordx4 v[84:87], v[84:85], off offset:2048
	global_load_dwordx4 v[88:91], v[88:89], off offset:2048
	global_load_dwordx4 v[92:95], v[92:93], off offset:1152
	v_and_b32_e32 v14, 0xfffff0, v75
	v_lshlrev_b32_e32 v15, 1, v75
	v_and_or_b32 v14, v15, 8, v14
	v_lshrrev_b32_e32 v15, 1, v75
	v_lshrrev_b32_e32 v14, 1, v14
	v_or_b32_e32 v14, v14, v18
	v_and_or_b32 v15, v15, 4, v19
	v_lshlrev_b32_e32 v14, 9, v14
	v_lshlrev_b32_e32 v15, 6, v15
	v_and_b32_e32 v19, 48, v22
	v_and_b32_e32 v20, 0xfffff0, v17
	v_lshlrev_b32_e32 v17, 1, v17
	v_or3_b32 v14, v14, v15, v19
	v_and_or_b32 v17, v17, 8, v20
	v_lshrrev_b32_e32 v17, 1, v17
	v_add_u32_e32 v212, 0, v14
	v_and_b32_e32 v76, 31, v74
	v_or_b32_e32 v17, v17, v18
	s_waitcnt vmcnt(0)
	v_lshlrev_b32_e32 v17, 9, v17
	v_lshlrev_b32_e32 v26, 7, v76
	v_and_b32_e32 v27, 0x70, v16
	v_or3_b32 v15, v17, v15, v19
	v_add_u32_e32 v213, 0, v15
	v_and_b32_e32 v77, 63, v74
	v_lshlrev_b32_e32 v28, 3, v77
	v_and_b32_e32 v22, 0xc0, v22
	v_and_or_b32 v29, v28, 24, v22
	v_lshlrev_b32_e32 v22, 1, v74
	v_and_b32_e32 v30, 32, v22
	v_mad_i64_i32 v[58:59], s[0:1], v75, s3, 0
	v_mad_i64_i32 v[54:55], s[0:1], v72, s3, 0
	s_mov_b32 s15, s13
	s_mov_b32 s1, s13
	s_mov_b32 s16, s13
	s_mov_b32 s17, s13
	s_mov_b32 s18, s13
	s_mov_b32 s19, s13
	s_mov_b32 s20, s13
	s_mov_b32 s21, s13
	s_mov_b32 s22, s13
	s_mov_b32 s23, s13
	s_mov_b32 s24, s13
	s_mov_b32 s25, s13
	s_mov_b32 s26, s13
	s_mov_b32 s27, s13
	v_add_u32_e32 v68, 64, v72
	v_mov_b32_e32 v209, 0
	s_waitcnt vmcnt(6)
	ds_write_b128 v212, v[2:5]
	v_lshlrev_b32_e32 v2, 7, v72
	v_and_b32_e32 v3, 0x70, v74
	v_bitop3_b32 v2, v56, v2, v3 bitop3:0xde
	v_add_u32_e32 v214, 0, v2
	v_bitop3_b32 v2, v0, v26, v27 bitop3:0xde
	v_add_u32_e32 v215, 0, v2
	s_waitcnt vmcnt(5)
	ds_write_b128 v213, v[6:9]
	v_add_u32_e32 v72, 0x80, v72
	s_waitcnt vmcnt(4)
	ds_write_b128 v214, v[10:13] offset:32768
	s_waitcnt lgkmcnt(0)
	s_barrier
	ds_read_b128 v[2:5], v215 offset:32768
	ds_read_b128 v[6:9], v215 offset:36864
	s_waitcnt vmcnt(3) lgkmcnt(1)
	v_mfma_f32_32x32x16_bf16 v[34:49], v[2:5], v[110:113], 0
	v_and_b32_e32 v2, 0x3fffffc0, v74
	v_lshl_add_u32 v207, v2, 2, s8
	v_or_b32_e32 v2, 32, v0
	v_bitop3_b32 v2, v2, v26, v27 bitop3:0xde
	v_add_u32_e32 v216, 0, v2
	ds_read_b128 v[18:21], v216 offset:32768
	ds_read_b128 v[22:25], v216 offset:36864
	s_waitcnt vmcnt(2) lgkmcnt(1)
	v_mfma_f32_32x32x16_bf16 v[34:49], v[18:21], v[106:109], v[34:49]
	v_and_b32_e32 v18, 0x100, v28
	v_or3_b32 v78, v29, v30, v18
	v_or_b32_e32 v18, 64, v0
	v_bitop3_b32 v18, v18, v26, v27 bitop3:0xde
	v_add_u32_e32 v217, 0, v18
	ds_read_b128 v[18:21], v217 offset:32768
	s_mov_b32 s8, 1
	v_mfma_f32_32x32x16_bf16 v[2:17], v[6:9], v[110:113], 0
	v_add_u32_e32 v211, s2, v78
	v_writelane_b32 v254, s0, 62
	v_lshl_add_u32 v208, v76, 2, v207
	s_nop 0
	v_writelane_b32 v255, s2, 0
	v_writelane_b32 v255, s3, 1
	v_writelane_b32 v255, s4, 2
	s_waitcnt lgkmcnt(1)
	v_mfma_f32_32x32x16_bf16 v[2:17], v[22:25], v[106:109], v[2:17]
	ds_read_b128 v[22:25], v217 offset:36864
	v_writelane_b32 v255, s5, 3
	v_writelane_b32 v255, s6, 4
	v_writelane_b32 v255, s7, 5
	v_writelane_b32 v255, s8, 6
	v_writelane_b32 v255, s9, 7
	v_writelane_b32 v255, s10, 8
	s_waitcnt vmcnt(1) lgkmcnt(1)
	v_mfma_f32_32x32x16_bf16 v[34:49], v[18:21], v[102:105], v[34:49]
	v_or_b32_e32 v18, 0x60, v0
	v_bitop3_b32 v18, v18, v26, v27 bitop3:0xde
	v_add_u32_e32 v218, 0, v18
	ds_read_b128 v[18:21], v218 offset:32768
	ds_read_b128 v[60:63], v218 offset:36864
	v_writelane_b32 v255, s11, 9
	v_writelane_b32 v255, s12, 10
	s_waitcnt lgkmcnt(2)
	v_mfma_f32_32x32x16_bf16 v[2:17], v[22:25], v[102:105], v[2:17]
	v_writelane_b32 v255, s13, 11
	v_writelane_b32 v255, s14, 12
	v_writelane_b32 v254, s1, 63
	v_writelane_b32 v255, s15, 13
	v_mad_i64_i32 v[68:69], s[0:1], v68, s3, v[50:51]
	v_lshl_add_u64 v[68:69], v[68:69], 0, v[56:57]
	s_waitcnt vmcnt(0) lgkmcnt(1)
	v_mfma_f32_32x32x16_bf16 v[34:49], v[18:21], v[98:101], v[34:49]
	v_mov_b64_e32 v[32:33], s[26:27]
	v_mov_b64_e32 v[18:19], s[12:13]
	v_mov_b64_e32 v[30:31], s[24:25]
	v_mov_b64_e32 v[28:29], s[22:23]
	v_mov_b64_e32 v[26:27], s[20:21]
	v_mov_b64_e32 v[24:25], s[18:19]
	v_mov_b64_e32 v[22:23], s[16:17]
	s_waitcnt lgkmcnt(0)
; #define SLOAD(i, k0) do { sr_[i].vs0 = *reinterpret_cast<const bf16x8*>(&Vh[(long)((k0) + sr) * LDP + sc]); sr_[i].vs1 = *reinterpret_cast<const bf16x8*>(&Vh[(long)((k0) + 32 + sr) * LDP + sc]); \
;     sr_[i].ks0 = *reinterpret_cast<const bf16x8*>(&Kh[(long)((k0) + ksr) * LDP + ksc]); if (DK == 128) sr_[i].ks1 = *reinterpret_cast<const bf16x8*>(&Kh[(long)((k0) + 32 + ksr) * LDP + ksc]); } while (0)
; #define SWAIT() do { if (SD == 1) asm volatile("s_waitcnt vmcnt(0)" ::: "memory"); else if (DK == 128) asm volatile("s_waitcnt vmcnt(4)" ::: "memory"); else asm volatile("s_waitcnt vmcnt(3)" ::: "memory"); } while (0)
; #define HOOK(P0, P1, j) do { if (NA) na_hook(P0, P1, krow0 + (j), q_row, q_col, win_r, win_c, rpb, inv_scale, hi); } while (0)
; __device__ __forceinline__ void partialSM(f32x16& p0, f32x16& p1, float& m_reg, float& mn, float& alpha, float C, float thrRaw) {
;   float pmax = p0[0];
; #pragma unroll
;   for (int r = 1; r < 16; ++r) pmax = fmaxf(pmax, p0[r]);
; #pragma unroll
;   for (int r = 0; r < 16; ++r) pmax = fmaxf(pmax, p1[r]);
;   { auto rr = __builtin_amdgcn_permlane32_swap(__float_as_uint(pmax), __float_as_uint(pmax), false, false);
;     pmax = fmaxf(__uint_as_float(rr[0]), __uint_as_float(rr[1])); }
;   if (__builtin_expect(__all(pmax - m_reg <= thrRaw), 1)) { mn = m_reg; alpha = 1.f; }
;   else { mn = fmaxf(m_reg, pmax); alpha = __builtin_amdgcn_exp2f((m_reg - mn) * C); m_reg = mn; }
;   float mnC = -mn * C;
; #pragma unroll
;   for (int r = 0; r < 16; ++r) p0[r] = fmaf(p0[r], C, mnC);
; #pragma unroll
;   for (int r = 0; r < 16; ++r) p1[r] = fmaf(p1[r], C, mnC);
; #pragma unroll
;   for (int r = 0; r < 16; ++r) p0[r] = __builtin_amdgcn_exp2f(p0[r]);
; }
; template <int DK, bool NA, bool QL, int SD> ...
;     ...
;   SLOAD(SE, 0); asm volatile("s_waitcnt vmcnt(0)" ::: "memory"); SWRITE(0, SE); __syncthreads();
;   qkt<DK, QL>(pA0, pA1, K_lds, qr, ql, r32, hi); HOOK(pA0, pA1, 0); partialSM(pA0, pA1, m_reg, mnA, alA, C, thrRaw);
;   SLOAD(SO, KVBLK); if (SD == 2) { if (2 < NT) SLOAD(SE, 2 * KVBLK); }
;   SWAIT(); SWRITE(1, SO); __syncthreads();
	v_mfma_f32_32x32x16_bf16 v[2:17], v[60:63], v[98:101], v[2:17]
	s_nop 2
	v_max_f32_e32 v60, v35, v35
	v_max_f32_e32 v61, v34, v34
	v_max_f32_e32 v60, v61, v60
	v_max3_f32 v60, v60, v36, v37
	v_max3_f32 v60, v60, v38, v39
	v_max3_f32 v60, v60, v40, v41
	v_max3_f32 v60, v60, v42, v43
	v_max3_f32 v60, v60, v44, v45
	v_max3_f32 v60, v60, v46, v47
	v_max3_f32 v60, v60, v48, v49
	v_max3_f32 v60, v60, v2, v3
	v_max3_f32 v60, v60, v4, v5
	v_max3_f32 v60, v60, v6, v7
	v_max3_f32 v60, v60, v8, v9
	v_max3_f32 v73, v60, v10, v11
	v_max3_f32 v73, v73, v12, v13
	v_add_u32_e32 v60, 64, v75
	v_add_u32_e32 v62, 0x60, v75
	v_max3_f32 v73, v73, v14, v15
	v_mad_i64_i32 v[60:61], s[0:1], v60, s3, v[50:51]
	v_mad_i64_i32 v[62:63], s[0:1], v62, s3, v[50:51]
	v_max3_f32 v79, v73, v16, v17
	v_mad_i64_i32 v[72:73], s[0:1], v72, s3, v[50:51]
	v_lshl_add_u64 v[60:61], v[60:61], 0, v[52:53]
	v_lshl_add_u64 v[64:65], v[62:63], 0, v[52:53]
	v_lshl_add_u64 v[56:57], v[72:73], 0, v[56:57]
	s_nop 0
	v_add_u32_e32 v72, 0x80, v75
	v_mov_b64_e32 v[20:21], s[14:15]
	global_load_dwordx4 v[122:125], v[56:57], off offset:1152
	v_add_u32_e32 v56, 0xa0, v75
	v_mad_i64_i32 v[56:57], s[0:1], v56, s3, v[50:51]
	v_lshl_add_u64 v[56:57], v[56:57], 0, v[52:53]
	v_mad_i64_i32 v[50:51], s[0:1], v72, s3, v[50:51]
	v_lshl_add_u64 v[50:51], v[50:51], 0, v[52:53]
	global_load_dwordx4 v[118:121], v[56:57], off offset:2048
	global_load_dwordx4 v[114:117], v[50:51], off offset:2048
	v_mov_b32_e32 v50, v79
	s_nop 1
	v_permlane32_swap_b32_e32 v79, v50
	v_max_f32_e32 v50, v50, v50
	v_max_f32_e32 v51, v79, v79
	v_max_f32_e32 v50, v51, v50
	v_add_f32_e32 v51, 0x7149f2ca, v50
	s_mov_b32 s0, 0x42800000
	v_max_f32_e32 v50, 0xf149f2ca, v50
	v_cmp_ge_f32_e32 vcc, s0, v51
	v_sub_f32_e32 v51, 0xf149f2ca, v50
	v_mul_f32_e32 v51, 0x3e38aa3b, v51
	v_exp_f32_e32 v51, v51
	s_cmp_eq_u64 vcc, exec
	s_cselect_b64 vcc, -1, 0
	v_cndmask_b32_e32 v142, v50, v199, vcc
	v_mul_f32_e32 v50, 0xbe38aa3b, v142
	v_cndmask_b32_e64 v219, v51, 1.0, vcc
	v_mov_b32_e32 v51, v50
	v_fmac_f32_e32 v51, 0x3e38aa3b, v49
	s_mov_b32 s0, 0x3e38aa3b
	v_fmamk_f32 v34, v34, 0x3e38aa3b, v50
	v_fmamk_f32 v35, v35, 0x3e38aa3b, v50
	v_fmamk_f32 v36, v36, 0x3e38aa3b, v50
	v_fmamk_f32 v37, v37, 0x3e38aa3b, v50
	v_fmamk_f32 v38, v38, 0x3e38aa3b, v50
	v_fmamk_f32 v39, v39, 0x3e38aa3b, v50
	v_fmamk_f32 v40, v40, 0x3e38aa3b, v50
	v_fmamk_f32 v41, v41, 0x3e38aa3b, v50
	v_fmamk_f32 v42, v42, 0x3e38aa3b, v50
	v_fmamk_f32 v43, v43, 0x3e38aa3b, v50
	v_fmamk_f32 v44, v44, 0x3e38aa3b, v50
	v_fmamk_f32 v45, v45, 0x3e38aa3b, v50
	v_fmamk_f32 v46, v46, 0x3e38aa3b, v50
	v_fmamk_f32 v47, v47, 0x3e38aa3b, v50
	v_fmamk_f32 v48, v48, 0x3e38aa3b, v50
	v_pk_fma_f32 v[138:139], v[2:3], s[0:1], v[50:51] op_sel_hi:[1,0,0]
	s_addk_i32 s2, 0x4000
	v_and_b32_e32 v2, 15, v74
	v_exp_f32_e32 v177, v34
	v_exp_f32_e32 v226, v35
	v_exp_f32_e32 v161, v36
	v_exp_f32_e32 v223, v37
	v_exp_f32_e32 v153, v38
	v_exp_f32_e32 v176, v39
	v_exp_f32_e32 v152, v40
	v_exp_f32_e32 v160, v41
	v_exp_f32_e32 v149, v42
	v_exp_f32_e32 v151, v43
	v_exp_f32_e32 v147, v44
	v_exp_f32_e32 v150, v45
	v_exp_f32_e32 v145, v46
	v_exp_f32_e32 v148, v47
	v_exp_f32_e32 v144, v48
	v_exp_f32_e32 v146, v51
	v_add_u32_e32 v210, s2, v78
	v_lshl_or_b32 v58, v2, 4, v58
	v_readlane_b32 s2, v254, 34
	v_and_b32_e32 v2, 7, v74
	s_waitcnt vmcnt(3)
	v_readlane_b32 s3, v254, 35
	v_lshl_or_b32 v54, v2, 4, v54
	v_pk_fma_f32 v[132:133], v[16:17], s[0:1], v[50:51] op_sel_hi:[1,0,0]
	v_pk_fma_f32 v[134:135], v[14:15], s[0:1], v[50:51] op_sel_hi:[1,0,0]
	v_pk_fma_f32 v[140:141], v[12:13], s[0:1], v[50:51] op_sel_hi:[1,0,0]
	v_pk_fma_f32 v[126:127], v[10:11], s[0:1], v[50:51] op_sel_hi:[1,0,0]
	v_pk_fma_f32 v[128:129], v[8:9], s[0:1], v[50:51] op_sel_hi:[1,0,0]
	v_pk_fma_f32 v[130:131], v[6:7], s[0:1], v[50:51] op_sel_hi:[1,0,0]
	v_pk_fma_f32 v[136:137], v[4:5], s[0:1], v[50:51] op_sel_hi:[1,0,0]
	s_waitcnt vmcnt(5)
	ds_write_b128 v212, v[84:87] offset:16384
	s_waitcnt vmcnt(4)
	ds_write_b128 v213, v[88:91] offset:16384
	s_waitcnt vmcnt(3)
	ds_write_b128 v214, v[92:95] offset:49152
	v_lshl_add_u64 v[156:157], s[2:3], 0, v[58:59]
	v_lshl_add_u64 v[158:159], s[2:3], 0, v[54:55]
	v_mov_b64_e32 v[48:49], v[32:33]
	v_mov_b64_e32 v[64:65], v[32:33]
	v_mov_b64_e32 v[2:3], v[18:19]
	v_cmp_gt_u32_e64 s[0:1], 32, v77
	v_mov_b64_e32 v[46:47], v[30:31]
	v_mov_b64_e32 v[44:45], v[28:29]
	v_mov_b64_e32 v[42:43], v[26:27]
	v_mov_b64_e32 v[40:41], v[24:25]
	v_mov_b64_e32 v[38:39], v[22:23]
	v_mov_b64_e32 v[36:37], v[20:21]
	v_mov_b64_e32 v[34:35], v[18:19]
	v_mov_b64_e32 v[62:63], v[30:31]
	v_mov_b64_e32 v[60:61], v[28:29]
	v_mov_b64_e32 v[58:59], v[26:27]
	v_mov_b64_e32 v[56:57], v[24:25]
	v_mov_b64_e32 v[54:55], v[22:23]
	v_mov_b64_e32 v[52:53], v[20:21]
	v_mov_b64_e32 v[50:51], v[18:19]
	v_mov_b64_e32 v[4:5], v[20:21]
	v_mov_b64_e32 v[6:7], v[22:23]
	v_mov_b64_e32 v[8:9], v[24:25]
	v_mov_b64_e32 v[10:11], v[26:27]
	v_mov_b64_e32 v[12:13], v[28:29]
	v_mov_b64_e32 v[14:15], v[30:31]
	v_mov_b64_e32 v[16:17], v[32:33]
	v_readlane_b32 s6, v254, 32
	v_readlane_b32 s7, v254, 33
	s_nop 3
	v_lshl_add_u64 v[178:179], v[156:157], 0, s[6:7]
	v_lshl_add_u64 v[204:205], v[158:159], 0, s[6:7]
	s_mov_b32 s6, 0xe130000
	s_mov_b32 s7, 0
	s_nop 0
	v_lshl_add_u64 v[180:181], v[178:179], 0, s[6:7]
	s_mov_b32 s6, 0xe0e0000
	s_nop 0
	v_lshl_add_u64 v[178:179], v[178:179], 0, s[6:7]
	v_lshl_add_u64 v[204:205], v[204:205], 0, s[6:7]
	s_waitcnt lgkmcnt(0)
	s_barrier
; #define SBAR() __builtin_amdgcn_sched_barrier(0)
; #define SLOAD(i, k0) do { sr_[i].vs0 = *reinterpret_cast<const bf16x8*>(&Vh[(long)((k0) + sr) * LDP + sc]); sr_[i].vs1 = *reinterpret_cast<const bf16x8*>(&Vh[(long)((k0) + 32 + sr) * LDP + sc]); \
;     sr_[i].ks0 = *reinterpret_cast<const bf16x8*>(&Kh[(long)((k0) + ksr) * LDP + ksc]); if (DK == 128) sr_[i].ks1 = *reinterpret_cast<const bf16x8*>(&Kh[(long)((k0) + 32 + ksr) * LDP + ksc]); } while (0)
; #define HOOK(P0, P1, j) do { if (NA) na_hook(P0, P1, krow0 + (j), q_row, q_col, win_r, win_c, rpb, inv_scale, hi); } while (0)
; __device__ __forceinline__ void finishSM(f32x16& p0, f32x16& p1, float alpha, float& l_reg, bf16x8& pa0, bf16x8& pa1, bf16x8& pa2, bf16x8& pa3) {
; #pragma unroll
;   for (int r = 0; r < 16; ++r) p1[r] = __builtin_amdgcn_exp2f(p1[r]);
;   float ps = 0;
; #pragma unroll
;   for (int r = 0; r < 16; ++r) ps += p0[r];
; #pragma unroll
;   for (int r = 0; r < 16; ++r) ps += p1[r];
;   { auto rr = __builtin_amdgcn_permlane32_swap(__float_as_uint(ps), __float_as_uint(ps), false, false);
;     ps = __uint_as_float(rr[0]) + __uint_as_float(rr[1]); }
;   l_reg = l_reg * alpha + ps;
;     ...
;   PK4(p0, 0, pa0); PK4(p0, 8, pa1); PK4(p1, 0, pa2); PK4(p1, 8, pa3);
;     ...
; }
; template <int DK, bool QL>
; __device__ __forceinline__ void qkt(f32x16& p0, f32x16& p1, const bf16* Ks, const bf16x8* qr, const char* ql, int r32, int hi) {
;   p0 = f32x16{}; p1 = f32x16{};
; #pragma unroll
;   for (int d0 = 0; d0 < DK / 16; ++d0) { int cb = (d0 * 16 + hi * 8) * 2;
;     const bf16x8 qv = QL ? *reinterpret_cast<const bf16x8*>(ql + d0 * 1024) : qr[d0];
;     bf16x8 b0 = *reinterpret_cast<const bf16x8*>((const char*)Ks + kswz<DK>(r32, cb));
;     bf16x8 b1 = *reinterpret_cast<const bf16x8*>((const char*)Ks + kswz<DK>(32 + r32, cb));
;     p0 = __builtin_amdgcn_mfma_f32_32x32x16_bf16(b0, qv, p0, 0, 0, 0);
;     p1 = __builtin_amdgcn_mfma_f32_32x32x16_bf16(b1, qv, p1, 0, 0, 0); }
; }
; template <int DK, bool NA, bool QL, int SD> ...
;     ...
;     SBAR(); qkt<DK, QL>(pB0, pB1, (bf16*)((char*)K_lds + SHM_K), qr, ql, r32, hi); HOOK(pB0, pB1, j);
;     finishSM(pA0, pA1, alA, l_reg, pa0, pa1, pa2, pa3); SBAR();
;     SLOAD(SO, (j + SD) * KVBLK); SBAR();
;     pv_d0(o, vb0, pa0, pa1, pa2, pa3); partialSM(pB0, pB1, m_reg, mnB, alB, C, thrRaw);
.LBB0_701:
	ds_read_b128 v[66:69], v215 offset:49152
	ds_read_b128 v[70:73], v215 offset:53248
	v_exp_f32_e32 v143, v138
	v_add_f32_e32 v138, 0, v177
	v_add_f32_e32 v138, v226, v138
	s_waitcnt lgkmcnt(1)
	v_mfma_f32_32x32x16_bf16 v[82:97], v[66:69], v[110:113], 0
	v_add_f32_e32 v138, v161, v138
	v_add_f32_e32 v138, v223, v138
	v_add_f32_e32 v138, v153, v138
	ds_read_b128 v[228:231], v216 offset:49152
	ds_read_b128 v[232:235], v216 offset:53248
	v_add_f32_e32 v138, v176, v138
	v_add_f32_e32 v138, v152, v138
	v_add_f32_e32 v138, v160, v138
	s_waitcnt lgkmcnt(2)
	v_mfma_f32_32x32x16_bf16 v[66:81], v[70:73], v[110:113], 0
	v_add_f32_e32 v138, v149, v138
	v_add_f32_e32 v138, v151, v138
	v_add_f32_e32 v138, v147, v138
	v_add_f32_e32 v138, v150, v138
	v_add_f32_e32 v138, v145, v138
	v_exp_f32_e32 v164, v139
	v_add_f32_e32 v138, v148, v138
	s_waitcnt lgkmcnt(1)
	v_mfma_f32_32x32x16_bf16 v[82:97], v[228:231], v[106:109], v[82:97]
	v_exp_f32_e32 v136, v136
	v_add_f32_e32 v138, v144, v138
	v_exp_f32_e32 v137, v137
	v_add_f32_e32 v138, v146, v138
	v_exp_f32_e32 v130, v130
	v_add_f32_e32 v138, v143, v138
	v_exp_f32_e32 v131, v131
	s_waitcnt lgkmcnt(0)
	v_mfma_f32_32x32x16_bf16 v[66:81], v[232:235], v[106:109], v[66:81]
	ds_read_b128 v[228:231], v217 offset:49152
	ds_read_b128 v[232:235], v217 offset:53248
	v_add_f32_e32 v138, v164, v138
	v_exp_f32_e32 v128, v128
	v_add_f32_e32 v138, v136, v138
	v_exp_f32_e32 v129, v129
	v_add_f32_e32 v138, v137, v138
	v_exp_f32_e32 v126, v126
	s_waitcnt lgkmcnt(1)
	v_mfma_f32_32x32x16_bf16 v[82:97], v[228:231], v[102:105], v[82:97]
	v_add_f32_e32 v138, v130, v138
	v_exp_f32_e32 v127, v127
	v_add_f32_e32 v138, v131, v138
	v_exp_f32_e32 v165, v140
	v_add_f32_e32 v138, v128, v138
	v_exp_f32_e32 v166, v141
	v_add_f32_e32 v138, v129, v138
	s_waitcnt lgkmcnt(0)
	v_mfma_f32_32x32x16_bf16 v[66:81], v[232:235], v[102:105], v[66:81]
	ds_read_b128 v[228:231], v218 offset:49152
	ds_read_b128 v[232:235], v218 offset:53248
	v_exp_f32_e32 v134, v134
	v_add_f32_e32 v138, v126, v138
	v_exp_f32_e32 v135, v135
	v_add_f32_e32 v138, v127, v138
	v_exp_f32_e32 v132, v132
	v_add_f32_e32 v138, v165, v138
	s_waitcnt lgkmcnt(1)
	v_mfma_f32_32x32x16_bf16 v[82:97], v[228:231], v[98:101], v[82:97]
	v_exp_f32_e32 v133, v133
	v_add_f32_e32 v138, v166, v138
	v_add_f32_e32 v138, v134, v138
	v_add_f32_e32 v138, v135, v138
	v_add_f32_e32 v138, v132, v138
	v_add_f32_e32 v220, v133, v138
	v_mov_b32_e32 v221, v220
	s_waitcnt lgkmcnt(0)
	v_mfma_f32_32x32x16_bf16 v[66:81], v[232:235], v[98:101], v[66:81]
	v_cvt_pk_bf16_f32 v138, v177, v226
	v_cvt_pk_bf16_f32 v139, v161, v223
	v_cvt_pk_bf16_f32 v140, v153, v176
	v_cvt_pk_bf16_f32 v141, v152, v160
	v_cvt_pk_bf16_f32 v222, v149, v151
	v_cvt_pk_bf16_f32 v223, v147, v150
	v_cvt_pk_bf16_f32 v224, v145, v148
	v_permlane32_swap_b32_e32 v220, v221
	v_permlane32_swap_b32_e32 v138, v140
	v_cvt_pk_bf16_f32 v225, v144, v146
	v_permlane32_swap_b32_e32 v222, v224
	v_cvt_pk_bf16_f32 v144, v143, v164
	v_cvt_pk_bf16_f32 v145, v136, v137
	v_cvt_pk_bf16_f32 v146, v130, v131
	v_cvt_pk_bf16_f32 v147, v128, v129
	v_cvt_pk_bf16_f32 v148, v126, v127
	v_cvt_pk_bf16_f32 v149, v165, v166
	v_cvt_pk_bf16_f32 v150, v134, v135
	v_cvt_pk_bf16_f32 v151, v132, v133
	v_permlane32_swap_b32_e32 v139, v141
	v_permlane32_swap_b32_e32 v223, v225
	v_permlane32_swap_b32_e32 v144, v146
	v_permlane32_swap_b32_e32 v145, v147
	v_permlane32_swap_b32_e32 v148, v150
	v_permlane32_swap_b32_e32 v149, v151
	global_load_dwordx4 v[182:185], v[178:179], off offset:2048
	global_load_dwordx4 v[194:197], v[180:181], off offset:2048
	global_load_dwordx4 v[134:137], v[204:205], off offset:1152
	s_mov_b32 s4, 0xa0000
	s_mov_b32 s5, 0
	s_nop 0
	v_lshl_add_u64 v[178:179], v[178:179], 0, s[4:5]
	v_lshl_add_u64 v[180:181], v[180:181], 0, s[4:5]
	v_lshl_add_u64 v[204:205], v[204:205], 0, s[4:5]
	ds_read_b64_tr_b16 v[226:227], v211 offset:0
	ds_read_b64_tr_b16 v[228:229], v211 offset:0x800
	ds_read_b64_tr_b16 v[230:231], v211 offset:0x1000
	ds_read_b64_tr_b16 v[232:233], v211 offset:0x1800
	ds_read_b64_tr_b16 v[234:235], v211 offset:0x2000
	ds_read_b64_tr_b16 v[236:237], v211 offset:0x2800
	ds_read_b64_tr_b16 v[238:239], v211 offset:0x3000
	ds_read_b64_tr_b16 v[240:241], v211 offset:0x3800
	s_waitcnt lgkmcnt(6)
	s_nop 0
	v_mfma_f32_32x32x16_bf16 v[2:17], v[138:141], v[226:229], v[2:17]
	ds_read_b64_tr_b16 v[226:227], v211 offset:0x200
	ds_read_b64_tr_b16 v[228:229], v211 offset:0xa00
	s_waitcnt lgkmcnt(6)
	v_mfma_f32_32x32x16_bf16 v[2:17], v[222:225], v[230:233], v[2:17]
	ds_read_b64_tr_b16 v[230:231], v211 offset:0x1200
	ds_read_b64_tr_b16 v[232:233], v211 offset:0x1a00
	s_waitcnt lgkmcnt(6)
	v_mfma_f32_32x32x16_bf16 v[2:17], v[144:147], v[234:237], v[2:17]
	ds_read_b64_tr_b16 v[234:235], v211 offset:0x2200
	ds_read_b64_tr_b16 v[236:237], v211 offset:0x2a00
	s_waitcnt lgkmcnt(6)
	v_mfma_f32_32x32x16_bf16 v[2:17], v[148:151], v[238:241], v[2:17]
	ds_read_b64_tr_b16 v[238:239], v211 offset:0x3200
	ds_read_b64_tr_b16 v[240:241], v211 offset:0x3a00
	s_waitcnt lgkmcnt(6)
	v_mfma_f32_32x32x16_bf16 v[50:65], v[138:141], v[226:229], v[50:65]
	ds_read_b64_tr_b16 v[226:227], v211 offset:0x400
	ds_read_b64_tr_b16 v[228:229], v211 offset:0xc00
	s_waitcnt lgkmcnt(6)
	v_mfma_f32_32x32x16_bf16 v[50:65], v[222:225], v[230:233], v[50:65]
	ds_read_b64_tr_b16 v[230:231], v211 offset:0x1400
	ds_read_b64_tr_b16 v[232:233], v211 offset:0x1c00
	s_waitcnt lgkmcnt(6)
	v_mfma_f32_32x32x16_bf16 v[50:65], v[144:147], v[234:237], v[50:65]
	ds_read_b64_tr_b16 v[234:235], v211 offset:0x2400
	ds_read_b64_tr_b16 v[236:237], v211 offset:0x2c00
	s_waitcnt lgkmcnt(6)
; #define SBAR() __builtin_amdgcn_sched_barrier(0)
; __device__ __forceinline__ void partialSM(f32x16& p0, f32x16& p1, float& m_reg, float& mn, float& alpha, float C, float thrRaw) {
;   float pmax = p0[0];
; #pragma unroll
;   for (int r = 1; r < 16; ++r) pmax = fmaxf(pmax, p0[r]);
; #pragma unroll
;   for (int r = 0; r < 16; ++r) pmax = fmaxf(pmax, p1[r]);
;   { auto rr = __builtin_amdgcn_permlane32_swap(__float_as_uint(pmax), __float_as_uint(pmax), false, false);
;     pmax = fmaxf(__uint_as_float(rr[0]), __uint_as_float(rr[1])); }
;   if (__builtin_expect(__all(pmax - m_reg <= thrRaw), 1)) { mn = m_reg; alpha = 1.f; }
;   else { mn = fmaxf(m_reg, pmax); alpha = __builtin_amdgcn_exp2f((m_reg - mn) * C); m_reg = mn; }
;   float mnC = -mn * C;
; #pragma unroll
;   for (int r = 0; r < 16; ++r) p0[r] = fmaf(p0[r], C, mnC);
; #pragma unroll
;   for (int r = 0; r < 16; ++r) p1[r] = fmaf(p1[r], C, mnC);
; #pragma unroll
;   for (int r = 0; r < 16; ++r) p0[r] = __builtin_amdgcn_exp2f(p0[r]);
; }
; template <int D0> __device__ __forceinline__ void pv_one(f32x16& od, int vb, bf16x8 pa0, bf16x8 pa1, bf16x8 pa2, bf16x8 pa3) {
;   const s16x4 l0 = tr_read<v_rd_off(D0, 0, 0)>(vb), h0 = tr_read<v_rd_off(D0, 0, 1)>(vb), l1 = tr_read<v_rd_off(D0, 1, 0)>(vb), h1 = tr_read<v_rd_off(D0, 1, 1)>(vb);
;   const s16x4 l2 = tr_read<v_rd_off(D0, 2, 0)>(vb), h2 = tr_read<v_rd_off(D0, 2, 1)>(vb), l3 = tr_read<v_rd_off(D0, 3, 0)>(vb), h3 = tr_read<v_rd_off(D0, 3, 1)>(vb);
;   asm volatile("s_waitcnt lgkmcnt(0)" ::: "memory"); SBAR();
;     ...
;   od = __builtin_amdgcn_mfma_f32_32x32x16_bf16(pa0, PK(l0, h0), od, 0, 0, 0);
;   od = __builtin_amdgcn_mfma_f32_32x32x16_bf16(pa1, PK(l1, h1), od, 0, 0, 0);
;   od = __builtin_amdgcn_mfma_f32_32x32x16_bf16(pa2, PK(l2, h2), od, 0, 0, 0);
;   od = __builtin_amdgcn_mfma_f32_32x32x16_bf16(pa3, PK(l3, h3), od, 0, 0, 0);
;     ...
; }
; __device__ __forceinline__ void pv_d0(f32x16* o, int vb, bf16x8 pa0, bf16x8 pa1, bf16x8 pa2, bf16x8 pa3) {
;   pv_one<0>(o[0], vb, pa0, pa1, pa2, pa3); pv_one<1>(o[1], vb, pa0, pa1, pa2, pa3); pv_one<2>(o[2], vb, pa0, pa1, pa2, pa3); pv_one<3>(o[3], vb, pa0, pa1, pa2, pa3);
	v_mfma_f32_32x32x16_bf16 v[50:65], v[148:151], v[238:241], v[50:65]
	ds_read_b64_tr_b16 v[238:239], v211 offset:0x3400
	ds_read_b64_tr_b16 v[240:241], v211 offset:0x3c00
	s_waitcnt lgkmcnt(6)
	v_mfma_f32_32x32x16_bf16 v[34:49], v[138:141], v[226:229], v[34:49]
	ds_read_b64_tr_b16 v[226:227], v211 offset:0x600
	ds_read_b64_tr_b16 v[228:229], v211 offset:0xe00
	s_waitcnt lgkmcnt(6)
	v_mfma_f32_32x32x16_bf16 v[34:49], v[222:225], v[230:233], v[34:49]
	ds_read_b64_tr_b16 v[230:231], v211 offset:0x1600
	ds_read_b64_tr_b16 v[232:233], v211 offset:0x1e00
	s_waitcnt lgkmcnt(6)
	v_mfma_f32_32x32x16_bf16 v[34:49], v[144:147], v[234:237], v[34:49]
	ds_read_b64_tr_b16 v[234:235], v211 offset:0x2600
	ds_read_b64_tr_b16 v[236:237], v211 offset:0x2e00
	s_waitcnt lgkmcnt(6)
	v_mfma_f32_32x32x16_bf16 v[34:49], v[148:151], v[238:241], v[34:49]
	ds_read_b64_tr_b16 v[238:239], v211 offset:0x3600
	ds_read_b64_tr_b16 v[240:241], v211 offset:0x3e00
	s_waitcnt lgkmcnt(6)
	v_mfma_f32_32x32x16_bf16 v[18:33], v[138:141], v[226:229], v[18:33]
	v_max_f32_e32 v138, v83, v82
	v_max3_f32 v138, v138, v84, v85
	v_max3_f32 v138, v138, v86, v87
	v_max3_f32 v138, v138, v88, v89
	v_max3_f32 v138, v138, v90, v91
	v_max3_f32 v138, v138, v92, v93
	v_max3_f32 v138, v138, v94, v95
	s_waitcnt lgkmcnt(4)
	v_mfma_f32_32x32x16_bf16 v[18:33], v[222:225], v[230:233], v[18:33]
	v_max3_f32 v138, v138, v96, v97
	v_max3_f32 v138, v138, v66, v67
	v_max3_f32 v138, v138, v68, v69
	v_max3_f32 v138, v138, v70, v71
	v_max3_f32 v138, v138, v72, v73
	v_max3_f32 v138, v138, v74, v75
	v_max3_f32 v138, v138, v76, v77
	v_max3_f32 v138, v138, v78, v79
	s_waitcnt lgkmcnt(2)
	v_mfma_f32_32x32x16_bf16 v[18:33], v[144:147], v[234:237], v[18:33]
	v_max3_f32 v138, v138, v80, v81
	v_mov_b32_e32 v139, v138
	s_nop 1
	v_permlane32_swap_b32_e32 v138, v139
	v_max_f32_e32 v138, v139, v138
	v_sub_f32_e32 v139, v138, v142
	s_mov_b32 s2, 0x42800000
	v_cmp_ge_f32_e32 vcc, s2, v139
	v_max_f32_e32 v138, v142, v138
	s_waitcnt lgkmcnt(0)
	v_mfma_f32_32x32x16_bf16 v[18:33], v[148:151], v[238:241], v[18:33]
	v_sub_f32_e32 v139, v142, v138
	v_mul_f32_e32 v139, 0x3e38aa3b, v139
	v_exp_f32_e32 v139, v139
	s_cmp_eq_u64 vcc, exec
	s_cselect_b64 s[2:3], -1, 0
	s_waitcnt vmcnt(3)
	v_cndmask_b32_e64 v222, v139, 1.0, s[2:3]
	v_cmp_gt_f32_e32 vcc, 1.0, v222
	s_waitcnt vmcnt(3)
	ds_write_b128 v214, v[122:125] offset:32768
	s_cbranch_vccz .LBB0_705
	s_and_saveexec_b64 s[4:5], s[0:1]
	ds_write_b32 v208, v222 offset:128
	s_or_b64 exec, exec, s[4:5]
	s_waitcnt lgkmcnt(0)
	v_add_u32_e32 v139, v207, v0
	ds_read_b128 v[144:147], v139 offset:224
	ds_read_b128 v[148:151], v139 offset:192
	ds_read_b128 v[224:227], v139 offset:160
	ds_read_b128 v[228:231], v139 offset:128
	s_waitcnt lgkmcnt(3)
	v_pk_mul_f32 v[14:15], v[14:15], v[144:145]
	s_waitcnt lgkmcnt(2)
	v_pk_mul_f32 v[10:11], v[10:11], v[148:149]
	s_waitcnt lgkmcnt(1)
	v_pk_mul_f32 v[6:7], v[6:7], v[224:225]
	v_pk_mul_f32 v[16:17], v[16:17], v[146:147]
	v_pk_mul_f32 v[12:13], v[12:13], v[150:151]
	v_pk_mul_f32 v[8:9], v[8:9], v[226:227]
	s_waitcnt lgkmcnt(0)
	v_pk_mul_f32 v[4:5], v[4:5], v[230:231]
	v_pk_mul_f32 v[2:3], v[2:3], v[228:229]
	v_pk_mul_f32 v[62:63], v[144:145], v[62:63]
	v_pk_mul_f32 v[58:59], v[148:149], v[58:59]
	v_pk_mul_f32 v[54:55], v[224:225], v[54:55]
	v_pk_mul_f32 v[64:65], v[146:147], v[64:65]
	v_pk_mul_f32 v[60:61], v[150:151], v[60:61]
	v_pk_mul_f32 v[56:57], v[226:227], v[56:57]
	v_pk_mul_f32 v[52:53], v[230:231], v[52:53]
	v_pk_mul_f32 v[50:51], v[228:229], v[50:51]
	v_pk_mul_f32 v[46:47], v[144:145], v[46:47]
	v_pk_mul_f32 v[42:43], v[148:149], v[42:43]
	v_pk_mul_f32 v[38:39], v[224:225], v[38:39]
	v_pk_mul_f32 v[48:49], v[146:147], v[48:49]
	v_pk_mul_f32 v[44:45], v[150:151], v[44:45]
	v_pk_mul_f32 v[40:41], v[226:227], v[40:41]
	v_pk_mul_f32 v[36:37], v[230:231], v[36:37]
	v_pk_mul_f32 v[34:35], v[228:229], v[34:35]
	v_pk_mul_f32 v[30:31], v[144:145], v[30:31]
	v_pk_mul_f32 v[26:27], v[148:149], v[26:27]
	v_pk_mul_f32 v[22:23], v[224:225], v[22:23]
	v_pk_mul_f32 v[32:33], v[146:147], v[32:33]
	v_pk_mul_f32 v[28:29], v[150:151], v[28:29]
	v_pk_mul_f32 v[24:25], v[226:227], v[24:25]
	v_pk_mul_f32 v[20:21], v[230:231], v[20:21]
	v_pk_mul_f32 v[18:19], v[228:229], v[18:19]
.LBB0_705:
	v_cndmask_b32_e64 v223, v138, v142, s[2:3]
	v_mul_f32_e32 v224, 0xbe38aa3b, v223
	v_fmamk_f32 v82, v82, 0x3e38aa3b, v224
	v_fmamk_f32 v83, v83, 0x3e38aa3b, v224
	v_fmamk_f32 v84, v84, 0x3e38aa3b, v224
	v_fmamk_f32 v85, v85, 0x3e38aa3b, v224
	v_fmamk_f32 v86, v86, 0x3e38aa3b, v224
	v_fmamk_f32 v87, v87, 0x3e38aa3b, v224
	v_fmamk_f32 v88, v88, 0x3e38aa3b, v224
	v_fmamk_f32 v89, v89, 0x3e38aa3b, v224
	v_fmamk_f32 v90, v90, 0x3e38aa3b, v224
	v_fmamk_f32 v91, v91, 0x3e38aa3b, v224
	v_fmamk_f32 v92, v92, 0x3e38aa3b, v224
	v_fmamk_f32 v93, v93, 0x3e38aa3b, v224
	v_fmamk_f32 v94, v94, 0x3e38aa3b, v224
	v_fmamk_f32 v95, v95, 0x3e38aa3b, v224
	v_fmamk_f32 v96, v96, 0x3e38aa3b, v224
	v_fmamk_f32 v97, v97, 0x3e38aa3b, v224
	v_exp_f32_e32 v138, v82
	v_exp_f32_e32 v153, v83
	v_exp_f32_e32 v139, v84
	v_exp_f32_e32 v152, v85
	v_exp_f32_e32 v140, v86
	v_exp_f32_e32 v151, v87
	v_exp_f32_e32 v141, v88
	v_exp_f32_e32 v150, v89
	v_exp_f32_e32 v142, v90
	v_exp_f32_e32 v149, v91
	v_exp_f32_e32 v143, v92
	v_exp_f32_e32 v148, v93
	v_exp_f32_e32 v144, v94
	v_exp_f32_e32 v147, v95
	v_exp_f32_e32 v145, v96
	v_exp_f32_e32 v146, v97
	v_fmamk_f32 v233, v66, 0x3e38aa3b, v224
	v_fmamk_f32 v234, v67, 0x3e38aa3b, v224
	v_fmamk_f32 v235, v68, 0x3e38aa3b, v224
	v_fmamk_f32 v236, v69, 0x3e38aa3b, v224
	v_fmamk_f32 v237, v70, 0x3e38aa3b, v224
	v_fmamk_f32 v226, v71, 0x3e38aa3b, v224
	v_fmamk_f32 v227, v72, 0x3e38aa3b, v224
	v_fmamk_f32 v228, v73, 0x3e38aa3b, v224
	v_fmamk_f32 v229, v74, 0x3e38aa3b, v224
	v_fmamk_f32 v230, v75, 0x3e38aa3b, v224
	v_fmamk_f32 v231, v76, 0x3e38aa3b, v224
	v_fmamk_f32 v232, v77, 0x3e38aa3b, v224
	v_fmamk_f32 v225, v78, 0x3e38aa3b, v224
	v_fmamk_f32 v238, v79, 0x3e38aa3b, v224
	v_fmamk_f32 v239, v80, 0x3e38aa3b, v224
	v_fmac_f32_e32 v224, 0x3e38aa3b, v81
	s_waitcnt lgkmcnt(0)
	s_barrier
; #define SBAR() __builtin_amdgcn_sched_barrier(0)
; #define SLOAD(i, k0) do { sr_[i].vs0 = *reinterpret_cast<const bf16x8*>(&Vh[(long)((k0) + sr) * LDP + sc]); sr_[i].vs1 = *reinterpret_cast<const bf16x8*>(&Vh[(long)((k0) + 32 + sr) * LDP + sc]); \
;     sr_[i].ks0 = *reinterpret_cast<const bf16x8*>(&Kh[(long)((k0) + ksr) * LDP + ksc]); if (DK == 128) sr_[i].ks1 = *reinterpret_cast<const bf16x8*>(&Kh[(long)((k0) + 32 + ksr) * LDP + ksc]); } while (0)
; #define HOOK(P0, P1, j) do { if (NA) na_hook(P0, P1, krow0 + (j), q_row, q_col, win_r, win_c, rpb, inv_scale, hi); } while (0)
; __device__ __forceinline__ void finishSM(f32x16& p0, f32x16& p1, float alpha, float& l_reg, bf16x8& pa0, bf16x8& pa1, bf16x8& pa2, bf16x8& pa3) {
; #pragma unroll
;   for (int r = 0; r < 16; ++r) p1[r] = __builtin_amdgcn_exp2f(p1[r]);
;   float ps = 0;
; #pragma unroll
;   for (int r = 0; r < 16; ++r) ps += p0[r];
; #pragma unroll
;   for (int r = 0; r < 16; ++r) ps += p1[r];
;   { auto rr = __builtin_amdgcn_permlane32_swap(__float_as_uint(ps), __float_as_uint(ps), false, false);
;     ps = __uint_as_float(rr[0]) + __uint_as_float(rr[1]); }
;   l_reg = l_reg * alpha + ps;
;     ...
;   PK4(p0, 0, pa0); PK4(p0, 8, pa1); PK4(p1, 0, pa2); PK4(p1, 8, pa3);
;     ...
; }
; template <int DK, bool QL>
; __device__ __forceinline__ void qkt(f32x16& p0, f32x16& p1, const bf16* Ks, const bf16x8* qr, const char* ql, int r32, int hi) {
;   p0 = f32x16{}; p1 = f32x16{};
; #pragma unroll
;   for (int d0 = 0; d0 < DK / 16; ++d0) { int cb = (d0 * 16 + hi * 8) * 2;
;     const bf16x8 qv = QL ? *reinterpret_cast<const bf16x8*>(ql + d0 * 1024) : qr[d0];
;     bf16x8 b0 = *reinterpret_cast<const bf16x8*>((const char*)Ks + kswz<DK>(r32, cb));
;     bf16x8 b1 = *reinterpret_cast<const bf16x8*>((const char*)Ks + kswz<DK>(32 + r32, cb));
;     p0 = __builtin_amdgcn_mfma_f32_32x32x16_bf16(b0, qv, p0, 0, 0, 0);
;     p1 = __builtin_amdgcn_mfma_f32_32x32x16_bf16(b1, qv, p1, 0, 0, 0); }
; }
; template <int DK, bool NA, bool QL, int SD> ...
;     ...
;     SBAR(); qkt<DK, QL>(pA0, pA1, K_lds, qr, ql, r32, hi); HOOK(pA0, pA1, j + 1);
;     finishSM(pB0, pB1, alB, l_reg, pa0, pa1, pa2, pa3); SBAR();
;     if (SD == 1 || j + 3 < NT) SLOAD(SE, (j + 1 + SD) * KVBLK); SBAR();
;     pv_d0(o, vb0 + (int)SHM_V, pa0, pa1, pa2, pa3); partialSM(pA0, pA1, m_reg, mnA, alA, C, thrRaw);
	ds_write_b128 v212, v[114:117]
	ds_write_b128 v213, v[118:121]
	ds_read_b128 v[66:69], v215 offset:32768
	ds_read_b128 v[70:73], v215 offset:36864
	v_exp_f32_e32 v164, v233
	v_exp_f32_e32 v233, v224
	v_add_f32_e32 v224, 0, v138
	v_add_f32_e32 v224, v153, v224
	s_waitcnt lgkmcnt(1)
	v_mfma_f32_32x32x16_bf16 v[82:97], v[66:69], v[110:113], 0
	v_add_f32_e32 v224, v139, v224
	v_add_f32_e32 v224, v152, v224
	v_add_f32_e32 v224, v140, v224
	ds_read_b128 v[240:243], v216 offset:32768
	ds_read_b128 v[244:247], v216 offset:36864
	v_add_f32_e32 v224, v151, v224
	v_add_f32_e32 v224, v141, v224
	v_add_f32_e32 v224, v150, v224
	s_waitcnt lgkmcnt(2)
	v_mfma_f32_32x32x16_bf16 v[66:81], v[70:73], v[110:113], 0
	v_add_f32_e32 v224, v142, v224
	v_add_f32_e32 v224, v149, v224
	v_add_f32_e32 v224, v143, v224
	v_add_f32_e32 v224, v148, v224
	v_add_f32_e32 v224, v144, v224
	v_exp_f32_e32 v165, v234
	v_add_f32_e32 v224, v147, v224
	s_waitcnt lgkmcnt(1)
	v_mfma_f32_32x32x16_bf16 v[82:97], v[240:243], v[106:109], v[82:97]
	v_exp_f32_e32 v166, v235
	v_add_f32_e32 v224, v145, v224
	v_exp_f32_e32 v167, v236
	v_add_f32_e32 v224, v146, v224
	v_exp_f32_e32 v172, v237
	v_add_f32_e32 v224, v164, v224
	v_exp_f32_e32 v173, v226
	s_waitcnt lgkmcnt(0)
	v_mfma_f32_32x32x16_bf16 v[66:81], v[244:247], v[106:109], v[66:81]
	ds_read_b128 v[240:243], v217 offset:32768
	ds_read_b128 v[244:247], v217 offset:36864
	v_add_f32_e32 v224, v165, v224
	v_exp_f32_e32 v174, v227
	v_add_f32_e32 v224, v166, v224
	v_exp_f32_e32 v175, v228
	v_add_f32_e32 v224, v167, v224
	v_exp_f32_e32 v226, v229
	s_waitcnt lgkmcnt(1)
	v_mfma_f32_32x32x16_bf16 v[82:97], v[240:243], v[102:105], v[82:97]
	v_add_f32_e32 v224, v172, v224
	v_exp_f32_e32 v227, v230
	v_add_f32_e32 v224, v173, v224
	v_exp_f32_e32 v228, v231
	v_add_f32_e32 v224, v174, v224
	v_exp_f32_e32 v229, v232
	v_add_f32_e32 v224, v175, v224
	s_waitcnt lgkmcnt(0)
	v_mfma_f32_32x32x16_bf16 v[66:81], v[244:247], v[102:105], v[66:81]
	ds_read_b128 v[240:243], v218 offset:32768
	ds_read_b128 v[244:247], v218 offset:36864
	v_exp_f32_e32 v230, v225
	v_add_f32_e32 v224, v226, v224
	v_exp_f32_e32 v231, v238
	v_add_f32_e32 v224, v227, v224
	v_exp_f32_e32 v232, v239
	v_add_f32_e32 v224, v228, v224
	s_waitcnt lgkmcnt(1)
	v_mfma_f32_32x32x16_bf16 v[82:97], v[240:243], v[98:101], v[82:97]
	v_add_f32_e32 v224, v229, v224
	v_add_f32_e32 v224, v230, v224
	v_add_f32_e32 v224, v231, v224
	v_add_f32_e32 v224, v232, v224
	v_add_f32_e32 v224, v233, v224
	v_mov_b32_e32 v225, v224
	v_cvt_pk_bf16_f32 v138, v138, v153
	s_waitcnt lgkmcnt(0)
	v_mfma_f32_32x32x16_bf16 v[66:81], v[244:247], v[98:101], v[66:81]
	v_cvt_pk_bf16_f32 v139, v139, v152
	v_cvt_pk_bf16_f32 v140, v140, v151
	v_cvt_pk_bf16_f32 v141, v141, v150
	v_cvt_pk_bf16_f32 v142, v142, v149
	v_cvt_pk_bf16_f32 v143, v143, v148
	v_cvt_pk_bf16_f32 v144, v144, v147
	v_cvt_pk_bf16_f32 v145, v145, v146
	v_cvt_pk_bf16_f32 v146, v164, v165
	v_cvt_pk_bf16_f32 v147, v166, v167
	v_cvt_pk_bf16_f32 v148, v172, v173
	v_cvt_pk_bf16_f32 v149, v174, v175
	v_cvt_pk_bf16_f32 v150, v226, v227
	v_cvt_pk_bf16_f32 v151, v228, v229
	v_cvt_pk_bf16_f32 v152, v230, v231
	v_cvt_pk_bf16_f32 v153, v232, v233
	v_permlane32_swap_b32_e32 v224, v225
	v_permlane32_swap_b32_e32 v138, v140
	v_permlane32_swap_b32_e32 v139, v141
	v_permlane32_swap_b32_e32 v142, v144
	v_permlane32_swap_b32_e32 v143, v145
	v_permlane32_swap_b32_e32 v146, v148
	v_permlane32_swap_b32_e32 v147, v149
	v_permlane32_swap_b32_e32 v150, v152
	v_permlane32_swap_b32_e32 v151, v153
	s_cmp_gt_u32 s8, 60
	s_cselect_b64 s[4:5], -1, 0
	s_and_b64 vcc, exec, s[4:5]
	s_cbranch_vccnz .Lod_d2
	global_load_dwordx4 v[114:117], v[178:179], off offset:2048
	global_load_dwordx4 v[118:121], v[180:181], off offset:2048
	global_load_dwordx4 v[122:125], v[204:205], off offset:1152
	s_mov_b32 s6, 0xa0000
	s_mov_b32 s7, 0
	s_nop 0
	v_lshl_add_u64 v[178:179], v[178:179], 0, s[6:7]
	v_lshl_add_u64 v[180:181], v[180:181], 0, s[6:7]
	v_lshl_add_u64 v[204:205], v[204:205], 0, s[6:7]
.LBB0_707:
	ds_read_b64_tr_b16 v[226:227], v210 offset:0
	ds_read_b64_tr_b16 v[228:229], v210 offset:0x800
	ds_read_b64_tr_b16 v[230:231], v210 offset:0x1000
	ds_read_b64_tr_b16 v[232:233], v210 offset:0x1800
	ds_read_b64_tr_b16 v[234:235], v210 offset:0x2000
	ds_read_b64_tr_b16 v[236:237], v210 offset:0x2800
	ds_read_b64_tr_b16 v[238:239], v210 offset:0x3000
	ds_read_b64_tr_b16 v[240:241], v210 offset:0x3800
	s_waitcnt lgkmcnt(6)
	s_nop 0
	v_mfma_f32_32x32x16_bf16 v[2:17], v[138:141], v[226:229], v[2:17]
	ds_read_b64_tr_b16 v[226:227], v210 offset:0x200
	ds_read_b64_tr_b16 v[228:229], v210 offset:0xa00
	s_waitcnt lgkmcnt(6)
	v_mfma_f32_32x32x16_bf16 v[2:17], v[142:145], v[230:233], v[2:17]
	ds_read_b64_tr_b16 v[230:231], v210 offset:0x1200
	ds_read_b64_tr_b16 v[232:233], v210 offset:0x1a00
	s_waitcnt lgkmcnt(6)
	v_mfma_f32_32x32x16_bf16 v[2:17], v[146:149], v[234:237], v[2:17]
	ds_read_b64_tr_b16 v[234:235], v210 offset:0x2200
	ds_read_b64_tr_b16 v[236:237], v210 offset:0x2a00
	s_waitcnt lgkmcnt(6)
	v_mfma_f32_32x32x16_bf16 v[2:17], v[150:153], v[238:241], v[2:17]
	ds_read_b64_tr_b16 v[238:239], v210 offset:0x3200
	ds_read_b64_tr_b16 v[240:241], v210 offset:0x3a00
	s_waitcnt lgkmcnt(6)
	v_mfma_f32_32x32x16_bf16 v[50:65], v[138:141], v[226:229], v[50:65]
	ds_read_b64_tr_b16 v[226:227], v210 offset:0x400
	ds_read_b64_tr_b16 v[228:229], v210 offset:0xc00
	s_waitcnt lgkmcnt(6)
	v_mfma_f32_32x32x16_bf16 v[50:65], v[142:145], v[230:233], v[50:65]
	ds_read_b64_tr_b16 v[230:231], v210 offset:0x1400
	ds_read_b64_tr_b16 v[232:233], v210 offset:0x1c00
	s_waitcnt lgkmcnt(6)
; #define SBAR() __builtin_amdgcn_sched_barrier(0)
; #define SLOAD(i, k0) do { sr_[i].vs0 = *reinterpret_cast<const bf16x8*>(&Vh[(long)((k0) + sr) * LDP + sc]); sr_[i].vs1 = *reinterpret_cast<const bf16x8*>(&Vh[(long)((k0) + 32 + sr) * LDP + sc]); \
;     sr_[i].ks0 = *reinterpret_cast<const bf16x8*>(&Kh[(long)((k0) + ksr) * LDP + ksc]); if (DK == 128) sr_[i].ks1 = *reinterpret_cast<const bf16x8*>(&Kh[(long)((k0) + 32 + ksr) * LDP + ksc]); } while (0)
; #define SWAIT() do { if (SD == 1) asm volatile("s_waitcnt vmcnt(0)" ::: "memory"); else if (DK == 128) asm volatile("s_waitcnt vmcnt(4)" ::: "memory"); else asm volatile("s_waitcnt vmcnt(3)" ::: "memory"); } while (0)
; #define HOOK(P0, P1, j) do { if (NA) na_hook(P0, P1, krow0 + (j), q_row, q_col, win_r, win_c, rpb, inv_scale, hi); } while (0)
; __device__ __forceinline__ void partialSM(f32x16& p0, f32x16& p1, float& m_reg, float& mn, float& alpha, float C, float thrRaw) {
;   float pmax = p0[0];
; #pragma unroll
;   for (int r = 1; r < 16; ++r) pmax = fmaxf(pmax, p0[r]);
; #pragma unroll
;   for (int r = 0; r < 16; ++r) pmax = fmaxf(pmax, p1[r]);
;   { auto rr = __builtin_amdgcn_permlane32_swap(__float_as_uint(pmax), __float_as_uint(pmax), false, false);
;     pmax = fmaxf(__uint_as_float(rr[0]), __uint_as_float(rr[1])); }
;   if (__builtin_expect(__all(pmax - m_reg <= thrRaw), 1)) { mn = m_reg; alpha = 1.f; }
;   else { mn = fmaxf(m_reg, pmax); alpha = __builtin_amdgcn_exp2f((m_reg - mn) * C); m_reg = mn; }
;   float mnC = -mn * C;
; #pragma unroll
;   for (int r = 0; r < 16; ++r) p0[r] = fmaf(p0[r], C, mnC);
; #pragma unroll
;   for (int r = 0; r < 16; ++r) p1[r] = fmaf(p1[r], C, mnC);
; #pragma unroll
;   for (int r = 0; r < 16; ++r) p0[r] = __builtin_amdgcn_exp2f(p0[r]);
; }
; template <int DK, bool NA, bool QL, int SD> ...
;     ...
;     __syncthreads(); SWAIT(); SWRITE(0, SE);
;     RESC(alB); __syncthreads();
;     SBAR(); qkt<DK, QL>(pA0, pA1, K_lds, qr, ql, r32, hi); HOOK(pA0, pA1, j + 1);
;     finishSM(pB0, pB1, alB, l_reg, pa0, pa1, pa2, pa3); SBAR();
;     if (SD == 1 || j + 3 < NT) SLOAD(SE, (j + 1 + SD) * KVBLK); SBAR();
;     pv_d0(o, vb0 + (int)SHM_V, pa0, pa1, pa2, pa3); partialSM(pA0, pA1, m_reg, mnA, alA, C, thrRaw);
;     __syncthreads(); SWAIT(); SWRITE(1, SO);
;     RESC(alA); __syncthreads();
;   }
	v_mfma_f32_32x32x16_bf16 v[50:65], v[146:149], v[234:237], v[50:65]
	ds_read_b64_tr_b16 v[234:235], v210 offset:0x2400
	ds_read_b64_tr_b16 v[236:237], v210 offset:0x2c00
	s_waitcnt lgkmcnt(6)
	v_mfma_f32_32x32x16_bf16 v[50:65], v[150:153], v[238:241], v[50:65]
	ds_read_b64_tr_b16 v[238:239], v210 offset:0x3400
	ds_read_b64_tr_b16 v[240:241], v210 offset:0x3c00
	s_waitcnt lgkmcnt(6)
	v_mfma_f32_32x32x16_bf16 v[34:49], v[138:141], v[226:229], v[34:49]
	ds_read_b64_tr_b16 v[226:227], v210 offset:0x600
	ds_read_b64_tr_b16 v[228:229], v210 offset:0xe00
	s_waitcnt lgkmcnt(6)
	v_mfma_f32_32x32x16_bf16 v[34:49], v[142:145], v[230:233], v[34:49]
	ds_read_b64_tr_b16 v[230:231], v210 offset:0x1600
	ds_read_b64_tr_b16 v[232:233], v210 offset:0x1e00
	s_waitcnt lgkmcnt(6)
	v_mfma_f32_32x32x16_bf16 v[34:49], v[146:149], v[234:237], v[34:49]
	ds_read_b64_tr_b16 v[234:235], v210 offset:0x2600
	ds_read_b64_tr_b16 v[236:237], v210 offset:0x2e00
	s_waitcnt lgkmcnt(6)
	v_mfma_f32_32x32x16_bf16 v[34:49], v[150:153], v[238:241], v[34:49]
	ds_read_b64_tr_b16 v[238:239], v210 offset:0x3600
	ds_read_b64_tr_b16 v[240:241], v210 offset:0x3e00
	s_waitcnt lgkmcnt(6)
	v_mfma_f32_32x32x16_bf16 v[18:33], v[138:141], v[226:229], v[18:33]
	v_max_f32_e32 v138, v83, v82
	v_max3_f32 v138, v138, v84, v85
	v_max3_f32 v138, v138, v86, v87
	v_max3_f32 v138, v138, v88, v89
	v_max3_f32 v138, v138, v90, v91
	v_max3_f32 v138, v138, v92, v93
	v_max3_f32 v138, v138, v94, v95
	s_waitcnt lgkmcnt(4)
	v_mfma_f32_32x32x16_bf16 v[18:33], v[142:145], v[230:233], v[18:33]
	v_max3_f32 v138, v138, v96, v97
	v_max3_f32 v138, v138, v66, v67
	v_max3_f32 v138, v138, v68, v69
	v_max3_f32 v138, v138, v70, v71
	v_max3_f32 v138, v138, v72, v73
	v_max3_f32 v138, v138, v74, v75
	v_max3_f32 v138, v138, v76, v77
	v_max3_f32 v138, v138, v78, v79
	s_waitcnt lgkmcnt(2)
	v_mfma_f32_32x32x16_bf16 v[18:33], v[146:149], v[234:237], v[18:33]
	v_max3_f32 v138, v138, v80, v81
	v_mov_b32_e32 v139, v138
	s_nop 1
	v_permlane32_swap_b32_e32 v138, v139
	v_max_f32_e32 v138, v139, v138
	v_sub_f32_e32 v139, v138, v223
	s_mov_b32 s2, 0x42800000
	v_cmp_ge_f32_e32 vcc, s2, v139
	v_max_f32_e32 v138, v223, v138
	s_waitcnt lgkmcnt(0)
	v_mfma_f32_32x32x16_bf16 v[18:33], v[150:153], v[238:241], v[18:33]
	v_sub_f32_e32 v139, v223, v138
	v_mul_f32_e32 v139, 0x3e38aa3b, v139
	v_exp_f32_e32 v139, v139
	s_cmp_eq_u64 vcc, exec
	s_cselect_b64 s[2:3], -1, 0
	s_waitcnt vmcnt(3)
	v_cndmask_b32_e64 v143, v139, 1.0, s[2:3]
	v_cmp_gt_f32_e32 vcc, 1.0, v143
	ds_write_b128 v214, v[134:137] offset:49152
	s_cbranch_vccz .LBB0_711
	s_and_saveexec_b64 s[6:7], s[0:1]
	ds_write_b32 v208, v143 offset:128
	s_or_b64 exec, exec, s[6:7]
	s_waitcnt lgkmcnt(0)
	v_add_u32_e32 v139, v207, v0
	ds_read_b128 v[126:129], v139 offset:224
	ds_read_b128 v[130:133], v139 offset:192
	ds_read_b128 v[134:137], v139 offset:160
	ds_read_b128 v[144:147], v139 offset:128
	s_waitcnt lgkmcnt(3)
	v_pk_mul_f32 v[14:15], v[14:15], v[126:127]
	s_waitcnt lgkmcnt(2)
	v_pk_mul_f32 v[10:11], v[10:11], v[130:131]
	s_waitcnt lgkmcnt(1)
	v_pk_mul_f32 v[6:7], v[6:7], v[134:135]
	v_pk_mul_f32 v[16:17], v[16:17], v[128:129]
	v_pk_mul_f32 v[12:13], v[12:13], v[132:133]
	v_pk_mul_f32 v[8:9], v[8:9], v[136:137]
	s_waitcnt lgkmcnt(0)
	v_pk_mul_f32 v[4:5], v[4:5], v[146:147]
	v_pk_mul_f32 v[2:3], v[2:3], v[144:145]
	v_pk_mul_f32 v[62:63], v[126:127], v[62:63]
	v_pk_mul_f32 v[58:59], v[130:131], v[58:59]
	v_pk_mul_f32 v[54:55], v[134:135], v[54:55]
	v_pk_mul_f32 v[64:65], v[128:129], v[64:65]
	v_pk_mul_f32 v[60:61], v[132:133], v[60:61]
	v_pk_mul_f32 v[56:57], v[136:137], v[56:57]
	v_pk_mul_f32 v[52:53], v[146:147], v[52:53]
	v_pk_mul_f32 v[50:51], v[144:145], v[50:51]
	v_pk_mul_f32 v[46:47], v[126:127], v[46:47]
	v_pk_mul_f32 v[42:43], v[130:131], v[42:43]
	v_pk_mul_f32 v[38:39], v[134:135], v[38:39]
	v_pk_mul_f32 v[48:49], v[128:129], v[48:49]
	v_pk_mul_f32 v[44:45], v[132:133], v[44:45]
	v_pk_mul_f32 v[40:41], v[136:137], v[40:41]
	v_pk_mul_f32 v[36:37], v[146:147], v[36:37]
	v_pk_mul_f32 v[34:35], v[144:145], v[34:35]
	v_pk_mul_f32 v[30:31], v[126:127], v[30:31]
	v_pk_mul_f32 v[26:27], v[130:131], v[26:27]
	v_pk_mul_f32 v[22:23], v[134:135], v[22:23]
	v_pk_mul_f32 v[32:33], v[128:129], v[32:33]
	v_pk_mul_f32 v[28:29], v[132:133], v[28:29]
	v_pk_mul_f32 v[24:25], v[136:137], v[24:25]
	v_pk_mul_f32 v[20:21], v[146:147], v[20:21]
	v_pk_mul_f32 v[18:19], v[144:145], v[18:19]
.LBB0_711:
	v_cndmask_b32_e64 v142, v138, v223, s[2:3]
	v_mul_f32_e32 v132, 0xbe38aa3b, v142
	v_mov_b32_e32 v133, v132
	v_fmamk_f32 v82, v82, 0x3e38aa3b, v132
	v_fmamk_f32 v83, v83, 0x3e38aa3b, v132
	v_fmamk_f32 v84, v84, 0x3e38aa3b, v132
	v_fmamk_f32 v85, v85, 0x3e38aa3b, v132
	v_fmamk_f32 v86, v86, 0x3e38aa3b, v132
	v_fmamk_f32 v87, v87, 0x3e38aa3b, v132
	v_fmamk_f32 v88, v88, 0x3e38aa3b, v132
	v_fmamk_f32 v89, v89, 0x3e38aa3b, v132
	v_fmamk_f32 v90, v90, 0x3e38aa3b, v132
	v_fmamk_f32 v91, v91, 0x3e38aa3b, v132
	v_fmamk_f32 v92, v92, 0x3e38aa3b, v132
	v_fmamk_f32 v93, v93, 0x3e38aa3b, v132
	v_fmamk_f32 v94, v94, 0x3e38aa3b, v132
	v_fmamk_f32 v95, v95, 0x3e38aa3b, v132
	v_fmamk_f32 v96, v96, 0x3e38aa3b, v132
	v_fmac_f32_e32 v133, 0x3e38aa3b, v97
	s_mov_b32 s2, 0x3e38aa3b
	v_exp_f32_e32 v177, v82
	v_exp_f32_e32 v226, v83
	v_exp_f32_e32 v161, v84
	v_exp_f32_e32 v223, v85
	v_exp_f32_e32 v153, v86
	v_exp_f32_e32 v176, v87
	v_exp_f32_e32 v152, v88
	v_exp_f32_e32 v160, v89
	v_exp_f32_e32 v149, v90
	v_exp_f32_e32 v151, v91
	v_exp_f32_e32 v147, v92
	v_exp_f32_e32 v150, v93
	v_exp_f32_e32 v145, v94
	v_exp_f32_e32 v148, v95
	v_exp_f32_e32 v144, v96
	v_exp_f32_e32 v146, v133
	v_pk_fma_f32 v[138:139], v[66:67], s[2:3], v[132:133] op_sel_hi:[1,0,0]
	v_add_f32_e32 v66, v220, v221
	v_pk_fma_f32 v[136:137], v[68:69], s[2:3], v[132:133] op_sel_hi:[1,0,0]
	v_pk_fma_f32 v[130:131], v[70:71], s[2:3], v[132:133] op_sel_hi:[1,0,0]
	v_pk_fma_f32 v[128:129], v[72:73], s[2:3], v[132:133] op_sel_hi:[1,0,0]
	v_pk_fma_f32 v[126:127], v[74:75], s[2:3], v[132:133] op_sel_hi:[1,0,0]
	v_pk_fma_f32 v[140:141], v[76:77], s[2:3], v[132:133] op_sel_hi:[1,0,0]
	v_pk_fma_f32 v[134:135], v[78:79], s[2:3], v[132:133] op_sel_hi:[1,0,0]
	v_pk_fma_f32 v[132:133], v[80:81], s[2:3], v[132:133] op_sel_hi:[1,0,0]
	v_fmac_f32_e32 v66, v219, v209
	v_add_f32_e32 v209, v224, v225
	v_fmac_f32_e32 v209, v66, v222
	s_add_i32 s8, s8, 2
	s_and_b64 vcc, exec, s[4:5]
	s_waitcnt lgkmcnt(0)
	s_barrier
	s_cbranch_vccnz .LBB0_713
	v_mov_b32_e32 v219, v143
	ds_write_b128 v212, v[182:185] offset:16384
	ds_write_b128 v213, v[194:197] offset:16384
	s_branch .LBB0_701
